# plus: MoE LayerNorm-2 rows load gain and bias once and drop 24 of 32 full vmcnt drains per wave
# speedup vs baseline: 1.0108x; 1.0045x over previous
; __device__ __forceinline__ float h2f_(unsigned short b) { return (float)__builtin_bit_cast(_Float16, b); }
; template <bool MOE>
; __device__ __forceinline__ void ln2_phase(const Frame& F, int layer) {
;     ...
;     const int nrow = (T - F.gw + F.NGW - 1) / F.NGW;
;     u32x2 nxr[2][4], na[2][4], nc[2][4], np_[2][4];
;     ...
;     if (nrow == 8) {
;         int s0a[8], s1a[8]; float w0a[8], w1a[8];
; #pragma unroll
;         for (int i = 0; i < 8; ++i) { const int tt = F.gw + i * F.NGW; s0a[i] = tsl[tt * 2]; s1a[i] = tsl[tt * 2 + 1]; w0a[i] = tw[tt * 2]; w1a[i] = tw[tt * 2 + 1]; }
;         LN2_LOAD(0, F.gw, s0a[0], s1a[0]); LN2_LOAD(1, F.gw + F.NGW, s0a[1], s1a[1]);
; #pragma unroll
;         for (int i = 0; i < 8; i += 2) { f32x4 v[2][4];
; #pragma unroll
;             for (int s_ = 0; s_ < 2; ++s_) { const float w0 = w0a[i + s_], w1 = w1a[i + s_];
; #pragma unroll
;                 for (int j = 0; j < 4; ++j) { const u32x2 x = nxr[s_][j], a = na[s_][j], c = nc[s_][j], pp = np_[s_][j];
;                     f32x4 f;
;                     f[0] = w0 * __uint_as_float(a.x << 16) + w1 * __uint_as_float(c.x << 16) + __uint_as_float(pp.x << 16);
;                     f[1] = w0 * __uint_as_float(a.x & 0xffff0000u) + w1 * __uint_as_float(c.x & 0xffff0000u) + __uint_as_float(pp.x & 0xffff0000u);
;                     f[2] = w0 * __uint_as_float(a.y << 16) + w1 * __uint_as_float(c.y << 16) + __uint_as_float(pp.y << 16);
;                     f[3] = w0 * __uint_as_float(a.y & 0xffff0000u) + w1 * __uint_as_float(c.y & 0xffff0000u) + __uint_as_float(pp.y & 0xffff0000u);
;                     v[s_][j] = (f32x4){h2f_((unsigned short)(x.x & 0xffffu)), h2f_((unsigned short)(x.x >> 16)), h2f_((unsigned short)(x.y & 0xffffu)), h2f_((unsigned short)(x.y >> 16))} * ALPHA + f; } }
.LBB0_2012:
	s_andn2_b64 vcc, exec, s[0:1]
	s_cbranch_vccnz .LBB0_2078
	s_lshl_b64 s[0:1], s[4:5], 2
	v_readlane_b32 s4, v254, 0
	v_readlane_b32 s5, v254, 1
	s_add_u32 s34, s4, s0
	s_addc_u32 s35, s5, s1
	s_add_u32 s26, s36, 0x1d600000
	s_addc_u32 s27, s37, 0
	v_readlane_b32 s6, v254, 2
	s_add_u32 s28, s36, 0x23600000
	v_readlane_b32 s7, v254, 3
	s_addc_u32 s29, s37, 0
	s_lshl_b32 s6, s12, 1
	s_ashr_i32 s7, s6, 31
	s_lshl_b64 s[0:1], s[6:7], 2
	s_add_u32 s22, s38, s0
	s_addc_u32 s23, s39, s1
	s_add_u32 s30, s24, s0
	s_addc_u32 s31, s25, s1
	s_add_i32 s18, s12, s2
	s_lshl_b32 s0, s18, 1
	s_ashr_i32 s1, s0, 31
	s_lshl_b64 s[0:1], s[0:1], 2
	s_add_u32 s4, s38, s0
	s_addc_u32 s5, s39, s1
	s_add_u32 s0, s24, s0
	s_addc_u32 s1, s25, s1
	s_lshl_b32 s3, s40, 5
	s_add_i32 s6, s6, s3
	s_ashr_i32 s7, s6, 31
	s_lshl_b64 s[8:9], s[6:7], 2
	s_add_u32 s10, s24, s8
	s_addc_u32 s11, s25, s9
	global_load_dwordx2 v[38:39], v35, s[10:11]
	global_load_dwordx2 v[4:5], v35, s[22:23]
	s_lshl_b32 s7, s40, 4
	s_add_i32 s14, s18, s7
	s_lshl_b32 s10, s14, 1
	s_ashr_i32 s11, s10, 31
	s_lshl_b64 s[16:17], s[10:11], 2
	s_add_u32 s10, s24, s16
	s_addc_u32 s11, s25, s17
	global_load_dwordx2 v[30:31], v35, s[10:11]
	s_add_i32 s10, s6, s3
	s_ashr_i32 s11, s10, 31
	s_lshl_b64 s[10:11], s[10:11], 2
	s_add_u32 s40, s38, s10
	s_addc_u32 s41, s39, s11
	s_add_u32 s10, s24, s10
	s_addc_u32 s11, s25, s11
	global_load_dwordx2 v[36:37], v35, s[40:41]
	global_load_dwordx2 v[22:23], v35, s[10:11]
	s_add_i32 s10, s14, s7
	s_lshl_b32 s40, s10, 1
	s_ashr_i32 s41, s40, 31
	s_lshl_b64 s[40:41], s[40:41], 2
	s_add_u32 s42, s38, s40
	s_addc_u32 s43, s39, s41
	s_add_u32 s40, s24, s40
	s_addc_u32 s41, s25, s41
	s_add_i32 s6, s10, s2
	global_load_dwordx2 v[32:33], v35, s[42:43]
	global_load_dwordx2 v[16:17], v35, s[40:41]
	s_lshl_b32 s40, s6, 1
	s_ashr_i32 s41, s40, 31
	s_lshl_b64 s[40:41], s[40:41], 2
	s_add_u32 s42, s38, s40
	s_addc_u32 s43, s39, s41
	s_add_u32 s40, s24, s40
	s_addc_u32 s41, s25, s41
	s_add_i32 s2, s6, s2
	global_load_dwordx2 v[20:21], v35, s[42:43]
	global_load_dwordx2 v[10:11], v35, s[40:41]
	s_lshl_b32 s40, s2, 1
	s_ashr_i32 s41, s40, 31
	s_lshl_b64 s[40:41], s[40:41], 2
	s_add_u32 s42, s38, s40
	s_addc_u32 s43, s39, s41
	s_add_u32 s24, s24, s40
	s_addc_u32 s25, s25, s41
	s_ashr_i32 s13, s12, 31
	global_load_dwordx2 v[18:19], v35, s[42:43]
	global_load_dwordx2 v[8:9], v35, s[24:25]
	s_lshl_b64 s[24:25], s[12:13], 11
	s_add_u32 s40, s26, s24
	v_lshlrev_b32_e32 v6, 2, v34
	s_addc_u32 s41, s27, s25
	v_ashrrev_i32_e32 v7, 31, v6
	v_lshlrev_b64 v[2:3], 1, v[6:7]
	s_add_u32 s22, s28, s24
	v_lshl_add_u64 v[12:13], s[40:41], 0, v[2:3]
	s_addc_u32 s23, s29, s25
	v_lshl_add_u64 v[26:27], s[22:23], 0, v[2:3]
	s_ashr_i32 s19, s18, 31
	s_lshl_b64 s[22:23], s[18:19], 11
	s_add_u32 s24, s26, s22
	s_addc_u32 s25, s27, s23
	v_lshl_add_u64 v[28:29], s[26:27], 0, v[2:3]
	s_waitcnt vmcnt(0)
	v_ashrrev_i32_e32 v15, 31, v4
	v_mov_b32_e32 v14, v4
	v_ashrrev_i32_e32 v25, 31, v5
	v_mov_b32_e32 v24, v5
	v_lshlrev_b64 v[14:15], 11, v[14:15]
	v_lshlrev_b64 v[4:5], 11, v[24:25]
	v_lshl_add_u64 v[14:15], s[20:21], 0, v[14:15]
	v_lshl_add_u64 v[14:15], v[14:15], 0, v[2:3]
	v_lshl_add_u64 v[4:5], s[20:21], 0, v[4:5]
	v_lshl_add_u64 v[24:25], v[4:5], 0, v[2:3]
	global_load_dwordx2 v[98:99], v[12:13], off
	global_load_dwordx2 v[94:95], v[14:15], off
	global_load_dwordx2 v[96:97], v[24:25], off
	global_load_dwordx2 v[4:5], v[26:27], off
	global_load_dwordx2 v[100:101], v[12:13], off offset:512
	global_load_dwordx2 v[90:91], v[14:15], off offset:512
	global_load_dwordx2 v[92:93], v[24:25], off offset:512
	global_load_dwordx2 v[82:83], v[26:27], off offset:512
	global_load_dwordx2 v[102:103], v[12:13], off offset:1024
	global_load_dwordx2 v[76:77], v[14:15], off offset:1024
	global_load_dwordx2 v[80:81], v[24:25], off offset:1024
	global_load_dwordx2 v[74:75], v[26:27], off offset:1024
	global_load_dwordx2 v[42:43], v[12:13], off offset:1536
	global_load_dwordx2 v[64:65], v[14:15], off offset:1536
	global_load_dwordx2 v[66:67], v[24:25], off offset:1536
	global_load_dwordx2 v[62:63], v[26:27], off offset:1536
	v_lshl_add_u64 v[12:13], s[24:25], 0, v[2:3]
	global_load_dwordx2 v[14:15], v35, s[4:5]
	s_add_u32 s4, s28, s22
	s_addc_u32 s5, s29, s23
	s_waitcnt vmcnt(0)
	v_cvt_f32_f16_e32 v104, v98
	v_lshlrev_b32_e32 v114, 16, v94
	v_and_b32_e32 v115, 0xffff0000, v96
	v_lshlrev_b32_e32 v112, 16, v96
	v_and_b32_e32 v113, 0xffff0000, v94
	v_lshlrev_b32_e32 v94, 16, v95
	v_cvt_f32_f16_sdwa v105, v98 dst_sel:DWORD dst_unused:UNUSED_PAD src0_sel:WORD_1
	v_lshlrev_b32_e32 v116, 16, v4
	v_and_b32_e32 v117, 0xffff0000, v4
	v_lshlrev_b32_e32 v4, 16, v5
	v_and_b32_e32 v5, 0xffff0000, v5
	v_lshlrev_b32_e32 v96, 16, v90
	v_cvt_f32_f16_e32 v98, v100
	v_cvt_f32_f16_e32 v108, v102
	v_cvt_f32_f16_sdwa v109, v102 dst_sel:DWORD dst_unused:UNUSED_PAD src0_sel:WORD_1
	v_cvt_f32_f16_e32 v102, v103
	v_cvt_f32_f16_sdwa v103, v103 dst_sel:DWORD dst_unused:UNUSED_PAD src0_sel:WORD_1
	v_ashrrev_i32_e32 v27, 31, v15
	v_mov_b32_e32 v26, v15
	v_ashrrev_i32_e32 v25, 31, v14
	v_mov_b32_e32 v24, v14
	v_lshlrev_b64 v[14:15], 11, v[26:27]
	v_lshl_add_u64 v[26:27], s[4:5], 0, v[2:3]
	s_lshl_b32 s4, s33, 10
	s_ashr_i32 s5, s4, 31
	s_add_u32 s40, s38, s16
	s_addc_u32 s41, s39, s17
	v_lshlrev_b64 v[24:25], 11, v[24:25]
	s_add_u32 s8, s38, s8
	v_lshl_add_u64 v[24:25], s[20:21], 0, v[24:25]
	v_lshl_add_u64 v[14:15], s[20:21], 0, v[14:15]
	s_addc_u32 s9, s39, s9
	v_lshl_add_u64 v[24:25], v[24:25], 0, v[2:3]
	v_lshl_add_u64 v[14:15], v[14:15], 0, v[2:3]
	global_load_dwordx2 v[106:107], v[12:13], off
	global_load_dwordx2 v[78:79], v[24:25], off
	global_load_dwordx2 v[84:85], v[14:15], off
	global_load_dwordx2 v[72:73], v[26:27], off
	global_load_dwordx2 v[88:89], v[12:13], off offset:512
	global_load_dwordx2 v[68:69], v[24:25], off offset:512
	global_load_dwordx2 v[70:71], v[14:15], off offset:512
	global_load_dwordx2 v[60:61], v[26:27], off offset:512
	global_load_dwordx2 v[86:87], v[12:13], off offset:1024
	global_load_dwordx2 v[54:55], v[24:25], off offset:1024
	global_load_dwordx2 v[56:57], v[14:15], off offset:1024
	global_load_dwordx2 v[52:53], v[26:27], off offset:1024
	global_load_dwordx2 v[44:45], v[12:13], off offset:1536
	global_load_dwordx2 v[48:49], v[24:25], off offset:1536
	global_load_dwordx2 v[50:51], v[14:15], off offset:1536
	global_load_dwordx2 v[46:47], v[26:27], off offset:1536
	global_load_dwordx2 v[110:111], v35, s[30:31]
	global_load_dwordx2 v[152:153], v35, s[0:1]
	global_load_dwordx2 v[12:13], v35, s[8:9]
	v_lshl_add_u64 v[26:27], s[28:29], 0, v[2:3]
	s_add_i32 s16, s12, s7
	s_ashr_i32 s17, s16, 31
	s_lshl_b64 s[24:25], s[16:17], 11
	s_ashr_i32 s15, s14, 31
	s_lshl_b64 s[22:23], s[14:15], 11
	s_lshl_b64 s[8:9], s[12:13], 12
	s_add_u32 s7, s34, s8
	s_addc_u32 s11, s35, s9
	s_cmp_eq_u32 s33, 3
	s_cselect_b64 s[8:9], -1, 0
	s_and_b64 s[0:1], s[8:9], exec
	s_cselect_b32 s1, s11, 0
	s_cselect_b32 s0, s7, 0
	s_waitcnt vmcnt(0)
; __device__ __forceinline__ float h2f_(unsigned short b) { return (float)__builtin_bit_cast(_Float16, b); }
; __device__ __forceinline__ float wave_sum(float v) {
; #pragma unroll
;     for (int o = 1; o < 64; o <<= 1) v += __shfl_xor(v, o);
;     return v;
; template <bool MOE>
; __device__ __forceinline__ void ln2_phase(const Frame& F, int layer) {
;     ...
;         for (int i = 0; i < 8; i += 2) { f32x4 v[2][4];
; #pragma unroll
;             for (int s_ = 0; s_ < 2; ++s_) { const float w0 = w0a[i + s_], w1 = w1a[i + s_];
; #pragma unroll
;                 for (int j = 0; j < 4; ++j) { const u32x2 x = nxr[s_][j], a = na[s_][j], c = nc[s_][j], pp = np_[s_][j];
;                     f32x4 f;
;                     f[0] = w0 * __uint_as_float(a.x << 16) + w1 * __uint_as_float(c.x << 16) + __uint_as_float(pp.x << 16);
;                     f[1] = w0 * __uint_as_float(a.x & 0xffff0000u) + w1 * __uint_as_float(c.x & 0xffff0000u) + __uint_as_float(pp.x & 0xffff0000u);
;                     f[2] = w0 * __uint_as_float(a.y << 16) + w1 * __uint_as_float(c.y << 16) + __uint_as_float(pp.y << 16);
;                     f[3] = w0 * __uint_as_float(a.y & 0xffff0000u) + w1 * __uint_as_float(c.y & 0xffff0000u) + __uint_as_float(pp.y & 0xffff0000u);
;                     v[s_][j] = (f32x4){h2f_((unsigned short)(x.x & 0xffffu)), h2f_((unsigned short)(x.x >> 16)), h2f_((unsigned short)(x.y & 0xffffu)), h2f_((unsigned short)(x.y >> 16))} * ALPHA + f; } }
;             if (i + 2 < 8) { LN2_LOAD(0, F.gw + (i + 2) * F.NGW, s0a[i + 2], s1a[i + 2]); LN2_LOAD(1, F.gw + (i + 3) * F.NGW, s0a[i + 3], s1a[i + 3]); }
	v_pk_mul_f32 v[114:115], v[110:111], v[114:115]
	s_nop 0
	v_pk_fma_f32 v[112:113], v[110:111], v[112:113], v[114:115] op_sel:[1,0,0] op_sel_hi:[0,1,1]
	v_ashrrev_i32_e32 v15, 31, v12
	v_mov_b32_e32 v14, v12
	v_ashrrev_i32_e32 v25, 31, v13
	v_mov_b32_e32 v24, v13
	global_load_dwordx2 v[12:13], v35, s[40:41]
	v_lshlrev_b64 v[40:41], 11, v[24:25]
	v_lshlrev_b64 v[58:59], 11, v[14:15]
	v_and_b32_e32 v115, 0xffff0000, v95
	v_and_b32_e32 v95, 0xffff0000, v97
	v_lshlrev_b32_e32 v114, 16, v97
	v_pk_mul_f32 v[94:95], v[110:111], v[94:95]
	v_and_b32_e32 v97, 0xffff0000, v92
	v_pk_fma_f32 v[94:95], v[110:111], v[114:115], v[94:95] op_sel:[1,0,0] op_sel_hi:[0,1,1]
	v_pk_add_f32 v[4:5], v[94:95], v[4:5]
	v_lshlrev_b32_e32 v94, 16, v92
	v_and_b32_e32 v95, 0xffff0000, v90
	v_pk_mul_f32 v[96:97], v[110:111], v[96:97]
	v_lshlrev_b32_e32 v90, 16, v91
	v_pk_fma_f32 v[94:95], v[110:111], v[94:95], v[96:97] op_sel:[1,0,0] op_sel_hi:[0,1,1]
	v_and_b32_e32 v97, 0xffff0000, v91
	v_and_b32_e32 v91, 0xffff0000, v93
	v_pk_add_f32 v[112:113], v[112:113], v[116:117]
	v_lshlrev_b32_e32 v96, 16, v93
	v_pk_mul_f32 v[90:91], v[110:111], v[90:91]
	v_lshlrev_b32_e32 v92, 16, v74
	v_pk_fma_f32 v[90:91], v[110:111], v[96:97], v[90:91] op_sel:[1,0,0] op_sel_hi:[0,1,1]
	v_and_b32_e32 v93, 0xffff0000, v74
	v_lshlrev_b32_e32 v74, 16, v75
	v_and_b32_e32 v75, 0xffff0000, v75
	s_waitcnt vmcnt(0)
	v_ashrrev_i32_e32 v25, 31, v13
	v_mov_b32_e32 v24, v13
	v_ashrrev_i32_e32 v15, 31, v12
	v_mov_b32_e32 v14, v12
	v_lshlrev_b64 v[12:13], 11, v[24:25]
	v_and_b32_e32 v24, 64, v234
	v_add_u32_e32 v24, 64, v24
	v_xor_b32_e32 v25, 1, v234
	v_cmp_lt_i32_e32 vcc, v25, v24
	v_lshlrev_b64 v[14:15], 11, v[14:15]
	s_nop 0
	v_cndmask_b32_e32 v25, v234, v25, vcc
	v_lshlrev_b32_e32 v34, 2, v25
	v_xor_b32_e32 v25, 2, v234
	v_cmp_lt_i32_e32 vcc, v25, v24
	s_nop 1
	v_cndmask_b32_e32 v25, v234, v25, vcc
	v_lshlrev_b32_e32 v164, 2, v25
	v_xor_b32_e32 v25, 4, v234
	v_cmp_lt_i32_e32 vcc, v25, v24
	s_nop 1
	v_cndmask_b32_e32 v25, v234, v25, vcc
	v_lshlrev_b32_e32 v165, 2, v25
	v_xor_b32_e32 v25, 8, v234
	v_cmp_lt_i32_e32 vcc, v25, v24
	s_nop 1
	v_cndmask_b32_e32 v25, v234, v25, vcc
	v_lshlrev_b32_e32 v166, 2, v25
	v_xor_b32_e32 v25, 16, v234
	v_cmp_lt_i32_e32 vcc, v25, v24
	s_nop 1
	v_cndmask_b32_e32 v25, v234, v25, vcc
	v_lshlrev_b32_e32 v167, 2, v25
	v_xor_b32_e32 v25, 32, v234
	v_cmp_lt_i32_e32 vcc, v25, v24
	s_nop 1
	v_cndmask_b32_e32 v24, v234, v25, vcc
	v_lshlrev_b32_e32 v168, 2, v24
	v_lshl_add_u64 v[24:25], s[20:21], 0, v[2:3]
	v_cvt_f32_f16_e32 v2, v99
	v_cvt_f32_f16_sdwa v3, v99 dst_sel:DWORD dst_unused:UNUSED_PAD src0_sel:WORD_1
	v_cvt_f32_f16_sdwa v99, v100 dst_sel:DWORD dst_unused:UNUSED_PAD src0_sel:WORD_1
	v_cvt_f32_f16_e32 v100, v101
	v_cvt_f32_f16_sdwa v101, v101 dst_sel:DWORD dst_unused:UNUSED_PAD src0_sel:WORD_1
	s_mov_b32 s20, 0x3fd744fd
	v_pk_fma_f32 v[2:3], v[2:3], s[20:21], v[4:5] op_sel_hi:[1,0,1]
	v_pk_fma_f32 v[4:5], v[104:105], s[20:21], v[112:113] op_sel_hi:[1,0,1]
	v_lshlrev_b32_e32 v104, 16, v82
	v_and_b32_e32 v105, 0xffff0000, v82
	v_lshlrev_b32_e32 v82, 16, v83
	v_and_b32_e32 v83, 0xffff0000, v83
	v_pk_add_f32 v[82:83], v[90:91], v[82:83]
	v_lshlrev_b32_e32 v90, 16, v76
	v_and_b32_e32 v91, 0xffff0000, v80
	v_pk_fma_f32 v[128:129], v[100:101], s[20:21], v[82:83] op_sel_hi:[1,0,1]
	v_lshlrev_b32_e32 v82, 16, v80
	v_and_b32_e32 v83, 0xffff0000, v76
	v_pk_mul_f32 v[90:91], v[110:111], v[90:91]
	v_lshlrev_b32_e32 v76, 16, v77
	v_pk_fma_f32 v[82:83], v[110:111], v[82:83], v[90:91] op_sel:[1,0,0] op_sel_hi:[0,1,1]
	v_and_b32_e32 v91, 0xffff0000, v77
	v_and_b32_e32 v77, 0xffff0000, v81
	v_lshlrev_b32_e32 v90, 16, v81
	v_pk_mul_f32 v[76:77], v[110:111], v[76:77]
	v_pk_add_f32 v[82:83], v[82:83], v[92:93]
	v_pk_fma_f32 v[76:77], v[110:111], v[90:91], v[76:77] op_sel:[1,0,0] op_sel_hi:[0,1,1]
	v_pk_add_f32 v[74:75], v[76:77], v[74:75]
	v_lshlrev_b32_e32 v76, 16, v64
	v_and_b32_e32 v77, 0xffff0000, v66
	v_pk_fma_f32 v[114:115], v[102:103], s[20:21], v[74:75] op_sel_hi:[1,0,1]
	v_lshlrev_b32_e32 v74, 16, v66
	v_and_b32_e32 v75, 0xffff0000, v64
	v_pk_mul_f32 v[76:77], v[110:111], v[76:77]
	v_lshlrev_b32_e32 v64, 16, v65
	v_pk_fma_f32 v[74:75], v[110:111], v[74:75], v[76:77] op_sel:[1,0,0] op_sel_hi:[0,1,1]
	v_lshlrev_b32_e32 v76, 16, v62
	v_and_b32_e32 v77, 0xffff0000, v62
	v_pk_add_f32 v[74:75], v[74:75], v[76:77]
	v_and_b32_e32 v77, 0xffff0000, v65
	v_and_b32_e32 v65, 0xffff0000, v67
	v_lshlrev_b32_e32 v76, 16, v67
	v_pk_mul_f32 v[64:65], v[110:111], v[64:65]
	v_lshlrev_b32_e32 v62, 16, v63
	v_pk_fma_f32 v[64:65], v[110:111], v[76:77], v[64:65] op_sel:[1,0,0] op_sel_hi:[0,1,1]
	v_and_b32_e32 v63, 0xffff0000, v63
	v_pk_add_f32 v[62:63], v[64:65], v[62:63]
	v_cvt_f32_f16_e32 v64, v42
	v_cvt_f32_f16_sdwa v65, v42 dst_sel:DWORD dst_unused:UNUSED_PAD src0_sel:WORD_1
	v_cvt_f32_f16_e32 v42, v43
	v_cvt_f32_f16_sdwa v43, v43 dst_sel:DWORD dst_unused:UNUSED_PAD src0_sel:WORD_1
	v_pk_fma_f32 v[116:117], v[108:109], s[20:21], v[82:83] op_sel_hi:[1,0,1]
	v_lshl_add_u64 v[40:41], v[24:25], 0, v[40:41]
	v_pk_add_f32 v[94:95], v[94:95], v[104:105]
	v_pk_fma_f32 v[108:109], v[42:43], s[20:21], v[62:63] op_sel_hi:[1,0,1]
	v_lshl_add_u64 v[42:43], v[28:29], 0, s[24:25]
	v_lshl_add_u64 v[62:63], v[26:27], 0, s[24:25]
	v_lshl_add_u64 v[58:59], v[24:25], 0, v[58:59]
	global_load_dwordx2 v[144:145], v[42:43], off
	global_load_dwordx2 v[148:149], v[58:59], off
	global_load_dwordx2 v[150:151], v[40:41], off
	global_load_dwordx2 v[146:147], v[62:63], off
	global_load_dwordx2 v[136:137], v[42:43], off offset:512
	global_load_dwordx2 v[140:141], v[58:59], off offset:512
	global_load_dwordx2 v[142:143], v[40:41], off offset:512
; __device__ __forceinline__ unsigned cvt4_fp8(float a, float b, float c, float d) { int w = 0; w = __builtin_amdgcn_cvt_pk_fp8_f32(a, b, w, false); w = __builtin_amdgcn_cvt_pk_fp8_f32(c, d, w, true); return (unsigned)w; }
; __device__ __forceinline__ void ln_row_write(f32x4 (&v)[4], const float* g, const float* bta, float* of, bf16_t* ob, int lane, unsigned char* o8 = nullptr) {
;     float s = 0.f;
; #pragma unroll
;     for (int j = 0; j < 4; ++j) s += (v[j][0] + v[j][1]) + (v[j][2] + v[j][3]);
;     const float mean = wave_sum(s) * (1.0f / 1024.0f); float s2 = 0.f;
; #pragma unroll
;     for (int j = 0; j < 4; ++j) { v[j] = v[j] - mean; s2 += (v[j][0] * v[j][0] + v[j][1] * v[j][1]) + (v[j][2] * v[j][2] + v[j][3] * v[j][3]); }
;     const float rstd = rsqrtf(wave_sum(s2) * (1.0f / 1024.0f) + EPS);
; #pragma unroll
;     for (int j = 0; j < 4; ++j) { const f32x4 gg = *(const f32x4*)(g + 4 * lane + 256 * j), bb = *(const f32x4*)(bta + 4 * lane + 256 * j); v[j] = v[j] * rstd * gg + bb;
;         if (of) *(f32x4*)(of + 4 * lane + 256 * j) = v[j]; u32x2 w; w.x = cvt_pk_f16(v[j][0], v[j][1]); w.y = cvt_pk_f16(v[j][2], v[j][3]); *(u32x2*)(ob + 4 * lane + 256 * j) = w;
;         if (o8) *(unsigned*)(o8 + 4 * lane + 256 * j) = cvt4_fp8(v[j][0], v[j][1], v[j][2], v[j][3]); }
	global_load_dwordx2 v[138:139], v[62:63], off offset:512
	global_load_dwordx2 v[120:121], v[42:43], off offset:1024
	global_load_dwordx2 v[132:133], v[58:59], off offset:1024
	global_load_dwordx2 v[134:135], v[40:41], off offset:1024
	global_load_dwordx2 v[126:127], v[62:63], off offset:1024
	global_load_dwordx2 v[112:113], v[42:43], off offset:1536
	global_load_dwordx2 v[118:119], v[58:59], off offset:1536
	global_load_dwordx2 v[122:123], v[40:41], off offset:1536
	global_load_dwordx2 v[124:125], v[62:63], off offset:1536
	v_lshl_add_u64 v[40:41], v[28:29], 0, s[22:23]
	v_lshl_add_u64 v[14:15], v[24:25], 0, v[14:15]
	v_lshl_add_u64 v[12:13], v[24:25], 0, v[12:13]
	v_lshl_add_u64 v[62:63], v[26:27], 0, s[22:23]
	v_pk_fma_f32 v[130:131], v[98:99], s[20:21], v[94:95] op_sel_hi:[1,0,1]
	v_pk_fma_f32 v[110:111], v[64:65], s[20:21], v[74:75] op_sel_hi:[1,0,1]
	global_load_dwordx2 v[98:99], v[40:41], off
	global_load_dwordx2 v[102:103], v[14:15], off
	global_load_dwordx2 v[104:105], v[12:13], off
	global_load_dwordx2 v[100:101], v[62:63], off
	global_load_dwordx2 v[90:91], v[40:41], off offset:512
	global_load_dwordx2 v[94:95], v[14:15], off offset:512
	global_load_dwordx2 v[96:97], v[12:13], off offset:512
	global_load_dwordx2 v[92:93], v[62:63], off offset:512
	global_load_dwordx2 v[74:75], v[40:41], off offset:1024
	global_load_dwordx2 v[80:81], v[14:15], off offset:1024
	global_load_dwordx2 v[82:83], v[12:13], off offset:1024
	global_load_dwordx2 v[76:77], v[62:63], off offset:1024
	global_load_dwordx2 v[58:59], v[40:41], off offset:1536
	global_load_dwordx2 v[64:65], v[14:15], off offset:1536
	global_load_dwordx2 v[66:67], v[12:13], off offset:1536
	s_nop 0
	global_load_dwordx2 v[62:63], v[62:63], off offset:1536
	v_pk_mov_b32 v[12:13], v[4:5], v[2:3] op_sel:[1,0]
	v_mov_b32_e32 v14, v4
	v_mov_b32_e32 v15, v3
	v_pk_add_f32 v[12:13], v[12:13], v[14:15]
	v_pk_mov_b32 v[14:15], v[130:131], v[128:129] op_sel:[1,0]
	v_mov_b32_e32 v154, v130
	v_mov_b32_e32 v155, v129
	v_pk_add_f32 v[14:15], v[14:15], v[154:155]
	v_add_f32_e32 v12, v12, v13
	v_pk_add_f32 v[14:15], v[14:15], v[14:15] op_sel:[0,1] op_sel_hi:[1,0]
	v_add_f32_e32 v12, 0, v12
	v_add_f32_e32 v154, v116, v117
	v_add_f32_e32 v156, v114, v115
	v_mov_b32_e32 v13, v110
	v_mov_b32_e32 v15, v111
	v_mov_b32_e32 v155, v108
	v_mov_b32_e32 v157, v109
	v_pk_add_f32 v[12:13], v[12:13], v[14:15]
	v_pk_add_f32 v[14:15], v[154:155], v[156:157]
	s_lshl_b64 s[20:21], s[4:5], 2
	v_pk_add_f32 v[12:13], v[12:13], v[14:15]
	v_readlane_b32 s24, v255, 18
	v_add_f32_e32 v12, v12, v13
	ds_bpermute_b32 v13, v34, v12
	v_readlane_b32 s25, v255, 19
	s_add_u32 s4, s24, s20
	v_readlane_b32 s26, v255, 20
	s_addc_u32 s5, s25, s21
	s_waitcnt lgkmcnt(0)
	v_add_f32_e32 v12, v12, v13
	ds_bpermute_b32 v13, v164, v12
	v_readlane_b32 s27, v255, 21
	s_add_u32 s20, s26, s20
	s_addc_u32 s21, s27, s21
	s_cmp_lg_u64 s[0:1], 0
	s_waitcnt lgkmcnt(0)
	v_add_f32_e32 v12, v12, v13
	ds_bpermute_b32 v13, v165, v12
	s_waitcnt lgkmcnt(0)
	v_add_f32_e32 v12, v12, v13
	ds_bpermute_b32 v13, v166, v12
	s_waitcnt lgkmcnt(0)
	v_add_f32_e32 v12, v12, v13
	ds_bpermute_b32 v13, v167, v12
	s_waitcnt lgkmcnt(0)
	v_add_f32_e32 v12, v12, v13
	ds_bpermute_b32 v13, v168, v12
	s_waitcnt lgkmcnt(0)
	v_add_f32_e32 v158, v12, v13
	v_fmamk_f32 v5, v158, 0xba800000, v5
	v_fmac_f32_e32 v4, 0xba800000, v158
	v_fmamk_f32 v3, v158, 0xba800000, v3
	v_fmac_f32_e32 v2, 0xba800000, v158
	v_pk_mul_f32 v[12:13], v[2:3], v[2:3]
	v_pk_mul_f32 v[14:15], v[4:5], v[4:5]
	v_fmamk_f32 v129, v158, 0xba800000, v129
	v_pk_mov_b32 v[154:155], v[14:15], v[12:13] op_sel:[1,0]
	v_mov_b32_e32 v15, v13
	v_pk_add_f32 v[12:13], v[154:155], v[14:15]
	v_fmac_f32_e32 v128, 0xba800000, v158
	v_fmamk_f32 v131, v158, 0xba800000, v131
	v_fmac_f32_e32 v130, 0xba800000, v158
	v_pk_add_f32 v[12:13], v[12:13], v[12:13] op_sel_hi:[0,1]
	v_pk_mul_f32 v[14:15], v[128:129], v[128:129]
	v_pk_mul_f32 v[154:155], v[130:131], v[130:131]
	v_fmac_f32_e32 v116, 0xba800000, v158
	v_pk_mov_b32 v[156:157], v[154:155], v[14:15] op_sel:[1,0]
	v_mov_b32_e32 v155, v15
	v_fmac_f32_e32 v114, 0xba800000, v158
	v_fmamk_f32 v117, v158, 0xba800000, v117
	v_mul_f32_e32 v12, v116, v116
	v_pk_add_f32 v[14:15], v[156:157], v[154:155]
	v_fmamk_f32 v115, v158, 0xba800000, v115
	v_pk_fma_f32 v[154:155], v[116:117], v[116:117], v[12:13] op_sel_hi:[1,1,0]
	v_mul_f32_e32 v12, v114, v114
	v_pk_add_f32 v[14:15], v[14:15], v[14:15] op_sel_hi:[0,1]
	v_pk_fma_f32 v[156:157], v[114:115], v[114:115], v[12:13] op_sel_hi:[1,1,0]
	v_fmamk_f32 v109, v158, 0xba800000, v109
	v_fmac_f32_e32 v108, 0xba800000, v158
	v_fmamk_f32 v111, v158, 0xba800000, v111
	v_fmac_f32_e32 v110, 0xba800000, v158
	v_mul_f32_e32 v154, v110, v110
	v_mul_f32_e32 v156, v111, v111
	v_mul_f32_e32 v12, v108, v108
	v_mul_f32_e32 v14, v109, v109
	v_pk_add_f32 v[154:155], v[154:155], v[156:157]
	v_pk_add_f32 v[12:13], v[12:13], v[14:15]
	v_lshlrev_b64 v[156:157], 2, v[6:7]
	v_pk_add_f32 v[12:13], v[154:155], v[12:13]
	v_lshl_add_u64 v[14:15], s[20:21], 0, v[156:157]
	v_add_f32_e32 v12, v12, v13
	ds_bpermute_b32 v13, v34, v12
	s_waitcnt lgkmcnt(0)
	v_add_f32_e32 v12, v12, v13
	ds_bpermute_b32 v13, v164, v12
	s_waitcnt lgkmcnt(0)
	v_add_f32_e32 v12, v12, v13
	ds_bpermute_b32 v13, v165, v12
	s_waitcnt lgkmcnt(0)
	v_add_f32_e32 v12, v12, v13
	ds_bpermute_b32 v13, v166, v12
	s_waitcnt lgkmcnt(0)
	v_add_f32_e32 v12, v12, v13
	ds_bpermute_b32 v13, v167, v12
	s_waitcnt lgkmcnt(0)
	v_add_f32_e32 v12, v12, v13
	ds_bpermute_b32 v13, v168, v12
	s_waitcnt lgkmcnt(0)
	v_add_f32_e32 v12, v12, v13
	v_fmamk_f32 v12, v12, 0x3a800000, v230
	v_cmp_gt_f32_e32 vcc, s97, v12
	v_mul_f32_e32 v13, 0x4b800000, v12
	s_nop 0
	v_cndmask_b32_e32 v12, v12, v13, vcc
	v_rsq_f32_e32 v12, v12
	s_nop 0
	v_mul_f32_e32 v13, 0x45800000, v12
	v_cndmask_b32_e32 v154, v12, v13, vcc
	v_lshl_add_u64 v[12:13], s[4:5], 0, v[156:157]
	global_load_dwordx4 v[176:179], v[12:13], off
	global_load_dwordx4 v[192:195], v[14:15], off
	v_pk_mul_f32 v[162:163], v[4:5], v[154:155] op_sel_hi:[1,0]
	v_pk_mul_f32 v[2:3], v[2:3], v[154:155] op_sel_hi:[1,0]
	s_cselect_b64 s[4:5], -1, 0
	s_cmp_eq_u64 s[0:1], 0
	v_lshl_add_u64 v[156:157], s[0:1], 0, v[156:157]
	s_waitcnt vmcnt(0)
	v_pk_fma_f32 v[4:5], v[178:179], v[2:3], v[194:195]
	v_pk_fma_f32 v[2:3], v[176:177], v[162:163], v[192:193]
	s_cbranch_scc1 .LBB0_2015
	global_store_dwordx4 v[156:157], v[2:5], off
; __device__ __forceinline__ unsigned cvt4_fp8(float a, float b, float c, float d) { int w = 0; w = __builtin_amdgcn_cvt_pk_fp8_f32(a, b, w, false); w = __builtin_amdgcn_cvt_pk_fp8_f32(c, d, w, true); return (unsigned)w; }
; __device__ __forceinline__ void ln_row_write(f32x4 (&v)[4], const float* g, const float* bta, float* of, bf16_t* ob, int lane, unsigned char* o8 = nullptr) {
;     ...
; #pragma unroll
;     for (int j = 0; j < 4; ++j) { const f32x4 gg = *(const f32x4*)(g + 4 * lane + 256 * j), bb = *(const f32x4*)(bta + 4 * lane + 256 * j); v[j] = v[j] * rstd * gg + bb;
;         if (of) *(f32x4*)(of + 4 * lane + 256 * j) = v[j]; u32x2 w; w.x = cvt_pk_f16(v[j][0], v[j][1]); w.y = cvt_pk_f16(v[j][2], v[j][3]); *(u32x2*)(ob + 4 * lane + 256 * j) = w;
;         if (o8) *(unsigned*)(o8 + 4 * lane + 256 * j) = cvt4_fp8(v[j][0], v[j][1], v[j][2], v[j][3]); }
.LBB0_2015:
	s_lshl_b64 s[0:1], s[12:13], 10
	v_lshl_add_u64 v[160:161], s[0:1], 1, v[28:29]
	v_cvt_pk_f16_f32 v162, v2, v3
	v_cvt_pk_f16_f32 v163, v4, v5
	global_store_dwordx2 v[160:161], v[162:163], off
	v_mov_b32_e32 v162, v35
	v_cvt_pk_fp8_f32 v162, v2, v3
	s_add_u32 s20, s36, 0xec00000
	s_addc_u32 s21, s37, 0
	s_add_u32 s22, s20, s0
	v_cvt_pk_fp8_f32 v162, v4, v5 op_sel:[0,0,1]
	s_addc_u32 s23, s21, s1
	v_lshl_add_u64 v[158:159], s[22:23], 0, v[6:7]
	v_mov_b32_e32 v163, v154
	global_store_dword v[158:159], v162, off
	global_load_dwordx4 v[180:183], v[12:13], off offset:1024
	global_load_dwordx4 v[206:209], v[14:15], off offset:1024
	v_mov_b32_e32 v162, v154
	v_mov_b32_e32 v155, v154
	v_pk_mul_f32 v[128:129], v[128:129], v[162:163]
	v_pk_mul_f32 v[130:131], v[130:131], v[154:155]
	s_andn2_b64 vcc, exec, s[4:5]
	s_waitcnt vmcnt(0)
	v_pk_fma_f32 v[4:5], v[128:129], v[182:183], v[208:209]
	v_cndmask_b32_e64 v128, 0, 1, s[4:5]
	v_pk_fma_f32 v[2:3], v[130:131], v[180:181], v[206:207]
	v_cmp_ne_u32_e64 s[0:1], 1, v128
	s_cbranch_vccnz .LBB0_2017
	global_store_dwordx4 v[156:157], v[2:5], off offset:1024
.LBB0_2017:
	v_mov_b32_e32 v128, v35
	v_cvt_pk_fp8_f32 v128, v2, v3
	v_cvt_pk_f16_f32 v2, v2, v3
	v_cvt_pk_f16_f32 v3, v4, v5
	v_pk_mul_f32 v[114:115], v[114:115], v[162:163]
	v_cvt_pk_fp8_f32 v128, v4, v5 op_sel:[0,0,1]
	v_pk_mul_f32 v[116:117], v[116:117], v[154:155]
	s_and_b64 vcc, exec, s[0:1]
	global_store_dwordx2 v[160:161], v[2:3], off offset:512
	global_store_dword v[158:159], v128, off offset:256
	global_load_dwordx4 v[184:187], v[12:13], off offset:2048
	s_nop 0
	global_load_dwordx4 v[210:213], v[14:15], off offset:2048
	s_waitcnt vmcnt(0)
	v_pk_fma_f32 v[4:5], v[114:115], v[186:187], v[212:213]
	v_pk_fma_f32 v[2:3], v[116:117], v[184:185], v[210:211]
	s_cbranch_vccnz .LBB0_2019
	global_store_dwordx4 v[156:157], v[2:5], off offset:2048
.LBB0_2019:
	v_mov_b32_e32 v114, v35
	v_cvt_pk_fp8_f32 v114, v2, v3
	v_cvt_pk_f16_f32 v2, v2, v3
	v_cvt_pk_f16_f32 v3, v4, v5
	v_mov_b32_e32 v128, v154
	v_cvt_pk_fp8_f32 v114, v4, v5 op_sel:[0,0,1]
	v_mov_b32_e32 v129, v154
	v_pk_mul_f32 v[110:111], v[110:111], v[154:155]
	global_store_dwordx2 v[160:161], v[2:3], off offset:1024
	global_store_dword v[158:159], v114, off offset:512
	global_load_dwordx4 v[188:191], v[12:13], off offset:3072
	s_nop 0
	global_load_dwordx4 v[214:217], v[14:15], off offset:3072
	v_pk_mul_f32 v[108:109], v[108:109], v[128:129]
	s_and_b64 vcc, exec, s[0:1]
	s_waitcnt vmcnt(0)
	v_pk_fma_f32 v[4:5], v[108:109], v[190:191], v[216:217]
	v_pk_fma_f32 v[2:3], v[110:111], v[188:189], v[214:215]
	s_cbranch_vccnz .LBB0_2021
	global_store_dwordx4 v[156:157], v[2:5], off offset:3072
.LBB0_2021:
	v_lshlrev_b32_e32 v128, 16, v78
	v_and_b32_e32 v129, 0xffff0000, v84
	v_cvt_f32_f16_sdwa v109, v106 dst_sel:DWORD dst_unused:UNUSED_PAD src0_sel:WORD_1
	v_cvt_f32_f16_e32 v108, v106
	v_cvt_f32_f16_sdwa v111, v107 dst_sel:DWORD dst_unused:UNUSED_PAD src0_sel:WORD_1
	v_cvt_f32_f16_e32 v110, v107
	v_cvt_f32_f16_sdwa v107, v88 dst_sel:DWORD dst_unused:UNUSED_PAD src0_sel:WORD_1
	v_cvt_f32_f16_e32 v106, v88
	v_cvt_f32_f16_sdwa v115, v89 dst_sel:DWORD dst_unused:UNUSED_PAD src0_sel:WORD_1
	v_cvt_f32_f16_e32 v114, v89
	v_cvt_f32_f16_sdwa v89, v86 dst_sel:DWORD dst_unused:UNUSED_PAD src0_sel:WORD_1
	v_cvt_f32_f16_e32 v88, v86
	v_cvt_f32_f16_sdwa v117, v87 dst_sel:DWORD dst_unused:UNUSED_PAD src0_sel:WORD_1
	v_cvt_f32_f16_e32 v116, v87
	v_lshlrev_b32_e32 v86, 16, v84
	v_and_b32_e32 v87, 0xffff0000, v78
	v_pk_mul_f32 v[128:129], v[152:153], v[128:129]
	v_lshlrev_b32_e32 v78, 16, v79
	v_pk_fma_f32 v[86:87], v[152:153], v[86:87], v[128:129] op_sel:[1,0,0] op_sel_hi:[0,1,1]
	v_and_b32_e32 v129, 0xffff0000, v79
	v_and_b32_e32 v79, 0xffff0000, v85
	v_lshlrev_b32_e32 v130, 16, v72
	v_and_b32_e32 v131, 0xffff0000, v72
	v_lshlrev_b32_e32 v128, 16, v85
	v_pk_mul_f32 v[78:79], v[152:153], v[78:79]
	v_pk_add_f32 v[86:87], v[86:87], v[130:131]
	v_lshlrev_b32_e32 v72, 16, v73
	v_and_b32_e32 v73, 0xffff0000, v73
	v_pk_fma_f32 v[78:79], v[152:153], v[128:129], v[78:79] op_sel:[1,0,0] op_sel_hi:[0,1,1]
	s_mov_b32 s0, 0x3fd744fd
	v_pk_add_f32 v[78:79], v[78:79], v[72:73]
	v_pk_fma_f32 v[72:73], v[108:109], s[0:1], v[86:87] op_sel_hi:[1,0,1]
	v_lshlrev_b32_e32 v86, 16, v68
	v_and_b32_e32 v87, 0xffff0000, v70
	v_lshlrev_b32_e32 v84, 16, v70
	v_and_b32_e32 v85, 0xffff0000, v68
	v_pk_mul_f32 v[86:87], v[152:153], v[86:87]
	v_lshlrev_b32_e32 v68, 16, v69
	v_pk_fma_f32 v[84:85], v[152:153], v[84:85], v[86:87] op_sel:[1,0,0] op_sel_hi:[0,1,1]
	v_and_b32_e32 v87, 0xffff0000, v69
	v_and_b32_e32 v69, 0xffff0000, v71
	v_lshlrev_b32_e32 v108, 16, v60
	v_and_b32_e32 v109, 0xffff0000, v60
	v_lshlrev_b32_e32 v86, 16, v71
	v_pk_mul_f32 v[68:69], v[152:153], v[68:69]
	v_pk_add_f32 v[84:85], v[84:85], v[108:109]
	v_lshlrev_b32_e32 v60, 16, v61
	v_and_b32_e32 v61, 0xffff0000, v61
	v_pk_fma_f32 v[68:69], v[152:153], v[86:87], v[68:69] op_sel:[1,0,0] op_sel_hi:[0,1,1]
	v_pk_add_f32 v[68:69], v[68:69], v[60:61]
	v_pk_fma_f32 v[60:61], v[106:107], s[0:1], v[84:85] op_sel_hi:[1,0,1]
	v_lshlrev_b32_e32 v84, 16, v54
	v_and_b32_e32 v85, 0xffff0000, v56
	v_lshlrev_b32_e32 v70, 16, v56
	v_and_b32_e32 v71, 0xffff0000, v54
	v_pk_mul_f32 v[84:85], v[152:153], v[84:85]
	v_lshlrev_b32_e32 v54, 16, v55
	v_pk_fma_f32 v[70:71], v[152:153], v[70:71], v[84:85] op_sel:[1,0,0] op_sel_hi:[0,1,1]
	v_and_b32_e32 v85, 0xffff0000, v55
	v_and_b32_e32 v55, 0xffff0000, v57
	v_lshlrev_b32_e32 v86, 16, v52
	v_and_b32_e32 v87, 0xffff0000, v52
	v_lshlrev_b32_e32 v84, 16, v57
	v_pk_mul_f32 v[54:55], v[152:153], v[54:55]
	v_pk_add_f32 v[70:71], v[70:71], v[86:87]
; __device__ __forceinline__ float h2f_(unsigned short b) { return (float)__builtin_bit_cast(_Float16, b); }
; __device__ __forceinline__ void ln_row_write(f32x4 (&v)[4], const float* g, const float* bta, float* of, bf16_t* ob, int lane, unsigned char* o8 = nullptr) {
;     float s = 0.f;
; #pragma unroll
;     for (int j = 0; j < 4; ++j) s += (v[j][0] + v[j][1]) + (v[j][2] + v[j][3]);
;     const float mean = wave_sum(s) * (1.0f / 1024.0f); float s2 = 0.f;
; #pragma unroll
;     for (int j = 0; j < 4; ++j) { v[j] = v[j] - mean; s2 += (v[j][0] * v[j][0] + v[j][1] * v[j][1]) + (v[j][2] * v[j][2] + v[j][3] * v[j][3]); }
;     const float rstd = rsqrtf(wave_sum(s2) * (1.0f / 1024.0f) + EPS);
; #pragma unroll
;     for (int j = 0; j < 4; ++j) { const f32x4 gg = *(const f32x4*)(g + 4 * lane + 256 * j), bb = *(const f32x4*)(bta + 4 * lane + 256 * j); v[j] = v[j] * rstd * gg + bb;
;         if (of) *(f32x4*)(of + 4 * lane + 256 * j) = v[j]; u32x2 w; w.x = cvt_pk_f16(v[j][0], v[j][1]); w.y = cvt_pk_f16(v[j][2], v[j][3]); *(u32x2*)(ob + 4 * lane + 256 * j) = w;
;         if (o8) *(unsigned*)(o8 + 4 * lane + 256 * j) = cvt4_fp8(v[j][0], v[j][1], v[j][2], v[j][3]); }
; template <bool MOE>
; __device__ __forceinline__ void ln2_phase(const Frame& F, int layer) {
;     ...
;             for (int s_ = 0; s_ < 2; ++s_) { const float w0 = w0a[i + s_], w1 = w1a[i + s_];
; #pragma unroll
;                 for (int j = 0; j < 4; ++j) { const u32x2 x = nxr[s_][j], a = na[s_][j], c = nc[s_][j], pp = np_[s_][j];
;                     f32x4 f;
;                     f[0] = w0 * __uint_as_float(a.x << 16) + w1 * __uint_as_float(c.x << 16) + __uint_as_float(pp.x << 16);
;                     f[1] = w0 * __uint_as_float(a.x & 0xffff0000u) + w1 * __uint_as_float(c.x & 0xffff0000u) + __uint_as_float(pp.x & 0xffff0000u);
;                     f[2] = w0 * __uint_as_float(a.y << 16) + w1 * __uint_as_float(c.y << 16) + __uint_as_float(pp.y << 16);
;                     f[3] = w0 * __uint_as_float(a.y & 0xffff0000u) + w1 * __uint_as_float(c.y & 0xffff0000u) + __uint_as_float(pp.y & 0xffff0000u);
;                     v[s_][j] = (f32x4){h2f_((unsigned short)(x.x & 0xffffu)), h2f_((unsigned short)(x.x >> 16)), h2f_((unsigned short)(x.y & 0xffffu)), h2f_((unsigned short)(x.y >> 16))} * ALPHA + f; } }
	v_lshlrev_b32_e32 v52, 16, v53
	v_and_b32_e32 v53, 0xffff0000, v53
	v_pk_fma_f32 v[54:55], v[152:153], v[84:85], v[54:55] op_sel:[1,0,0] op_sel_hi:[0,1,1]
	v_pk_add_f32 v[54:55], v[54:55], v[52:53]
	v_pk_fma_f32 v[52:53], v[88:89], s[0:1], v[70:71] op_sel_hi:[1,0,1]
	v_lshlrev_b32_e32 v70, 16, v48
	v_and_b32_e32 v71, 0xffff0000, v50
	v_lshlrev_b32_e32 v56, 16, v50
	v_and_b32_e32 v57, 0xffff0000, v48
	v_pk_mul_f32 v[70:71], v[152:153], v[70:71]
	v_lshlrev_b32_e32 v48, 16, v49
	v_pk_fma_f32 v[56:57], v[152:153], v[56:57], v[70:71] op_sel:[1,0,0] op_sel_hi:[0,1,1]
	v_lshlrev_b32_e32 v70, 16, v46
	v_and_b32_e32 v71, 0xffff0000, v46
	v_pk_add_f32 v[56:57], v[56:57], v[70:71]
	v_lshlrev_b32_e32 v70, 16, v51
	v_and_b32_e32 v71, 0xffff0000, v49
	v_and_b32_e32 v49, 0xffff0000, v51
	v_cvt_f32_f16_sdwa v51, v45 dst_sel:DWORD dst_unused:UNUSED_PAD src0_sel:WORD_1
	v_cvt_f32_f16_e32 v50, v45
	v_pk_mul_f32 v[48:49], v[152:153], v[48:49]
	v_lshlrev_b32_e32 v46, 16, v47
	v_pk_fma_f32 v[48:49], v[152:153], v[70:71], v[48:49] op_sel:[1,0,0] op_sel_hi:[0,1,1]
	v_and_b32_e32 v47, 0xffff0000, v47
	v_pk_add_f32 v[48:49], v[48:49], v[46:47]
	v_cvt_f32_f16_sdwa v47, v44 dst_sel:DWORD dst_unused:UNUSED_PAD src0_sel:WORD_1
	v_cvt_f32_f16_e32 v46, v44
	v_pk_fma_f32 v[44:45], v[50:51], s[0:1], v[48:49] op_sel_hi:[1,0,1]
	v_cvt_pk_f16_f32 v48, v2, v3
	v_cvt_pk_f16_f32 v49, v4, v5
	global_store_dwordx2 v[160:161], v[48:49], off offset:1536
	v_mov_b32_e32 v48, v35
	v_cvt_pk_fp8_f32 v48, v2, v3
	v_pk_fma_f32 v[78:79], v[110:111], s[0:1], v[78:79] op_sel_hi:[1,0,1]
	v_pk_fma_f32 v[68:69], v[114:115], s[0:1], v[68:69] op_sel_hi:[1,0,1]
	v_pk_mov_b32 v[2:3], v[72:73], v[78:79] op_sel:[1,0]
	v_cvt_pk_fp8_f32 v48, v4, v5 op_sel:[0,0,1]
	v_mov_b32_e32 v4, v72
	v_mov_b32_e32 v5, v79
	v_pk_add_f32 v[2:3], v[2:3], v[4:5]
	global_store_dword v[158:159], v48, off offset:768
	v_pk_mov_b32 v[4:5], v[60:61], v[68:69] op_sel:[1,0]
	v_mov_b32_e32 v48, v60
	v_mov_b32_e32 v49, v69
	v_pk_add_f32 v[4:5], v[4:5], v[48:49]
	v_pk_fma_f32 v[54:55], v[116:117], s[0:1], v[54:55] op_sel_hi:[1,0,1]
	v_pk_fma_f32 v[46:47], v[46:47], s[0:1], v[56:57] op_sel_hi:[1,0,1]
	v_add_f32_e32 v2, v2, v3
	v_pk_add_f32 v[4:5], v[4:5], v[4:5] op_sel:[0,1] op_sel_hi:[1,0]
	v_add_f32_e32 v2, 0, v2
	v_add_f32_e32 v48, v52, v53
	v_add_f32_e32 v50, v54, v55
	v_mov_b32_e32 v3, v46
	v_mov_b32_e32 v5, v47
	v_mov_b32_e32 v49, v44
	v_mov_b32_e32 v51, v45
	v_pk_add_f32 v[2:3], v[2:3], v[4:5]
	v_pk_add_f32 v[4:5], v[48:49], v[50:51]
	s_lshl_b64 s[0:1], s[18:19], 12
	v_pk_add_f32 v[2:3], v[2:3], v[4:5]
	s_add_u32 s4, s34, s0
	v_add_f32_e32 v2, v2, v3
	ds_bpermute_b32 v3, v34, v2
	s_addc_u32 s5, s35, s1
	s_and_b64 s[0:1], s[8:9], exec
	s_cselect_b32 s1, s5, 0
	s_cselect_b32 s0, s4, 0
	s_waitcnt lgkmcnt(0)
	v_add_f32_e32 v2, v2, v3
	ds_bpermute_b32 v3, v164, v2
	s_cmp_lg_u64 s[0:1], 0
	s_cselect_b64 s[4:5], -1, 0
	s_cmp_eq_u64 s[0:1], 0
	s_waitcnt lgkmcnt(0)
	v_add_f32_e32 v2, v2, v3
	ds_bpermute_b32 v3, v165, v2
	s_waitcnt lgkmcnt(0)
	v_add_f32_e32 v2, v2, v3
	ds_bpermute_b32 v3, v166, v2
	s_waitcnt lgkmcnt(0)
	v_add_f32_e32 v2, v2, v3
	ds_bpermute_b32 v3, v167, v2
	s_waitcnt lgkmcnt(0)
	v_add_f32_e32 v2, v2, v3
	ds_bpermute_b32 v3, v168, v2
	s_waitcnt lgkmcnt(0)
	v_add_f32_e32 v56, v2, v3
	v_fmamk_f32 v73, v56, 0xba800000, v73
	v_fmac_f32_e32 v72, 0xba800000, v56
	v_fmamk_f32 v79, v56, 0xba800000, v79
	v_fmac_f32_e32 v78, 0xba800000, v56
	v_pk_mul_f32 v[2:3], v[78:79], v[78:79]
	v_pk_mul_f32 v[4:5], v[72:73], v[72:73]
	v_fmamk_f32 v69, v56, 0xba800000, v69
	v_pk_mov_b32 v[48:49], v[4:5], v[2:3] op_sel:[1,0]
	v_mov_b32_e32 v5, v3
	v_pk_add_f32 v[2:3], v[48:49], v[4:5]
	v_fmac_f32_e32 v68, 0xba800000, v56
	v_fmamk_f32 v61, v56, 0xba800000, v61
	v_fmac_f32_e32 v60, 0xba800000, v56
	v_pk_add_f32 v[2:3], v[2:3], v[2:3] op_sel_hi:[0,1]
	v_pk_mul_f32 v[4:5], v[68:69], v[68:69]
	v_pk_mul_f32 v[48:49], v[60:61], v[60:61]
	v_fmac_f32_e32 v52, 0xba800000, v56
	v_pk_mov_b32 v[50:51], v[48:49], v[4:5] op_sel:[1,0]
	v_mov_b32_e32 v49, v5
	v_fmac_f32_e32 v54, 0xba800000, v56
	v_fmamk_f32 v53, v56, 0xba800000, v53
	v_mul_f32_e32 v2, v52, v52
	v_pk_add_f32 v[4:5], v[50:51], v[48:49]
	v_fmamk_f32 v55, v56, 0xba800000, v55
	v_pk_fma_f32 v[48:49], v[52:53], v[52:53], v[2:3] op_sel_hi:[1,1,0]
	v_mul_f32_e32 v2, v54, v54
	v_pk_add_f32 v[4:5], v[4:5], v[4:5] op_sel_hi:[0,1]
	v_pk_fma_f32 v[50:51], v[54:55], v[54:55], v[2:3] op_sel_hi:[1,1,0]
	v_fmamk_f32 v45, v56, 0xba800000, v45
	v_fmac_f32_e32 v44, 0xba800000, v56
	v_fmamk_f32 v47, v56, 0xba800000, v47
	v_fmac_f32_e32 v46, 0xba800000, v56
	v_mul_f32_e32 v48, v46, v46
	v_mul_f32_e32 v50, v47, v47
	v_mul_f32_e32 v2, v44, v44
	v_mul_f32_e32 v4, v45, v45
	v_pk_add_f32 v[48:49], v[48:49], v[50:51]
	v_pk_add_f32 v[2:3], v[2:3], v[4:5]
	s_nop 0
	v_pk_add_f32 v[2:3], v[48:49], v[2:3]
	v_lshl_add_u64 v[48:49], v[6:7], 2, s[0:1]
	v_add_f32_e32 v2, v2, v3
	ds_bpermute_b32 v3, v34, v2
	s_waitcnt lgkmcnt(0)
	v_add_f32_e32 v2, v2, v3
	ds_bpermute_b32 v3, v164, v2
	s_waitcnt lgkmcnt(0)
	v_add_f32_e32 v2, v2, v3
	ds_bpermute_b32 v3, v165, v2
	s_waitcnt lgkmcnt(0)
	v_add_f32_e32 v2, v2, v3
	ds_bpermute_b32 v3, v166, v2
	s_waitcnt lgkmcnt(0)
	v_add_f32_e32 v2, v2, v3
	ds_bpermute_b32 v3, v167, v2
	s_waitcnt lgkmcnt(0)
	v_add_f32_e32 v2, v2, v3
	ds_bpermute_b32 v3, v168, v2
	s_waitcnt lgkmcnt(0)
	v_add_f32_e32 v2, v2, v3
	v_fmamk_f32 v2, v2, 0x3a800000, v230
	v_cmp_gt_f32_e32 vcc, s97, v2
	v_mul_f32_e32 v3, 0x4b800000, v2
	s_nop 0
	v_cndmask_b32_e32 v2, v2, v3, vcc
	v_rsq_f32_e32 v2, v2
	s_nop 0
	v_mul_f32_e32 v3, 0x45800000, v2
	v_cndmask_b32_e32 v50, v2, v3, vcc
	v_pk_mul_f32 v[56:57], v[72:73], v[50:51] op_sel_hi:[1,0]
	v_pk_mul_f32 v[70:71], v[78:79], v[50:51] op_sel_hi:[1,0]
	v_pk_fma_f32 v[2:3], v[176:177], v[56:57], v[192:193]
	v_pk_fma_f32 v[4:5], v[178:179], v[70:71], v[194:195]
	s_cbranch_scc1 .LBB0_2023
	global_store_dwordx4 v[48:49], v[2:5], off
; __device__ __forceinline__ float h2f_(unsigned short b) { return (float)__builtin_bit_cast(_Float16, b); }
; __device__ __forceinline__ unsigned cvt4_fp8(float a, float b, float c, float d) { int w = 0; w = __builtin_amdgcn_cvt_pk_fp8_f32(a, b, w, false); w = __builtin_amdgcn_cvt_pk_fp8_f32(c, d, w, true); return (unsigned)w; }
; __device__ __forceinline__ void ln_row_write(f32x4 (&v)[4], const float* g, const float* bta, float* of, bf16_t* ob, int lane, unsigned char* o8 = nullptr) {
;     ...
; #pragma unroll
;     for (int j = 0; j < 4; ++j) { const f32x4 gg = *(const f32x4*)(g + 4 * lane + 256 * j), bb = *(const f32x4*)(bta + 4 * lane + 256 * j); v[j] = v[j] * rstd * gg + bb;
;         if (of) *(f32x4*)(of + 4 * lane + 256 * j) = v[j]; u32x2 w; w.x = cvt_pk_f16(v[j][0], v[j][1]); w.y = cvt_pk_f16(v[j][2], v[j][3]); *(u32x2*)(ob + 4 * lane + 256 * j) = w;
;         if (o8) *(unsigned*)(o8 + 4 * lane + 256 * j) = cvt4_fp8(v[j][0], v[j][1], v[j][2], v[j][3]); }
; template <bool MOE>
; __device__ __forceinline__ void ln2_phase(const Frame& F, int layer) {
;     ...
;             for (int s_ = 0; s_ < 2; ++s_) { const float w0 = w0a[i + s_], w1 = w1a[i + s_];
; #pragma unroll
;                 for (int j = 0; j < 4; ++j) { const u32x2 x = nxr[s_][j], a = na[s_][j], c = nc[s_][j], pp = np_[s_][j];
;                     f32x4 f;
;                     f[0] = w0 * __uint_as_float(a.x << 16) + w1 * __uint_as_float(c.x << 16) + __uint_as_float(pp.x << 16);
;                     f[1] = w0 * __uint_as_float(a.x & 0xffff0000u) + w1 * __uint_as_float(c.x & 0xffff0000u) + __uint_as_float(pp.x & 0xffff0000u);
;                     f[2] = w0 * __uint_as_float(a.y << 16) + w1 * __uint_as_float(c.y << 16) + __uint_as_float(pp.y << 16);
;                     f[3] = w0 * __uint_as_float(a.y & 0xffff0000u) + w1 * __uint_as_float(c.y & 0xffff0000u) + __uint_as_float(pp.y & 0xffff0000u);
;                     v[s_][j] = (f32x4){h2f_((unsigned short)(x.x & 0xffffu)), h2f_((unsigned short)(x.x >> 16)), h2f_((unsigned short)(x.y & 0xffffu)), h2f_((unsigned short)(x.y >> 16))} * ALPHA + f; } }
.LBB0_2023:
	s_lshl_b64 s[0:1], s[18:19], 10
	v_lshl_add_u64 v[70:71], s[0:1], 1, v[28:29]
	v_cvt_pk_f16_f32 v72, v2, v3
	v_cvt_pk_f16_f32 v73, v4, v5
	global_store_dwordx2 v[70:71], v[72:73], off
	v_mov_b32_e32 v72, v35
	v_cvt_pk_fp8_f32 v72, v2, v3
	s_add_u32 s18, s20, s0
	s_addc_u32 s19, s21, s1
	v_lshl_add_u64 v[56:57], s[18:19], 0, v[6:7]
	v_cvt_pk_fp8_f32 v72, v4, v5 op_sel:[0,0,1]
	v_mov_b32_e32 v51, v50
	v_mov_b32_e32 v73, v50
	v_pk_mul_f32 v[60:61], v[60:61], v[50:51]
	global_store_dword v[56:57], v72, off
	v_mov_b32_e32 v72, v50
	v_pk_mul_f32 v[68:69], v[68:69], v[72:73]
	s_andn2_b64 vcc, exec, s[4:5]
	v_pk_fma_f32 v[2:3], v[60:61], v[180:181], v[206:207]
	v_cndmask_b32_e64 v60, 0, 1, s[4:5]
	v_pk_fma_f32 v[4:5], v[68:69], v[182:183], v[208:209]
	v_cmp_ne_u32_e64 s[0:1], 1, v60
	s_cbranch_vccnz .LBB0_2025
	global_store_dwordx4 v[48:49], v[2:5], off offset:1024
.LBB0_2025:
	v_mov_b32_e32 v60, v35
	v_cvt_pk_fp8_f32 v60, v2, v3
	v_cvt_pk_f16_f32 v2, v2, v3
	v_cvt_pk_f16_f32 v3, v4, v5
	v_pk_mul_f32 v[54:55], v[54:55], v[72:73]
	v_cvt_pk_fp8_f32 v60, v4, v5 op_sel:[0,0,1]
	v_pk_mul_f32 v[52:53], v[52:53], v[50:51]
	s_and_b64 vcc, exec, s[0:1]
	global_store_dwordx2 v[70:71], v[2:3], off offset:512
	global_store_dword v[56:57], v60, off offset:256
	s_nop 0
	v_pk_fma_f32 v[4:5], v[54:55], v[186:187], v[212:213]
	v_pk_fma_f32 v[2:3], v[52:53], v[184:185], v[210:211]
	s_cbranch_vccnz .LBB0_2027
	global_store_dwordx4 v[48:49], v[2:5], off offset:2048
.LBB0_2027:
	v_mov_b32_e32 v52, v35
	v_cvt_pk_fp8_f32 v52, v2, v3
	v_cvt_pk_f16_f32 v2, v2, v3
	v_cvt_pk_f16_f32 v3, v4, v5
	v_mov_b32_e32 v60, v50
	v_cvt_pk_fp8_f32 v52, v4, v5 op_sel:[0,0,1]
	v_mov_b32_e32 v61, v50
	v_pk_mul_f32 v[46:47], v[46:47], v[50:51]
	global_store_dwordx2 v[70:71], v[2:3], off offset:1024
	global_store_dword v[56:57], v52, off offset:512
	s_nop 0
	v_pk_mul_f32 v[44:45], v[44:45], v[60:61]
	s_and_b64 vcc, exec, s[0:1]
	s_waitcnt vmcnt(0)
	v_pk_fma_f32 v[4:5], v[44:45], v[190:191], v[216:217]
	v_pk_fma_f32 v[2:3], v[46:47], v[188:189], v[214:215]
	s_cbranch_vccnz .LBB0_2029
	global_store_dwordx4 v[48:49], v[2:5], off offset:3072
.LBB0_2029:
	v_cvt_pk_f16_f32 v44, v2, v3
	v_cvt_pk_f16_f32 v45, v4, v5
	global_store_dwordx2 v[70:71], v[44:45], off offset:1536
	v_mov_b32_e32 v44, v35
	v_cvt_pk_fp8_f32 v44, v2, v3
	v_lshlrev_b32_e32 v2, 16, v150
	v_and_b32_e32 v3, 0xffff0000, v148
	v_and_b32_e32 v45, 0xffff0000, v151
	v_cvt_pk_fp8_f32 v44, v4, v5 op_sel:[0,0,1]
	v_lshlrev_b32_e32 v4, 16, v148
	v_and_b32_e32 v5, 0xffff0000, v150
	v_pk_mul_f32 v[4:5], v[38:39], v[4:5]
	global_store_dword v[56:57], v44, off offset:768
	v_pk_fma_f32 v[2:3], v[38:39], v[2:3], v[4:5] op_sel:[1,0,0] op_sel_hi:[0,1,1]
	v_lshlrev_b32_e32 v4, 16, v146
	v_and_b32_e32 v5, 0xffff0000, v146
	v_lshlrev_b32_e32 v44, 16, v149
	v_pk_add_f32 v[2:3], v[2:3], v[4:5]
	v_lshlrev_b32_e32 v4, 16, v151
	v_and_b32_e32 v5, 0xffff0000, v149
	v_pk_mul_f32 v[44:45], v[38:39], v[44:45]
	v_cvt_f32_f16_sdwa v47, v145 dst_sel:DWORD dst_unused:UNUSED_PAD src0_sel:WORD_1
	v_pk_fma_f32 v[4:5], v[38:39], v[4:5], v[44:45] op_sel:[1,0,0] op_sel_hi:[0,1,1]
	v_lshlrev_b32_e32 v44, 16, v147
	v_and_b32_e32 v45, 0xffff0000, v147
	v_cvt_f32_f16_e32 v46, v145
	v_pk_add_f32 v[4:5], v[4:5], v[44:45]
	v_cvt_f32_f16_sdwa v45, v144 dst_sel:DWORD dst_unused:UNUSED_PAD src0_sel:WORD_1
	v_cvt_f32_f16_e32 v44, v144
	s_mov_b32 s0, 0x3fd744fd
	v_pk_fma_f32 v[4:5], v[46:47], s[0:1], v[4:5] op_sel_hi:[1,0,1]
	v_lshlrev_b32_e32 v46, 16, v140
	v_and_b32_e32 v47, 0xffff0000, v142
	v_pk_fma_f32 v[2:3], v[44:45], s[0:1], v[2:3] op_sel_hi:[1,0,1]
	v_lshlrev_b32_e32 v44, 16, v142
	v_and_b32_e32 v45, 0xffff0000, v140
	v_pk_mul_f32 v[46:47], v[38:39], v[46:47]
	v_lshlrev_b32_e32 v48, 16, v141
	v_pk_fma_f32 v[44:45], v[38:39], v[44:45], v[46:47] op_sel:[1,0,0] op_sel_hi:[0,1,1]
	v_lshlrev_b32_e32 v46, 16, v138
	v_and_b32_e32 v47, 0xffff0000, v138
	v_and_b32_e32 v49, 0xffff0000, v143
	v_pk_add_f32 v[44:45], v[44:45], v[46:47]
	v_lshlrev_b32_e32 v46, 16, v143
	v_and_b32_e32 v47, 0xffff0000, v141
	v_pk_mul_f32 v[48:49], v[38:39], v[48:49]
	v_cvt_f32_f16_sdwa v51, v137 dst_sel:DWORD dst_unused:UNUSED_PAD src0_sel:WORD_1
	v_pk_fma_f32 v[46:47], v[38:39], v[46:47], v[48:49] op_sel:[1,0,0] op_sel_hi:[0,1,1]
	v_lshlrev_b32_e32 v48, 16, v139
	v_and_b32_e32 v49, 0xffff0000, v139
	v_cvt_f32_f16_e32 v50, v137
	v_pk_add_f32 v[46:47], v[46:47], v[48:49]
	v_cvt_f32_f16_sdwa v49, v136 dst_sel:DWORD dst_unused:UNUSED_PAD src0_sel:WORD_1
	v_cvt_f32_f16_e32 v48, v136
	v_pk_fma_f32 v[148:149], v[50:51], s[0:1], v[46:47] op_sel_hi:[1,0,1]
	v_lshlrev_b32_e32 v46, 16, v132
	v_and_b32_e32 v47, 0xffff0000, v134
	v_pk_fma_f32 v[146:147], v[48:49], s[0:1], v[44:45] op_sel_hi:[1,0,1]
	v_lshlrev_b32_e32 v44, 16, v134
	v_and_b32_e32 v45, 0xffff0000, v132
	v_pk_mul_f32 v[46:47], v[38:39], v[46:47]
	v_lshlrev_b32_e32 v48, 16, v133
	v_pk_fma_f32 v[44:45], v[38:39], v[44:45], v[46:47] op_sel:[1,0,0] op_sel_hi:[0,1,1]
	v_lshlrev_b32_e32 v46, 16, v126
	v_and_b32_e32 v47, 0xffff0000, v126
	v_and_b32_e32 v49, 0xffff0000, v135
	v_pk_add_f32 v[44:45], v[44:45], v[46:47]
	v_lshlrev_b32_e32 v46, 16, v135
	v_and_b32_e32 v47, 0xffff0000, v133
	v_pk_mul_f32 v[48:49], v[38:39], v[48:49]
	v_cvt_f32_f16_sdwa v51, v121 dst_sel:DWORD dst_unused:UNUSED_PAD src0_sel:WORD_1
	v_pk_fma_f32 v[46:47], v[38:39], v[46:47], v[48:49] op_sel:[1,0,0] op_sel_hi:[0,1,1]
	v_lshlrev_b32_e32 v48, 16, v127
	v_and_b32_e32 v49, 0xffff0000, v127
	v_cvt_f32_f16_e32 v50, v121
	v_pk_add_f32 v[46:47], v[46:47], v[48:49]
	v_cvt_f32_f16_sdwa v49, v120 dst_sel:DWORD dst_unused:UNUSED_PAD src0_sel:WORD_1
	v_cvt_f32_f16_e32 v48, v120
; __device__ __forceinline__ float h2f_(unsigned short b) { return (float)__builtin_bit_cast(_Float16, b); }
; __device__ __forceinline__ void ln_row_write(f32x4 (&v)[4], const float* g, const float* bta, float* of, bf16_t* ob, int lane, unsigned char* o8 = nullptr) {
;     float s = 0.f;
; #pragma unroll
;     for (int j = 0; j < 4; ++j) s += (v[j][0] + v[j][1]) + (v[j][2] + v[j][3]);
;     const float mean = wave_sum(s) * (1.0f / 1024.0f); float s2 = 0.f;
; #pragma unroll
;     for (int j = 0; j < 4; ++j) { v[j] = v[j] - mean; s2 += (v[j][0] * v[j][0] + v[j][1] * v[j][1]) + (v[j][2] * v[j][2] + v[j][3] * v[j][3]); }
;     const float rstd = rsqrtf(wave_sum(s2) * (1.0f / 1024.0f) + EPS);
; template <bool MOE>
; __device__ __forceinline__ void ln2_phase(const Frame& F, int layer) {
;     ...
;             for (int s_ = 0; s_ < 2; ++s_) { const float w0 = w0a[i + s_], w1 = w1a[i + s_];
; #pragma unroll
;                 for (int j = 0; j < 4; ++j) { const u32x2 x = nxr[s_][j], a = na[s_][j], c = nc[s_][j], pp = np_[s_][j];
;                     f32x4 f;
;                     f[0] = w0 * __uint_as_float(a.x << 16) + w1 * __uint_as_float(c.x << 16) + __uint_as_float(pp.x << 16);
;                     f[1] = w0 * __uint_as_float(a.x & 0xffff0000u) + w1 * __uint_as_float(c.x & 0xffff0000u) + __uint_as_float(pp.x & 0xffff0000u);
;                     f[2] = w0 * __uint_as_float(a.y << 16) + w1 * __uint_as_float(c.y << 16) + __uint_as_float(pp.y << 16);
;                     f[3] = w0 * __uint_as_float(a.y & 0xffff0000u) + w1 * __uint_as_float(c.y & 0xffff0000u) + __uint_as_float(pp.y & 0xffff0000u);
;                     v[s_][j] = (f32x4){h2f_((unsigned short)(x.x & 0xffffu)), h2f_((unsigned short)(x.x >> 16)), h2f_((unsigned short)(x.y & 0xffffu)), h2f_((unsigned short)(x.y >> 16))} * ALPHA + f; } }
;             if (i + 2 < 8) { LN2_LOAD(0, F.gw + (i + 2) * F.NGW, s0a[i + 2], s1a[i + 2]); LN2_LOAD(1, F.gw + (i + 3) * F.NGW, s0a[i + 3], s1a[i + 3]); }
	v_pk_fma_f32 v[140:141], v[50:51], s[0:1], v[46:47] op_sel_hi:[1,0,1]
	v_lshlrev_b32_e32 v46, 16, v118
	v_and_b32_e32 v47, 0xffff0000, v122
	v_pk_fma_f32 v[138:139], v[48:49], s[0:1], v[44:45] op_sel_hi:[1,0,1]
	v_lshlrev_b32_e32 v44, 16, v122
	v_and_b32_e32 v45, 0xffff0000, v118
	v_pk_mul_f32 v[46:47], v[38:39], v[46:47]
	v_lshlrev_b32_e32 v48, 16, v119
	v_pk_fma_f32 v[44:45], v[38:39], v[44:45], v[46:47] op_sel:[1,0,0] op_sel_hi:[0,1,1]
	v_lshlrev_b32_e32 v46, 16, v124
	v_and_b32_e32 v47, 0xffff0000, v124
	v_and_b32_e32 v49, 0xffff0000, v123
	v_pk_add_f32 v[44:45], v[44:45], v[46:47]
	v_lshlrev_b32_e32 v46, 16, v123
	v_and_b32_e32 v47, 0xffff0000, v119
	v_pk_mul_f32 v[48:49], v[38:39], v[48:49]
	s_add_i32 s12, s12, s3
	v_pk_fma_f32 v[38:39], v[38:39], v[46:47], v[48:49] op_sel:[1,0,0] op_sel_hi:[0,1,1]
	v_lshlrev_b32_e32 v46, 16, v125
	v_and_b32_e32 v47, 0xffff0000, v125
	v_pk_add_f32 v[38:39], v[38:39], v[46:47]
	v_cvt_f32_f16_sdwa v47, v112 dst_sel:DWORD dst_unused:UNUSED_PAD src0_sel:WORD_1
	v_cvt_f32_f16_e32 v46, v112
	v_cvt_f32_f16_sdwa v49, v113 dst_sel:DWORD dst_unused:UNUSED_PAD src0_sel:WORD_1
	v_cvt_f32_f16_e32 v48, v113
	s_ashr_i32 s13, s12, 31
	v_pk_fma_f32 v[144:145], v[46:47], s[0:1], v[44:45] op_sel_hi:[1,0,1]
	v_ashrrev_i32_e32 v45, 31, v36
	v_mov_b32_e32 v44, v36
	v_pk_fma_f32 v[142:143], v[48:49], s[0:1], v[38:39] op_sel_hi:[1,0,1]
	s_lshl_b64 s[0:1], s[12:13], 11
	v_lshlrev_b64 v[44:45], 11, v[44:45]
	v_ashrrev_i32_e32 v47, 31, v37
	v_mov_b32_e32 v46, v37
	v_lshl_add_u64 v[38:39], v[28:29], 0, s[0:1]
	v_lshl_add_u64 v[44:45], v[24:25], 0, v[44:45]
	v_lshlrev_b64 v[36:37], 11, v[46:47]
	v_lshl_add_u64 v[46:47], v[26:27], 0, s[0:1]
	s_ashr_i32 s11, s10, 31
	v_lshl_add_u64 v[36:37], v[24:25], 0, v[36:37]
	global_load_dwordx2 v[130:131], v[38:39], off
	global_load_dwordx2 v[134:135], v[44:45], off
	global_load_dwordx2 v[136:137], v[36:37], off
	global_load_dwordx2 v[132:133], v[46:47], off
	global_load_dwordx2 v[122:123], v[38:39], off offset:512
	global_load_dwordx2 v[126:127], v[44:45], off offset:512
	global_load_dwordx2 v[128:129], v[36:37], off offset:512
	global_load_dwordx2 v[124:125], v[46:47], off offset:512
	global_load_dwordx2 v[110:111], v[38:39], off offset:1024
	global_load_dwordx2 v[118:119], v[44:45], off offset:1024
	global_load_dwordx2 v[120:121], v[36:37], off offset:1024
	global_load_dwordx2 v[116:117], v[46:47], off offset:1024
	global_load_dwordx2 v[106:107], v[38:39], off offset:1536
	global_load_dwordx2 v[108:109], v[44:45], off offset:1536
	global_load_dwordx2 v[112:113], v[36:37], off offset:1536
	global_load_dwordx2 v[114:115], v[46:47], off offset:1536
	v_ashrrev_i32_e32 v45, 31, v32
	v_mov_b32_e32 v44, v32
	v_ashrrev_i32_e32 v47, 31, v33
	v_mov_b32_e32 v46, v33
	s_lshl_b64 s[0:1], s[10:11], 11
	v_lshlrev_b64 v[44:45], 11, v[44:45]
	v_lshlrev_b64 v[32:33], 11, v[46:47]
	v_lshl_add_u64 v[36:37], v[28:29], 0, s[0:1]
	v_lshl_add_u64 v[44:45], v[24:25], 0, v[44:45]
	v_lshl_add_u64 v[48:49], v[24:25], 0, v[32:33]
	v_lshl_add_u64 v[150:151], v[26:27], 0, s[0:1]
	global_load_dwordx2 v[78:79], v[36:37], off
	global_load_dwordx2 v[86:87], v[44:45], off
	global_load_dwordx2 v[88:89], v[48:49], off
	global_load_dwordx2 v[84:85], v[150:151], off
	global_load_dwordx2 v[60:61], v[36:37], off offset:512
	global_load_dwordx2 v[70:71], v[44:45], off offset:512
	global_load_dwordx2 v[72:73], v[48:49], off offset:512
	global_load_dwordx2 v[68:69], v[150:151], off offset:512
	global_load_dwordx2 v[50:51], v[36:37], off offset:1024
	global_load_dwordx2 v[54:55], v[44:45], off offset:1024
	global_load_dwordx2 v[56:57], v[48:49], off offset:1024
	global_load_dwordx2 v[52:53], v[150:151], off offset:1024
	global_load_dwordx2 v[32:33], v[36:37], off offset:1536
	global_load_dwordx2 v[46:47], v[44:45], off offset:1536
	s_nop 0
	global_load_dwordx2 v[48:49], v[48:49], off offset:1536
	s_nop 0
	global_load_dwordx2 v[44:45], v[150:151], off offset:1536
	v_pk_mov_b32 v[150:151], v[2:3], v[4:5] op_sel:[1,0]
	v_mov_b32_e32 v152, v2
	v_mov_b32_e32 v153, v5
	v_pk_add_f32 v[150:151], v[150:151], v[152:153]
	v_pk_mov_b32 v[152:153], v[146:147], v[148:149] op_sel:[1,0]
	v_mov_b32_e32 v154, v146
	v_mov_b32_e32 v155, v149
	v_pk_add_f32 v[152:153], v[152:153], v[154:155]
	v_add_f32_e32 v150, v150, v151
	v_pk_add_f32 v[152:153], v[152:153], v[152:153] op_sel:[0,1] op_sel_hi:[1,0]
	v_add_f32_e32 v150, 0, v150
	v_add_f32_e32 v154, v138, v139
	v_add_f32_e32 v156, v140, v141
	v_mov_b32_e32 v151, v144
	v_mov_b32_e32 v153, v145
	v_mov_b32_e32 v155, v142
	v_mov_b32_e32 v157, v143
	v_pk_add_f32 v[150:151], v[150:151], v[152:153]
	v_pk_add_f32 v[152:153], v[154:155], v[156:157]
	s_lshl_b64 s[0:1], s[16:17], 12
	v_pk_add_f32 v[150:151], v[150:151], v[152:153]
	s_add_u32 s3, s34, s0
	v_add_f32_e32 v150, v150, v151
	ds_bpermute_b32 v151, v34, v150
	s_addc_u32 s4, s35, s1
	s_and_b64 s[0:1], s[8:9], exec
	s_cselect_b32 s1, s4, 0
	s_cselect_b32 s0, s3, 0
	s_waitcnt lgkmcnt(0)
	v_add_f32_e32 v150, v150, v151
	ds_bpermute_b32 v151, v164, v150
	s_cmp_lg_u64 s[0:1], 0
	s_cselect_b64 s[4:5], -1, 0
	s_cmp_eq_u64 s[0:1], 0
	s_waitcnt lgkmcnt(0)
	v_add_f32_e32 v150, v150, v151
	ds_bpermute_b32 v151, v165, v150
	s_waitcnt lgkmcnt(0)
	v_add_f32_e32 v150, v150, v151
	ds_bpermute_b32 v151, v166, v150
	s_waitcnt lgkmcnt(0)
	v_add_f32_e32 v150, v150, v151
	ds_bpermute_b32 v151, v167, v150
	s_waitcnt lgkmcnt(0)
	v_add_f32_e32 v150, v150, v151
	ds_bpermute_b32 v151, v168, v150
	s_waitcnt lgkmcnt(0)
; __device__ __forceinline__ unsigned cvt4_fp8(float a, float b, float c, float d) { int w = 0; w = __builtin_amdgcn_cvt_pk_fp8_f32(a, b, w, false); w = __builtin_amdgcn_cvt_pk_fp8_f32(c, d, w, true); return (unsigned)w; }
; __device__ __forceinline__ void ln_row_write(f32x4 (&v)[4], const float* g, const float* bta, float* of, bf16_t* ob, int lane, unsigned char* o8 = nullptr) {
;     float s = 0.f;
; #pragma unroll
;     for (int j = 0; j < 4; ++j) s += (v[j][0] + v[j][1]) + (v[j][2] + v[j][3]);
;     const float mean = wave_sum(s) * (1.0f / 1024.0f); float s2 = 0.f;
; #pragma unroll
;     for (int j = 0; j < 4; ++j) { v[j] = v[j] - mean; s2 += (v[j][0] * v[j][0] + v[j][1] * v[j][1]) + (v[j][2] * v[j][2] + v[j][3] * v[j][3]); }
;     const float rstd = rsqrtf(wave_sum(s2) * (1.0f / 1024.0f) + EPS);
; #pragma unroll
;     for (int j = 0; j < 4; ++j) { const f32x4 gg = *(const f32x4*)(g + 4 * lane + 256 * j), bb = *(const f32x4*)(bta + 4 * lane + 256 * j); v[j] = v[j] * rstd * gg + bb;
;         if (of) *(f32x4*)(of + 4 * lane + 256 * j) = v[j]; u32x2 w; w.x = cvt_pk_f16(v[j][0], v[j][1]); w.y = cvt_pk_f16(v[j][2], v[j][3]); *(u32x2*)(ob + 4 * lane + 256 * j) = w;
;         if (o8) *(unsigned*)(o8 + 4 * lane + 256 * j) = cvt4_fp8(v[j][0], v[j][1], v[j][2], v[j][3]); }
	v_add_f32_e32 v158, v150, v151
	v_fmamk_f32 v3, v158, 0xba800000, v3
	v_fmac_f32_e32 v2, 0xba800000, v158
	v_fmamk_f32 v5, v158, 0xba800000, v5
	v_fmac_f32_e32 v4, 0xba800000, v158
	v_pk_mul_f32 v[150:151], v[4:5], v[4:5]
	v_pk_mul_f32 v[152:153], v[2:3], v[2:3]
	v_fmamk_f32 v149, v158, 0xba800000, v149
	v_pk_mov_b32 v[154:155], v[152:153], v[150:151] op_sel:[1,0]
	v_mov_b32_e32 v153, v151
	v_pk_add_f32 v[150:151], v[154:155], v[152:153]
	v_fmac_f32_e32 v148, 0xba800000, v158
	v_fmamk_f32 v147, v158, 0xba800000, v147
	v_fmac_f32_e32 v146, 0xba800000, v158
	v_pk_add_f32 v[150:151], v[150:151], v[150:151] op_sel_hi:[0,1]
	v_pk_mul_f32 v[152:153], v[148:149], v[148:149]
	v_pk_mul_f32 v[154:155], v[146:147], v[146:147]
	v_fmac_f32_e32 v138, 0xba800000, v158
	v_pk_mov_b32 v[156:157], v[154:155], v[152:153] op_sel:[1,0]
	v_mov_b32_e32 v155, v153
	v_fmac_f32_e32 v140, 0xba800000, v158
	v_fmamk_f32 v139, v158, 0xba800000, v139
	v_mul_f32_e32 v150, v138, v138
	v_pk_add_f32 v[152:153], v[156:157], v[154:155]
	v_fmamk_f32 v141, v158, 0xba800000, v141
	v_pk_fma_f32 v[154:155], v[138:139], v[138:139], v[150:151] op_sel_hi:[1,1,0]
	v_mul_f32_e32 v150, v140, v140
	v_pk_add_f32 v[152:153], v[152:153], v[152:153] op_sel_hi:[0,1]
	v_pk_fma_f32 v[156:157], v[140:141], v[140:141], v[150:151] op_sel_hi:[1,1,0]
	v_fmamk_f32 v143, v158, 0xba800000, v143
	v_fmac_f32_e32 v142, 0xba800000, v158
	v_fmamk_f32 v145, v158, 0xba800000, v145
	v_fmac_f32_e32 v144, 0xba800000, v158
	v_mul_f32_e32 v154, v144, v144
	v_mul_f32_e32 v156, v145, v145
	v_mul_f32_e32 v150, v142, v142
	v_mul_f32_e32 v152, v143, v143
	v_pk_add_f32 v[154:155], v[154:155], v[156:157]
	v_pk_add_f32 v[150:151], v[150:151], v[152:153]
	s_nop 0
	v_pk_add_f32 v[150:151], v[154:155], v[150:151]
	v_add_f32_e32 v150, v150, v151
	ds_bpermute_b32 v151, v34, v150
	s_waitcnt lgkmcnt(0)
	v_add_f32_e32 v150, v150, v151
	ds_bpermute_b32 v151, v164, v150
	s_waitcnt lgkmcnt(0)
	v_add_f32_e32 v150, v150, v151
	ds_bpermute_b32 v151, v165, v150
	s_waitcnt lgkmcnt(0)
	v_add_f32_e32 v150, v150, v151
	ds_bpermute_b32 v151, v166, v150
	s_waitcnt lgkmcnt(0)
	v_add_f32_e32 v150, v150, v151
	ds_bpermute_b32 v151, v167, v150
	s_waitcnt lgkmcnt(0)
	v_add_f32_e32 v150, v150, v151
	ds_bpermute_b32 v151, v168, v150
	s_waitcnt lgkmcnt(0)
	v_add_f32_e32 v150, v150, v151
	v_fmamk_f32 v150, v150, 0x3a800000, v230
	v_cmp_gt_f32_e32 vcc, s97, v150
	v_mul_f32_e32 v151, 0x4b800000, v150
	s_nop 0
	v_cndmask_b32_e32 v150, v150, v151, vcc
	v_rsq_f32_e32 v150, v150
	s_nop 0
	v_mul_f32_e32 v151, 0x45800000, v150
	v_cndmask_b32_e32 v152, v150, v151, vcc
	v_pk_mul_f32 v[2:3], v[2:3], v[152:153] op_sel_hi:[1,0]
	v_pk_mul_f32 v[4:5], v[4:5], v[152:153] op_sel_hi:[1,0]
	v_lshl_add_u64 v[150:151], v[6:7], 2, s[0:1]
	v_pk_fma_f32 v[4:5], v[178:179], v[4:5], v[194:195]
	v_pk_fma_f32 v[2:3], v[176:177], v[2:3], v[192:193]
	s_cbranch_scc1 .LBB0_2031
	global_store_dwordx4 v[150:151], v[2:5], off
.LBB0_2031:
	v_cvt_pk_f16_f32 v156, v2, v3
	v_cvt_pk_f16_f32 v157, v4, v5
	global_store_dwordx2 v[42:43], v[156:157], off
	v_mov_b32_e32 v156, v35
	v_cvt_pk_fp8_f32 v156, v2, v3
	s_lshl_b64 s[0:1], s[16:17], 10
	s_add_u32 s0, s20, s0
	s_addc_u32 s1, s21, s1
	v_cvt_pk_fp8_f32 v156, v4, v5 op_sel:[0,0,1]
	v_lshl_add_u64 v[154:155], s[0:1], 0, v[6:7]
	v_mov_b32_e32 v153, v152
	v_mov_b32_e32 v157, v152
	global_store_dword v[154:155], v156, off
	v_mov_b32_e32 v156, v152
	v_pk_mul_f32 v[146:147], v[146:147], v[152:153]
	v_pk_mul_f32 v[148:149], v[148:149], v[156:157]
	s_andn2_b64 vcc, exec, s[4:5]
	v_pk_fma_f32 v[2:3], v[146:147], v[180:181], v[206:207]
	v_cndmask_b32_e64 v146, 0, 1, s[4:5]
	v_pk_fma_f32 v[4:5], v[148:149], v[182:183], v[208:209]
	v_cmp_ne_u32_e64 s[0:1], 1, v146
	s_cbranch_vccnz .LBB0_2033
	global_store_dwordx4 v[150:151], v[2:5], off offset:1024
.LBB0_2033:
	v_mov_b32_e32 v146, v35
	v_cvt_pk_fp8_f32 v146, v2, v3
	v_cvt_pk_f16_f32 v2, v2, v3
	v_cvt_pk_f16_f32 v3, v4, v5
	v_pk_mul_f32 v[140:141], v[140:141], v[156:157]
	v_cvt_pk_fp8_f32 v146, v4, v5 op_sel:[0,0,1]
	v_pk_mul_f32 v[138:139], v[138:139], v[152:153]
	s_and_b64 vcc, exec, s[0:1]
	global_store_dwordx2 v[42:43], v[2:3], off offset:512
	global_store_dword v[154:155], v146, off offset:256
	s_nop 0
	v_pk_fma_f32 v[4:5], v[140:141], v[186:187], v[212:213]
	v_pk_fma_f32 v[2:3], v[138:139], v[184:185], v[210:211]
	s_cbranch_vccnz .LBB0_2035
	global_store_dwordx4 v[150:151], v[2:5], off offset:2048
.LBB0_2035:
	v_mov_b32_e32 v138, v35
	v_cvt_pk_fp8_f32 v138, v2, v3
	v_cvt_pk_f16_f32 v2, v2, v3
	v_cvt_pk_f16_f32 v3, v4, v5
	v_mov_b32_e32 v146, v152
	v_cvt_pk_fp8_f32 v138, v4, v5 op_sel:[0,0,1]
	v_mov_b32_e32 v147, v152
	v_pk_mul_f32 v[144:145], v[144:145], v[152:153]
	global_store_dwordx2 v[42:43], v[2:3], off offset:1024
	global_store_dword v[154:155], v138, off offset:512
	s_nop 0
	v_pk_mul_f32 v[142:143], v[142:143], v[146:147]
	s_and_b64 vcc, exec, s[0:1]
	v_pk_fma_f32 v[4:5], v[142:143], v[190:191], v[216:217]
	v_pk_fma_f32 v[2:3], v[144:145], v[188:189], v[214:215]
	s_cbranch_vccnz .LBB0_2037
	global_store_dwordx4 v[150:151], v[2:5], off offset:3072
; __device__ __forceinline__ float h2f_(unsigned short b) { return (float)__builtin_bit_cast(_Float16, b); }
; __device__ __forceinline__ void ln_row_write(f32x4 (&v)[4], const float* g, const float* bta, float* of, bf16_t* ob, int lane, unsigned char* o8 = nullptr) {
;     float s = 0.f;
; #pragma unroll
;     for (int j = 0; j < 4; ++j) s += (v[j][0] + v[j][1]) + (v[j][2] + v[j][3]);
;     const float mean = wave_sum(s) * (1.0f / 1024.0f); float s2 = 0.f;
; template <bool MOE>
; __device__ __forceinline__ void ln2_phase(const Frame& F, int layer) {
;     ...
;             for (int s_ = 0; s_ < 2; ++s_) { const float w0 = w0a[i + s_], w1 = w1a[i + s_];
; #pragma unroll
;                 for (int j = 0; j < 4; ++j) { const u32x2 x = nxr[s_][j], a = na[s_][j], c = nc[s_][j], pp = np_[s_][j];
;                     f32x4 f;
;                     f[0] = w0 * __uint_as_float(a.x << 16) + w1 * __uint_as_float(c.x << 16) + __uint_as_float(pp.x << 16);
;                     f[1] = w0 * __uint_as_float(a.x & 0xffff0000u) + w1 * __uint_as_float(c.x & 0xffff0000u) + __uint_as_float(pp.x & 0xffff0000u);
;                     f[2] = w0 * __uint_as_float(a.y << 16) + w1 * __uint_as_float(c.y << 16) + __uint_as_float(pp.y << 16);
;                     f[3] = w0 * __uint_as_float(a.y & 0xffff0000u) + w1 * __uint_as_float(c.y & 0xffff0000u) + __uint_as_float(pp.y & 0xffff0000u);
;                     v[s_][j] = (f32x4){h2f_((unsigned short)(x.x & 0xffffu)), h2f_((unsigned short)(x.x >> 16)), h2f_((unsigned short)(x.y & 0xffffu)), h2f_((unsigned short)(x.y >> 16))} * ALPHA + f; } }
.LBB0_2037:
	v_lshlrev_b32_e32 v140, 16, v102
	v_and_b32_e32 v141, 0xffff0000, v104
	v_lshlrev_b32_e32 v138, 16, v104
	v_and_b32_e32 v139, 0xffff0000, v102
	v_pk_mul_f32 v[140:141], v[30:31], v[140:141]
	v_lshlrev_b32_e32 v102, 16, v103
	v_pk_fma_f32 v[138:139], v[30:31], v[138:139], v[140:141] op_sel:[1,0,0] op_sel_hi:[0,1,1]
	v_lshlrev_b32_e32 v140, 16, v100
	v_and_b32_e32 v141, 0xffff0000, v100
	v_pk_add_f32 v[138:139], v[138:139], v[140:141]
	v_and_b32_e32 v141, 0xffff0000, v103
	v_and_b32_e32 v103, 0xffff0000, v105
	v_lshlrev_b32_e32 v140, 16, v105
	v_pk_mul_f32 v[102:103], v[30:31], v[102:103]
	v_lshlrev_b32_e32 v100, 16, v101
	v_pk_fma_f32 v[102:103], v[30:31], v[140:141], v[102:103] op_sel:[1,0,0] op_sel_hi:[0,1,1]
	v_and_b32_e32 v101, 0xffff0000, v101
	v_cvt_f32_f16_sdwa v105, v99 dst_sel:DWORD dst_unused:UNUSED_PAD src0_sel:WORD_1
	v_cvt_f32_f16_e32 v104, v99
	v_pk_add_f32 v[100:101], v[102:103], v[100:101]
	v_cvt_f32_f16_sdwa v103, v98 dst_sel:DWORD dst_unused:UNUSED_PAD src0_sel:WORD_1
	v_cvt_f32_f16_e32 v102, v98
	s_mov_b32 s0, 0x3fd744fd
	v_pk_fma_f32 v[100:101], v[104:105], s[0:1], v[100:101] op_sel_hi:[1,0,1]
	v_lshlrev_b32_e32 v104, 16, v94
	v_and_b32_e32 v105, 0xffff0000, v96
	v_pk_fma_f32 v[98:99], v[102:103], s[0:1], v[138:139] op_sel_hi:[1,0,1]
	v_lshlrev_b32_e32 v102, 16, v96
	v_and_b32_e32 v103, 0xffff0000, v94
	v_pk_mul_f32 v[104:105], v[30:31], v[104:105]
	v_lshlrev_b32_e32 v94, 16, v95
	v_pk_fma_f32 v[102:103], v[30:31], v[102:103], v[104:105] op_sel:[1,0,0] op_sel_hi:[0,1,1]
	v_lshlrev_b32_e32 v104, 16, v92
	v_and_b32_e32 v105, 0xffff0000, v92
	v_pk_add_f32 v[102:103], v[102:103], v[104:105]
	v_and_b32_e32 v105, 0xffff0000, v95
	v_and_b32_e32 v95, 0xffff0000, v97
	v_lshlrev_b32_e32 v104, 16, v97
	v_pk_mul_f32 v[94:95], v[30:31], v[94:95]
	v_lshlrev_b32_e32 v92, 16, v93
	v_pk_fma_f32 v[94:95], v[30:31], v[104:105], v[94:95] op_sel:[1,0,0] op_sel_hi:[0,1,1]
	v_and_b32_e32 v93, 0xffff0000, v93
	v_cvt_f32_f16_sdwa v97, v91 dst_sel:DWORD dst_unused:UNUSED_PAD src0_sel:WORD_1
	v_cvt_f32_f16_e32 v96, v91
	v_pk_add_f32 v[92:93], v[94:95], v[92:93]
	v_cvt_f32_f16_sdwa v95, v90 dst_sel:DWORD dst_unused:UNUSED_PAD src0_sel:WORD_1
	v_cvt_f32_f16_e32 v94, v90
	v_pk_fma_f32 v[92:93], v[96:97], s[0:1], v[92:93] op_sel_hi:[1,0,1]
	v_lshlrev_b32_e32 v96, 16, v80
	v_and_b32_e32 v97, 0xffff0000, v82
	v_pk_fma_f32 v[90:91], v[94:95], s[0:1], v[102:103] op_sel_hi:[1,0,1]
	v_lshlrev_b32_e32 v94, 16, v82
	v_and_b32_e32 v95, 0xffff0000, v80
	v_pk_mul_f32 v[96:97], v[30:31], v[96:97]
	v_lshlrev_b32_e32 v80, 16, v81
	v_pk_fma_f32 v[94:95], v[30:31], v[94:95], v[96:97] op_sel:[1,0,0] op_sel_hi:[0,1,1]
	v_lshlrev_b32_e32 v96, 16, v76
	v_and_b32_e32 v97, 0xffff0000, v76
	v_pk_add_f32 v[94:95], v[94:95], v[96:97]
	v_and_b32_e32 v97, 0xffff0000, v81
	v_and_b32_e32 v81, 0xffff0000, v83
	v_lshlrev_b32_e32 v96, 16, v83
	v_pk_mul_f32 v[80:81], v[30:31], v[80:81]
	v_lshlrev_b32_e32 v76, 16, v77
	v_pk_fma_f32 v[80:81], v[30:31], v[96:97], v[80:81] op_sel:[1,0,0] op_sel_hi:[0,1,1]
	v_and_b32_e32 v77, 0xffff0000, v77
	v_cvt_f32_f16_sdwa v83, v75 dst_sel:DWORD dst_unused:UNUSED_PAD src0_sel:WORD_1
	v_cvt_f32_f16_e32 v82, v75
	v_pk_add_f32 v[76:77], v[80:81], v[76:77]
	v_cvt_f32_f16_sdwa v81, v74 dst_sel:DWORD dst_unused:UNUSED_PAD src0_sel:WORD_1
	v_cvt_f32_f16_e32 v80, v74
	v_pk_fma_f32 v[76:77], v[82:83], s[0:1], v[76:77] op_sel_hi:[1,0,1]
	v_lshlrev_b32_e32 v82, 16, v64
	v_and_b32_e32 v83, 0xffff0000, v66
	v_pk_fma_f32 v[74:75], v[80:81], s[0:1], v[94:95] op_sel_hi:[1,0,1]
	v_lshlrev_b32_e32 v80, 16, v66
	v_and_b32_e32 v81, 0xffff0000, v64
	v_pk_mul_f32 v[82:83], v[30:31], v[82:83]
	v_lshlrev_b32_e32 v64, 16, v65
	v_pk_fma_f32 v[80:81], v[30:31], v[80:81], v[82:83] op_sel:[1,0,0] op_sel_hi:[0,1,1]
	v_lshlrev_b32_e32 v82, 16, v62
	v_and_b32_e32 v83, 0xffff0000, v62
	v_pk_add_f32 v[80:81], v[80:81], v[82:83]
	v_and_b32_e32 v83, 0xffff0000, v65
	v_and_b32_e32 v65, 0xffff0000, v67
	v_lshlrev_b32_e32 v82, 16, v67
	v_pk_mul_f32 v[64:65], v[30:31], v[64:65]
	v_lshlrev_b32_e32 v62, 16, v63
	v_pk_fma_f32 v[30:31], v[30:31], v[82:83], v[64:65] op_sel:[1,0,0] op_sel_hi:[0,1,1]
	v_and_b32_e32 v63, 0xffff0000, v63
	v_pk_add_f32 v[30:31], v[30:31], v[62:63]
	v_cvt_f32_f16_sdwa v63, v58 dst_sel:DWORD dst_unused:UNUSED_PAD src0_sel:WORD_1
	v_cvt_f32_f16_e32 v62, v58
	v_cvt_f32_f16_sdwa v65, v59 dst_sel:DWORD dst_unused:UNUSED_PAD src0_sel:WORD_1
	v_cvt_f32_f16_e32 v64, v59
	v_pk_fma_f32 v[58:59], v[62:63], s[0:1], v[80:81] op_sel_hi:[1,0,1]
	v_cvt_pk_f16_f32 v62, v2, v3
	v_cvt_pk_f16_f32 v63, v4, v5
	global_store_dwordx2 v[42:43], v[62:63], off offset:1536
	v_mov_b32_e32 v42, v35
	v_cvt_pk_fp8_f32 v42, v2, v3
	v_pk_mov_b32 v[2:3], v[98:99], v[100:101] op_sel:[1,0]
	v_mov_b32_e32 v43, v93
	v_pk_fma_f32 v[30:31], v[64:65], s[0:1], v[30:31] op_sel_hi:[1,0,1]
	v_cvt_pk_fp8_f32 v42, v4, v5 op_sel:[0,0,1]
	v_mov_b32_e32 v4, v98
	v_mov_b32_e32 v5, v101
	v_pk_add_f32 v[2:3], v[2:3], v[4:5]
	global_store_dword v[154:155], v42, off offset:768
	v_pk_mov_b32 v[4:5], v[90:91], v[92:93] op_sel:[1,0]
	v_mov_b32_e32 v42, v90
	v_pk_add_f32 v[4:5], v[4:5], v[42:43]
	v_add_f32_e32 v2, v2, v3
	v_pk_add_f32 v[4:5], v[4:5], v[4:5] op_sel:[0,1] op_sel_hi:[1,0]
	v_add_f32_e32 v2, 0, v2
	v_add_f32_e32 v42, v74, v75
	v_add_f32_e32 v62, v76, v77
	v_mov_b32_e32 v3, v58
	v_mov_b32_e32 v5, v59
	v_mov_b32_e32 v43, v30
	v_mov_b32_e32 v63, v31
	v_pk_add_f32 v[2:3], v[2:3], v[4:5]
	v_pk_add_f32 v[4:5], v[42:43], v[62:63]
	s_lshl_b64 s[0:1], s[14:15], 12
	v_pk_add_f32 v[2:3], v[2:3], v[4:5]
	s_add_u32 s3, s34, s0
	v_add_f32_e32 v2, v2, v3
	ds_bpermute_b32 v3, v34, v2
	s_addc_u32 s4, s35, s1
	s_and_b64 s[0:1], s[8:9], exec
	s_cselect_b32 s1, s4, 0
	s_cselect_b32 s0, s3, 0
	s_waitcnt lgkmcnt(0)
; __device__ __forceinline__ unsigned cvt4_fp8(float a, float b, float c, float d) { int w = 0; w = __builtin_amdgcn_cvt_pk_fp8_f32(a, b, w, false); w = __builtin_amdgcn_cvt_pk_fp8_f32(c, d, w, true); return (unsigned)w; }
; __device__ __forceinline__ void ln_row_write(f32x4 (&v)[4], const float* g, const float* bta, float* of, bf16_t* ob, int lane, unsigned char* o8 = nullptr) {
;     float s = 0.f;
; #pragma unroll
;     for (int j = 0; j < 4; ++j) s += (v[j][0] + v[j][1]) + (v[j][2] + v[j][3]);
;     const float mean = wave_sum(s) * (1.0f / 1024.0f); float s2 = 0.f;
; #pragma unroll
;     for (int j = 0; j < 4; ++j) { v[j] = v[j] - mean; s2 += (v[j][0] * v[j][0] + v[j][1] * v[j][1]) + (v[j][2] * v[j][2] + v[j][3] * v[j][3]); }
;     const float rstd = rsqrtf(wave_sum(s2) * (1.0f / 1024.0f) + EPS);
; #pragma unroll
;     for (int j = 0; j < 4; ++j) { const f32x4 gg = *(const f32x4*)(g + 4 * lane + 256 * j), bb = *(const f32x4*)(bta + 4 * lane + 256 * j); v[j] = v[j] * rstd * gg + bb;
;         if (of) *(f32x4*)(of + 4 * lane + 256 * j) = v[j]; u32x2 w; w.x = cvt_pk_f16(v[j][0], v[j][1]); w.y = cvt_pk_f16(v[j][2], v[j][3]); *(u32x2*)(ob + 4 * lane + 256 * j) = w;
;         if (o8) *(unsigned*)(o8 + 4 * lane + 256 * j) = cvt4_fp8(v[j][0], v[j][1], v[j][2], v[j][3]); }
	v_add_f32_e32 v2, v2, v3
	ds_bpermute_b32 v3, v164, v2
	s_cmp_lg_u64 s[0:1], 0
	s_cselect_b64 s[4:5], -1, 0
	s_cmp_eq_u64 s[0:1], 0
	s_waitcnt lgkmcnt(0)
	v_add_f32_e32 v2, v2, v3
	ds_bpermute_b32 v3, v165, v2
	s_waitcnt lgkmcnt(0)
	v_add_f32_e32 v2, v2, v3
	ds_bpermute_b32 v3, v166, v2
	s_waitcnt lgkmcnt(0)
	v_add_f32_e32 v2, v2, v3
	ds_bpermute_b32 v3, v167, v2
	s_waitcnt lgkmcnt(0)
	v_add_f32_e32 v2, v2, v3
	ds_bpermute_b32 v3, v168, v2
	s_waitcnt lgkmcnt(0)
	v_add_f32_e32 v64, v2, v3
	v_fmamk_f32 v99, v64, 0xba800000, v99
	v_fmac_f32_e32 v98, 0xba800000, v64
	v_fmamk_f32 v101, v64, 0xba800000, v101
	v_fmac_f32_e32 v100, 0xba800000, v64
	v_pk_mul_f32 v[2:3], v[100:101], v[100:101]
	v_pk_mul_f32 v[4:5], v[98:99], v[98:99]
	v_fmamk_f32 v93, v64, 0xba800000, v93
	v_pk_mov_b32 v[42:43], v[4:5], v[2:3] op_sel:[1,0]
	v_mov_b32_e32 v5, v3
	v_pk_add_f32 v[2:3], v[42:43], v[4:5]
	v_fmac_f32_e32 v92, 0xba800000, v64
	v_fmamk_f32 v91, v64, 0xba800000, v91
	v_fmac_f32_e32 v90, 0xba800000, v64
	v_pk_add_f32 v[2:3], v[2:3], v[2:3] op_sel_hi:[0,1]
	v_pk_mul_f32 v[4:5], v[92:93], v[92:93]
	v_pk_mul_f32 v[42:43], v[90:91], v[90:91]
	v_fmac_f32_e32 v74, 0xba800000, v64
	v_pk_mov_b32 v[62:63], v[42:43], v[4:5] op_sel:[1,0]
	v_mov_b32_e32 v43, v5
	v_fmac_f32_e32 v76, 0xba800000, v64
	v_fmamk_f32 v75, v64, 0xba800000, v75
	v_mul_f32_e32 v2, v74, v74
	v_pk_add_f32 v[4:5], v[62:63], v[42:43]
	v_fmamk_f32 v77, v64, 0xba800000, v77
	v_pk_fma_f32 v[42:43], v[74:75], v[74:75], v[2:3] op_sel_hi:[1,1,0]
	v_mul_f32_e32 v2, v76, v76
	v_pk_add_f32 v[4:5], v[4:5], v[4:5] op_sel_hi:[0,1]
	v_pk_fma_f32 v[62:63], v[76:77], v[76:77], v[2:3] op_sel_hi:[1,1,0]
	v_fmamk_f32 v31, v64, 0xba800000, v31
	v_fmac_f32_e32 v30, 0xba800000, v64
	v_fmamk_f32 v59, v64, 0xba800000, v59
	v_fmac_f32_e32 v58, 0xba800000, v64
	v_mul_f32_e32 v42, v58, v58
	v_mul_f32_e32 v62, v59, v59
	v_mul_f32_e32 v2, v30, v30
	v_mul_f32_e32 v4, v31, v31
	v_pk_add_f32 v[42:43], v[42:43], v[62:63]
	v_pk_add_f32 v[2:3], v[2:3], v[4:5]
	s_nop 0
	v_pk_add_f32 v[2:3], v[42:43], v[2:3]
	v_lshl_add_u64 v[42:43], v[6:7], 2, s[0:1]
	v_add_f32_e32 v2, v2, v3
	ds_bpermute_b32 v3, v34, v2
	s_waitcnt lgkmcnt(0)
	v_add_f32_e32 v2, v2, v3
	ds_bpermute_b32 v3, v164, v2
	s_waitcnt lgkmcnt(0)
	v_add_f32_e32 v2, v2, v3
	ds_bpermute_b32 v3, v165, v2
	s_waitcnt lgkmcnt(0)
	v_add_f32_e32 v2, v2, v3
	ds_bpermute_b32 v3, v166, v2
	s_waitcnt lgkmcnt(0)
	v_add_f32_e32 v2, v2, v3
	ds_bpermute_b32 v3, v167, v2
	s_waitcnt lgkmcnt(0)
	v_add_f32_e32 v2, v2, v3
	ds_bpermute_b32 v3, v168, v2
	s_waitcnt lgkmcnt(0)
	v_add_f32_e32 v2, v2, v3
	v_fmamk_f32 v2, v2, 0x3a800000, v230
	v_cmp_gt_f32_e32 vcc, s97, v2
	v_mul_f32_e32 v3, 0x4b800000, v2
	s_nop 0
	v_cndmask_b32_e32 v2, v2, v3, vcc
	v_rsq_f32_e32 v2, v2
	s_nop 0
	v_mul_f32_e32 v3, 0x45800000, v2
	v_cndmask_b32_e32 v62, v2, v3, vcc
	v_pk_mul_f32 v[80:81], v[98:99], v[62:63] op_sel_hi:[1,0]
	v_pk_mul_f32 v[82:83], v[100:101], v[62:63] op_sel_hi:[1,0]
	v_pk_fma_f32 v[2:3], v[176:177], v[80:81], v[192:193]
	v_pk_fma_f32 v[4:5], v[178:179], v[82:83], v[194:195]
	s_cbranch_scc1 .LBB0_2039
	global_store_dwordx4 v[42:43], v[2:5], off
.LBB0_2039:
	v_cvt_pk_f16_f32 v66, v2, v3
	v_cvt_pk_f16_f32 v67, v4, v5
	global_store_dwordx2 v[40:41], v[66:67], off
	v_mov_b32_e32 v66, v35
	v_cvt_pk_fp8_f32 v66, v2, v3
	s_lshl_b64 s[0:1], s[14:15], 10
	s_add_u32 s0, s20, s0
	s_addc_u32 s1, s21, s1
	v_cvt_pk_fp8_f32 v66, v4, v5 op_sel:[0,0,1]
	v_lshl_add_u64 v[64:65], s[0:1], 0, v[6:7]
	v_mov_b32_e32 v63, v62
	v_mov_b32_e32 v67, v62
	global_store_dword v[64:65], v66, off
	v_mov_b32_e32 v66, v62
	v_pk_mul_f32 v[90:91], v[90:91], v[62:63]
	v_pk_mul_f32 v[92:93], v[92:93], v[66:67]
	s_andn2_b64 vcc, exec, s[4:5]
	v_pk_fma_f32 v[2:3], v[90:91], v[180:181], v[206:207]
	v_cndmask_b32_e64 v80, 0, 1, s[4:5]
	v_pk_fma_f32 v[4:5], v[92:93], v[182:183], v[208:209]
	v_cmp_ne_u32_e64 s[0:1], 1, v80
	s_cbranch_vccnz .LBB0_2041
	global_store_dwordx4 v[42:43], v[2:5], off offset:1024
.LBB0_2041:
	v_mov_b32_e32 v80, v35
	v_cvt_pk_fp8_f32 v80, v2, v3
	v_cvt_pk_f16_f32 v2, v2, v3
	v_cvt_pk_f16_f32 v3, v4, v5
	v_pk_mul_f32 v[66:67], v[76:77], v[66:67]
	v_cvt_pk_fp8_f32 v80, v4, v5 op_sel:[0,0,1]
	v_pk_mul_f32 v[74:75], v[74:75], v[62:63]
	s_and_b64 vcc, exec, s[0:1]
	global_store_dwordx2 v[40:41], v[2:3], off offset:512
	global_store_dword v[64:65], v80, off offset:256
	s_nop 0
	v_pk_fma_f32 v[4:5], v[66:67], v[186:187], v[212:213]
	v_pk_fma_f32 v[2:3], v[74:75], v[184:185], v[210:211]
	s_cbranch_vccnz .LBB0_2043
	global_store_dwordx4 v[42:43], v[2:5], off offset:2048
.LBB0_2043:
	v_mov_b32_e32 v66, v35
	v_cvt_pk_fp8_f32 v66, v2, v3
	v_cvt_pk_f16_f32 v2, v2, v3
	v_cvt_pk_f16_f32 v3, v4, v5
	v_mov_b32_e32 v67, v62
	v_cvt_pk_fp8_f32 v66, v4, v5 op_sel:[0,0,1]
	v_pk_mul_f32 v[58:59], v[58:59], v[62:63]
	s_and_b64 vcc, exec, s[0:1]
	global_store_dwordx2 v[40:41], v[2:3], off offset:1024
	global_store_dword v[64:65], v66, off offset:512
	s_nop 0
	v_mov_b32_e32 v66, v62
	v_pk_mul_f32 v[30:31], v[30:31], v[66:67]
	s_waitcnt vmcnt(0)
	v_pk_fma_f32 v[2:3], v[58:59], v[188:189], v[214:215]
	v_pk_fma_f32 v[4:5], v[30:31], v[190:191], v[216:217]
	s_cbranch_vccnz .LBB0_2045
	global_store_dwordx4 v[42:43], v[2:5], off offset:3072
; __device__ __forceinline__ float h2f_(unsigned short b) { return (float)__builtin_bit_cast(_Float16, b); }
; template <bool MOE>
; __device__ __forceinline__ void ln2_phase(const Frame& F, int layer) {
;     ...
;             for (int s_ = 0; s_ < 2; ++s_) { const float w0 = w0a[i + s_], w1 = w1a[i + s_];
; #pragma unroll
;                 for (int j = 0; j < 4; ++j) { const u32x2 x = nxr[s_][j], a = na[s_][j], c = nc[s_][j], pp = np_[s_][j];
;                     f32x4 f;
;                     f[0] = w0 * __uint_as_float(a.x << 16) + w1 * __uint_as_float(c.x << 16) + __uint_as_float(pp.x << 16);
;                     f[1] = w0 * __uint_as_float(a.x & 0xffff0000u) + w1 * __uint_as_float(c.x & 0xffff0000u) + __uint_as_float(pp.x & 0xffff0000u);
;                     f[2] = w0 * __uint_as_float(a.y << 16) + w1 * __uint_as_float(c.y << 16) + __uint_as_float(pp.y << 16);
;                     f[3] = w0 * __uint_as_float(a.y & 0xffff0000u) + w1 * __uint_as_float(c.y & 0xffff0000u) + __uint_as_float(pp.y & 0xffff0000u);
;                     v[s_][j] = (f32x4){h2f_((unsigned short)(x.x & 0xffffu)), h2f_((unsigned short)(x.x >> 16)), h2f_((unsigned short)(x.y & 0xffffu)), h2f_((unsigned short)(x.y >> 16))} * ALPHA + f; } }
;             if (i + 2 < 8) { LN2_LOAD(0, F.gw + (i + 2) * F.NGW, s0a[i + 2], s1a[i + 2]); LN2_LOAD(1, F.gw + (i + 3) * F.NGW, s0a[i + 3], s1a[i + 3]); }
.LBB0_2045:
	v_cvt_pk_f16_f32 v30, v2, v3
	v_cvt_pk_f16_f32 v31, v4, v5
	global_store_dwordx2 v[40:41], v[30:31], off offset:1536
	v_mov_b32_e32 v30, v35
	v_cvt_pk_fp8_f32 v30, v2, v3
	v_lshlrev_b32_e32 v2, 16, v136
	v_and_b32_e32 v3, 0xffff0000, v134
	v_and_b32_e32 v31, 0xffff0000, v137
	v_cvt_pk_fp8_f32 v30, v4, v5 op_sel:[0,0,1]
	v_lshlrev_b32_e32 v4, 16, v134
	v_and_b32_e32 v5, 0xffff0000, v136
	v_pk_mul_f32 v[4:5], v[22:23], v[4:5]
	global_store_dword v[64:65], v30, off offset:768
	v_pk_fma_f32 v[2:3], v[22:23], v[2:3], v[4:5] op_sel:[1,0,0] op_sel_hi:[0,1,1]
	v_lshlrev_b32_e32 v4, 16, v132
	v_and_b32_e32 v5, 0xffff0000, v132
	v_lshlrev_b32_e32 v30, 16, v135
	v_pk_add_f32 v[2:3], v[2:3], v[4:5]
	v_lshlrev_b32_e32 v4, 16, v137
	v_and_b32_e32 v5, 0xffff0000, v135
	v_pk_mul_f32 v[30:31], v[22:23], v[30:31]
	v_cvt_f32_f16_sdwa v41, v131 dst_sel:DWORD dst_unused:UNUSED_PAD src0_sel:WORD_1
	v_pk_fma_f32 v[4:5], v[22:23], v[4:5], v[30:31] op_sel:[1,0,0] op_sel_hi:[0,1,1]
	v_lshlrev_b32_e32 v30, 16, v133
	v_and_b32_e32 v31, 0xffff0000, v133
	v_cvt_f32_f16_e32 v40, v131
	v_pk_add_f32 v[4:5], v[4:5], v[30:31]
	v_cvt_f32_f16_sdwa v31, v130 dst_sel:DWORD dst_unused:UNUSED_PAD src0_sel:WORD_1
	v_cvt_f32_f16_e32 v30, v130
	s_mov_b32 s0, 0x3fd744fd
	v_pk_fma_f32 v[4:5], v[40:41], s[0:1], v[4:5] op_sel_hi:[1,0,1]
	v_lshlrev_b32_e32 v40, 16, v126
	v_and_b32_e32 v41, 0xffff0000, v128
	v_pk_fma_f32 v[2:3], v[30:31], s[0:1], v[2:3] op_sel_hi:[1,0,1]
	v_lshlrev_b32_e32 v30, 16, v128
	v_and_b32_e32 v31, 0xffff0000, v126
	v_pk_mul_f32 v[40:41], v[22:23], v[40:41]
	v_lshlrev_b32_e32 v42, 16, v127
	v_pk_fma_f32 v[30:31], v[22:23], v[30:31], v[40:41] op_sel:[1,0,0] op_sel_hi:[0,1,1]
	v_lshlrev_b32_e32 v40, 16, v124
	v_and_b32_e32 v41, 0xffff0000, v124
	v_and_b32_e32 v43, 0xffff0000, v129
	v_pk_add_f32 v[30:31], v[30:31], v[40:41]
	v_lshlrev_b32_e32 v40, 16, v129
	v_and_b32_e32 v41, 0xffff0000, v127
	v_pk_mul_f32 v[42:43], v[22:23], v[42:43]
	v_cvt_f32_f16_sdwa v59, v123 dst_sel:DWORD dst_unused:UNUSED_PAD src0_sel:WORD_1
	v_pk_fma_f32 v[40:41], v[22:23], v[40:41], v[42:43] op_sel:[1,0,0] op_sel_hi:[0,1,1]
	v_lshlrev_b32_e32 v42, 16, v125
	v_and_b32_e32 v43, 0xffff0000, v125
	v_cvt_f32_f16_e32 v58, v123
	v_pk_add_f32 v[40:41], v[40:41], v[42:43]
	v_cvt_f32_f16_sdwa v43, v122 dst_sel:DWORD dst_unused:UNUSED_PAD src0_sel:WORD_1
	v_cvt_f32_f16_e32 v42, v122
	v_pk_fma_f32 v[134:135], v[58:59], s[0:1], v[40:41] op_sel_hi:[1,0,1]
	v_lshlrev_b32_e32 v40, 16, v118
	v_and_b32_e32 v41, 0xffff0000, v120
	v_pk_fma_f32 v[132:133], v[42:43], s[0:1], v[30:31] op_sel_hi:[1,0,1]
	v_lshlrev_b32_e32 v30, 16, v120
	v_and_b32_e32 v31, 0xffff0000, v118
	v_pk_mul_f32 v[40:41], v[22:23], v[40:41]
	v_lshlrev_b32_e32 v42, 16, v119
	v_pk_fma_f32 v[30:31], v[22:23], v[30:31], v[40:41] op_sel:[1,0,0] op_sel_hi:[0,1,1]
	v_lshlrev_b32_e32 v40, 16, v116
	v_and_b32_e32 v41, 0xffff0000, v116
	v_and_b32_e32 v43, 0xffff0000, v121
	v_pk_add_f32 v[30:31], v[30:31], v[40:41]
	v_lshlrev_b32_e32 v40, 16, v121
	v_and_b32_e32 v41, 0xffff0000, v119
	v_pk_mul_f32 v[42:43], v[22:23], v[42:43]
	v_cvt_f32_f16_sdwa v59, v111 dst_sel:DWORD dst_unused:UNUSED_PAD src0_sel:WORD_1
	v_pk_fma_f32 v[40:41], v[22:23], v[40:41], v[42:43] op_sel:[1,0,0] op_sel_hi:[0,1,1]
	v_lshlrev_b32_e32 v42, 16, v117
	v_and_b32_e32 v43, 0xffff0000, v117
	v_cvt_f32_f16_e32 v58, v111
	v_pk_add_f32 v[40:41], v[40:41], v[42:43]
	v_cvt_f32_f16_sdwa v43, v110 dst_sel:DWORD dst_unused:UNUSED_PAD src0_sel:WORD_1
	v_cvt_f32_f16_e32 v42, v110
	v_pk_fma_f32 v[126:127], v[58:59], s[0:1], v[40:41] op_sel_hi:[1,0,1]
	v_lshlrev_b32_e32 v40, 16, v108
	v_and_b32_e32 v41, 0xffff0000, v112
	v_pk_fma_f32 v[124:125], v[42:43], s[0:1], v[30:31] op_sel_hi:[1,0,1]
	v_lshlrev_b32_e32 v30, 16, v112
	v_and_b32_e32 v31, 0xffff0000, v108
	v_pk_mul_f32 v[40:41], v[22:23], v[40:41]
	v_lshlrev_b32_e32 v42, 16, v109
	v_pk_fma_f32 v[30:31], v[22:23], v[30:31], v[40:41] op_sel:[1,0,0] op_sel_hi:[0,1,1]
	v_lshlrev_b32_e32 v40, 16, v114
	v_and_b32_e32 v41, 0xffff0000, v114
	v_and_b32_e32 v43, 0xffff0000, v113
	v_pk_add_f32 v[30:31], v[30:31], v[40:41]
	v_lshlrev_b32_e32 v40, 16, v113
	v_and_b32_e32 v41, 0xffff0000, v109
	v_pk_mul_f32 v[42:43], v[22:23], v[42:43]
	s_ashr_i32 s7, s6, 31
	v_pk_fma_f32 v[22:23], v[22:23], v[40:41], v[42:43] op_sel:[1,0,0] op_sel_hi:[0,1,1]
	v_lshlrev_b32_e32 v40, 16, v115
	v_and_b32_e32 v41, 0xffff0000, v115
	v_pk_add_f32 v[22:23], v[22:23], v[40:41]
	v_cvt_f32_f16_sdwa v41, v106 dst_sel:DWORD dst_unused:UNUSED_PAD src0_sel:WORD_1
	v_cvt_f32_f16_e32 v40, v106
	v_cvt_f32_f16_sdwa v43, v107 dst_sel:DWORD dst_unused:UNUSED_PAD src0_sel:WORD_1
	v_cvt_f32_f16_e32 v42, v107
	s_ashr_i32 s3, s2, 31
	v_pk_fma_f32 v[130:131], v[40:41], s[0:1], v[30:31] op_sel_hi:[1,0,1]
	v_ashrrev_i32_e32 v31, 31, v20
	v_mov_b32_e32 v30, v20
	v_ashrrev_i32_e32 v41, 31, v21
	v_mov_b32_e32 v40, v21
	v_pk_fma_f32 v[128:129], v[42:43], s[0:1], v[22:23] op_sel_hi:[1,0,1]
	s_lshl_b64 s[0:1], s[6:7], 11
	v_lshlrev_b64 v[30:31], 11, v[30:31]
	v_lshlrev_b64 v[20:21], 11, v[40:41]
	v_lshl_add_u64 v[22:23], v[28:29], 0, s[0:1]
	v_lshl_add_u64 v[30:31], v[24:25], 0, v[30:31]
	v_lshl_add_u64 v[20:21], v[24:25], 0, v[20:21]
	v_lshl_add_u64 v[40:41], v[26:27], 0, s[0:1]
	s_lshl_b64 s[0:1], s[2:3], 11
	global_load_dwordx2 v[116:117], v[22:23], off
	global_load_dwordx2 v[120:121], v[30:31], off
	global_load_dwordx2 v[122:123], v[20:21], off
	global_load_dwordx2 v[118:119], v[40:41], off
	global_load_dwordx2 v[108:109], v[22:23], off offset:512
	global_load_dwordx2 v[112:113], v[30:31], off offset:512
	global_load_dwordx2 v[114:115], v[20:21], off offset:512
; __device__ __forceinline__ unsigned cvt4_fp8(float a, float b, float c, float d) { int w = 0; w = __builtin_amdgcn_cvt_pk_fp8_f32(a, b, w, false); w = __builtin_amdgcn_cvt_pk_fp8_f32(c, d, w, true); return (unsigned)w; }
; __device__ __forceinline__ void ln_row_write(f32x4 (&v)[4], const float* g, const float* bta, float* of, bf16_t* ob, int lane, unsigned char* o8 = nullptr) {
;     float s = 0.f;
; #pragma unroll
;     for (int j = 0; j < 4; ++j) s += (v[j][0] + v[j][1]) + (v[j][2] + v[j][3]);
;     const float mean = wave_sum(s) * (1.0f / 1024.0f); float s2 = 0.f;
; #pragma unroll
;     for (int j = 0; j < 4; ++j) { v[j] = v[j] - mean; s2 += (v[j][0] * v[j][0] + v[j][1] * v[j][1]) + (v[j][2] * v[j][2] + v[j][3] * v[j][3]); }
;     const float rstd = rsqrtf(wave_sum(s2) * (1.0f / 1024.0f) + EPS);
; #pragma unroll
;     for (int j = 0; j < 4; ++j) { const f32x4 gg = *(const f32x4*)(g + 4 * lane + 256 * j), bb = *(const f32x4*)(bta + 4 * lane + 256 * j); v[j] = v[j] * rstd * gg + bb;
;         if (of) *(f32x4*)(of + 4 * lane + 256 * j) = v[j]; u32x2 w; w.x = cvt_pk_f16(v[j][0], v[j][1]); w.y = cvt_pk_f16(v[j][2], v[j][3]); *(u32x2*)(ob + 4 * lane + 256 * j) = w;
;         if (o8) *(unsigned*)(o8 + 4 * lane + 256 * j) = cvt4_fp8(v[j][0], v[j][1], v[j][2], v[j][3]); }
	global_load_dwordx2 v[110:111], v[40:41], off offset:512
	global_load_dwordx2 v[96:97], v[22:23], off offset:1024
	global_load_dwordx2 v[104:105], v[30:31], off offset:1024
	global_load_dwordx2 v[106:107], v[20:21], off offset:1024
	global_load_dwordx2 v[102:103], v[40:41], off offset:1024
	global_load_dwordx2 v[92:93], v[22:23], off offset:1536
	global_load_dwordx2 v[94:95], v[30:31], off offset:1536
	global_load_dwordx2 v[98:99], v[20:21], off offset:1536
	global_load_dwordx2 v[100:101], v[40:41], off offset:1536
	v_lshl_add_u64 v[20:21], v[28:29], 0, s[0:1]
	v_ashrrev_i32_e32 v29, 31, v18
	v_mov_b32_e32 v28, v18
	v_ashrrev_i32_e32 v31, 31, v19
	v_mov_b32_e32 v30, v19
	v_lshlrev_b64 v[28:29], 11, v[28:29]
	v_lshlrev_b64 v[18:19], 11, v[30:31]
	v_lshl_add_u64 v[28:29], v[24:25], 0, v[28:29]
	v_lshl_add_u64 v[24:25], v[24:25], 0, v[18:19]
	v_lshl_add_u64 v[136:137], v[26:27], 0, s[0:1]
	global_load_dwordx2 v[76:77], v[20:21], off
	global_load_dwordx2 v[82:83], v[28:29], off
	global_load_dwordx2 v[90:91], v[24:25], off
	global_load_dwordx2 v[80:81], v[136:137], off
	global_load_dwordx2 v[62:63], v[20:21], off offset:512
	global_load_dwordx2 v[66:67], v[28:29], off offset:512
	global_load_dwordx2 v[74:75], v[24:25], off offset:512
	global_load_dwordx2 v[64:65], v[136:137], off offset:512
	global_load_dwordx2 v[30:31], v[20:21], off offset:1024
	global_load_dwordx2 v[42:43], v[28:29], off offset:1024
	global_load_dwordx2 v[58:59], v[24:25], off offset:1024
	global_load_dwordx2 v[40:41], v[136:137], off offset:1024
	global_load_dwordx2 v[18:19], v[20:21], off offset:1536
	global_load_dwordx2 v[26:27], v[28:29], off offset:1536
	s_nop 0
	global_load_dwordx2 v[28:29], v[24:25], off offset:1536
	s_nop 0
	global_load_dwordx2 v[24:25], v[136:137], off offset:1536
	v_pk_mov_b32 v[136:137], v[2:3], v[4:5] op_sel:[1,0]
	v_mov_b32_e32 v138, v2
	v_mov_b32_e32 v139, v5
	v_pk_add_f32 v[136:137], v[136:137], v[138:139]
	v_pk_mov_b32 v[138:139], v[132:133], v[134:135] op_sel:[1,0]
	v_mov_b32_e32 v140, v132
	v_mov_b32_e32 v141, v135
	v_pk_add_f32 v[138:139], v[138:139], v[140:141]
	v_add_f32_e32 v136, v136, v137
	v_pk_add_f32 v[138:139], v[138:139], v[138:139] op_sel:[0,1] op_sel_hi:[1,0]
	v_add_f32_e32 v136, 0, v136
	v_add_f32_e32 v140, v124, v125
	v_add_f32_e32 v142, v126, v127
	v_mov_b32_e32 v137, v130
	v_mov_b32_e32 v139, v131
	v_mov_b32_e32 v141, v128
	v_mov_b32_e32 v143, v129
	v_pk_add_f32 v[136:137], v[136:137], v[138:139]
	v_pk_add_f32 v[138:139], v[140:141], v[142:143]
	s_lshl_b64 s[0:1], s[12:13], 12
	v_pk_add_f32 v[136:137], v[136:137], v[138:139]
	s_add_u32 s4, s34, s0
	v_add_f32_e32 v136, v136, v137
	ds_bpermute_b32 v137, v34, v136
	s_addc_u32 s5, s35, s1
	s_and_b64 s[0:1], s[8:9], exec
	s_cselect_b32 s1, s5, 0
	s_cselect_b32 s0, s4, 0
	s_waitcnt lgkmcnt(0)
	v_add_f32_e32 v136, v136, v137
	ds_bpermute_b32 v137, v164, v136
	s_cmp_lg_u64 s[0:1], 0
	s_cselect_b64 s[4:5], -1, 0
	s_cmp_eq_u64 s[0:1], 0
	s_waitcnt lgkmcnt(0)
	v_add_f32_e32 v136, v136, v137
	ds_bpermute_b32 v137, v165, v136
	s_waitcnt lgkmcnt(0)
	v_add_f32_e32 v136, v136, v137
	ds_bpermute_b32 v137, v166, v136
	s_waitcnt lgkmcnt(0)
	v_add_f32_e32 v136, v136, v137
	ds_bpermute_b32 v137, v167, v136
	s_waitcnt lgkmcnt(0)
	v_add_f32_e32 v136, v136, v137
	ds_bpermute_b32 v137, v168, v136
	s_waitcnt lgkmcnt(0)
	v_add_f32_e32 v144, v136, v137
	v_fmamk_f32 v3, v144, 0xba800000, v3
	v_fmac_f32_e32 v2, 0xba800000, v144
	v_fmamk_f32 v5, v144, 0xba800000, v5
	v_fmac_f32_e32 v4, 0xba800000, v144
	v_pk_mul_f32 v[136:137], v[4:5], v[4:5]
	v_pk_mul_f32 v[138:139], v[2:3], v[2:3]
	v_fmamk_f32 v135, v144, 0xba800000, v135
	v_pk_mov_b32 v[140:141], v[138:139], v[136:137] op_sel:[1,0]
	v_mov_b32_e32 v139, v137
	v_pk_add_f32 v[136:137], v[140:141], v[138:139]
	v_fmac_f32_e32 v134, 0xba800000, v144
	v_fmamk_f32 v133, v144, 0xba800000, v133
	v_fmac_f32_e32 v132, 0xba800000, v144
	v_pk_add_f32 v[136:137], v[136:137], v[136:137] op_sel_hi:[0,1]
	v_pk_mul_f32 v[138:139], v[134:135], v[134:135]
	v_pk_mul_f32 v[140:141], v[132:133], v[132:133]
	v_fmac_f32_e32 v124, 0xba800000, v144
	v_pk_mov_b32 v[142:143], v[140:141], v[138:139] op_sel:[1,0]
	v_mov_b32_e32 v141, v139
	v_fmac_f32_e32 v126, 0xba800000, v144
	v_fmamk_f32 v125, v144, 0xba800000, v125
	v_mul_f32_e32 v136, v124, v124
	v_pk_add_f32 v[138:139], v[142:143], v[140:141]
	v_fmamk_f32 v127, v144, 0xba800000, v127
	v_pk_fma_f32 v[140:141], v[124:125], v[124:125], v[136:137] op_sel_hi:[1,1,0]
	v_mul_f32_e32 v136, v126, v126
	v_pk_add_f32 v[138:139], v[138:139], v[138:139] op_sel_hi:[0,1]
	v_pk_fma_f32 v[142:143], v[126:127], v[126:127], v[136:137] op_sel_hi:[1,1,0]
	v_fmamk_f32 v129, v144, 0xba800000, v129
	v_fmac_f32_e32 v128, 0xba800000, v144
	v_fmamk_f32 v131, v144, 0xba800000, v131
	v_fmac_f32_e32 v130, 0xba800000, v144
	v_mul_f32_e32 v140, v130, v130
	v_mul_f32_e32 v142, v131, v131
	v_mul_f32_e32 v136, v128, v128
	v_mul_f32_e32 v138, v129, v129
	v_pk_add_f32 v[140:141], v[140:141], v[142:143]
	v_pk_add_f32 v[136:137], v[136:137], v[138:139]
	s_nop 0
	v_pk_add_f32 v[136:137], v[140:141], v[136:137]
	v_add_f32_e32 v136, v136, v137
	ds_bpermute_b32 v137, v34, v136
	s_waitcnt lgkmcnt(0)
	v_add_f32_e32 v136, v136, v137
	ds_bpermute_b32 v137, v164, v136
	s_waitcnt lgkmcnt(0)
	v_add_f32_e32 v136, v136, v137
	ds_bpermute_b32 v137, v165, v136
	s_waitcnt lgkmcnt(0)
	v_add_f32_e32 v136, v136, v137
	ds_bpermute_b32 v137, v166, v136
	s_waitcnt lgkmcnt(0)
	v_add_f32_e32 v136, v136, v137
	ds_bpermute_b32 v137, v167, v136
	s_waitcnt lgkmcnt(0)
	v_add_f32_e32 v136, v136, v137
	ds_bpermute_b32 v137, v168, v136
	s_waitcnt lgkmcnt(0)
	v_add_f32_e32 v136, v136, v137
	v_fmamk_f32 v136, v136, 0x3a800000, v230
	v_cmp_gt_f32_e32 vcc, s97, v136
	v_mul_f32_e32 v137, 0x4b800000, v136
	s_nop 0
	v_cndmask_b32_e32 v136, v136, v137, vcc
	v_rsq_f32_e32 v136, v136
	s_nop 0
	v_mul_f32_e32 v137, 0x45800000, v136
	v_cndmask_b32_e32 v138, v136, v137, vcc
	v_pk_mul_f32 v[2:3], v[2:3], v[138:139] op_sel_hi:[1,0]
	v_pk_mul_f32 v[4:5], v[4:5], v[138:139] op_sel_hi:[1,0]
	v_lshl_add_u64 v[136:137], v[6:7], 2, s[0:1]
	v_pk_fma_f32 v[4:5], v[178:179], v[4:5], v[194:195]
	v_pk_fma_f32 v[2:3], v[176:177], v[2:3], v[192:193]
	s_cbranch_scc1 .LBB0_2047
	global_store_dwordx4 v[136:137], v[2:5], off
; __device__ __forceinline__ float h2f_(unsigned short b) { return (float)__builtin_bit_cast(_Float16, b); }
; __device__ __forceinline__ unsigned cvt4_fp8(float a, float b, float c, float d) { int w = 0; w = __builtin_amdgcn_cvt_pk_fp8_f32(a, b, w, false); w = __builtin_amdgcn_cvt_pk_fp8_f32(c, d, w, true); return (unsigned)w; }
; __device__ __forceinline__ void ln_row_write(f32x4 (&v)[4], const float* g, const float* bta, float* of, bf16_t* ob, int lane, unsigned char* o8 = nullptr) {
;     ...
; #pragma unroll
;     for (int j = 0; j < 4; ++j) { const f32x4 gg = *(const f32x4*)(g + 4 * lane + 256 * j), bb = *(const f32x4*)(bta + 4 * lane + 256 * j); v[j] = v[j] * rstd * gg + bb;
;         if (of) *(f32x4*)(of + 4 * lane + 256 * j) = v[j]; u32x2 w; w.x = cvt_pk_f16(v[j][0], v[j][1]); w.y = cvt_pk_f16(v[j][2], v[j][3]); *(u32x2*)(ob + 4 * lane + 256 * j) = w;
;         if (o8) *(unsigned*)(o8 + 4 * lane + 256 * j) = cvt4_fp8(v[j][0], v[j][1], v[j][2], v[j][3]); }
; template <bool MOE>
; __device__ __forceinline__ void ln2_phase(const Frame& F, int layer) {
;     ...
;             for (int s_ = 0; s_ < 2; ++s_) { const float w0 = w0a[i + s_], w1 = w1a[i + s_];
; #pragma unroll
;                 for (int j = 0; j < 4; ++j) { const u32x2 x = nxr[s_][j], a = na[s_][j], c = nc[s_][j], pp = np_[s_][j];
;                     f32x4 f;
;                     f[0] = w0 * __uint_as_float(a.x << 16) + w1 * __uint_as_float(c.x << 16) + __uint_as_float(pp.x << 16);
;                     f[1] = w0 * __uint_as_float(a.x & 0xffff0000u) + w1 * __uint_as_float(c.x & 0xffff0000u) + __uint_as_float(pp.x & 0xffff0000u);
;                     f[2] = w0 * __uint_as_float(a.y << 16) + w1 * __uint_as_float(c.y << 16) + __uint_as_float(pp.y << 16);
;                     f[3] = w0 * __uint_as_float(a.y & 0xffff0000u) + w1 * __uint_as_float(c.y & 0xffff0000u) + __uint_as_float(pp.y & 0xffff0000u);
;                     v[s_][j] = (f32x4){h2f_((unsigned short)(x.x & 0xffffu)), h2f_((unsigned short)(x.x >> 16)), h2f_((unsigned short)(x.y & 0xffffu)), h2f_((unsigned short)(x.y >> 16))} * ALPHA + f; } }
.LBB0_2047:
	v_cvt_pk_f16_f32 v142, v2, v3
	v_cvt_pk_f16_f32 v143, v4, v5
	global_store_dwordx2 v[38:39], v[142:143], off
	v_mov_b32_e32 v142, v35
	v_cvt_pk_fp8_f32 v142, v2, v3
	s_lshl_b64 s[0:1], s[12:13], 10
	s_add_u32 s0, s20, s0
	s_addc_u32 s1, s21, s1
	v_cvt_pk_fp8_f32 v142, v4, v5 op_sel:[0,0,1]
	v_lshl_add_u64 v[140:141], s[0:1], 0, v[6:7]
	v_mov_b32_e32 v139, v138
	v_mov_b32_e32 v143, v138
	global_store_dword v[140:141], v142, off
	v_mov_b32_e32 v142, v138
	v_pk_mul_f32 v[132:133], v[132:133], v[138:139]
	v_pk_mul_f32 v[134:135], v[134:135], v[142:143]
	s_andn2_b64 vcc, exec, s[4:5]
	v_pk_fma_f32 v[2:3], v[132:133], v[180:181], v[206:207]
	v_cndmask_b32_e64 v132, 0, 1, s[4:5]
	v_pk_fma_f32 v[4:5], v[134:135], v[182:183], v[208:209]
	v_cmp_ne_u32_e64 s[0:1], 1, v132
	s_cbranch_vccnz .LBB0_2049
	global_store_dwordx4 v[136:137], v[2:5], off offset:1024
.LBB0_2049:
	v_mov_b32_e32 v132, v35
	v_cvt_pk_fp8_f32 v132, v2, v3
	v_cvt_pk_f16_f32 v2, v2, v3
	v_cvt_pk_f16_f32 v3, v4, v5
	v_pk_mul_f32 v[126:127], v[126:127], v[142:143]
	v_cvt_pk_fp8_f32 v132, v4, v5 op_sel:[0,0,1]
	v_pk_mul_f32 v[124:125], v[124:125], v[138:139]
	s_and_b64 vcc, exec, s[0:1]
	global_store_dwordx2 v[38:39], v[2:3], off offset:512
	global_store_dword v[140:141], v132, off offset:256
	s_nop 0
	v_pk_fma_f32 v[4:5], v[126:127], v[186:187], v[212:213]
	v_pk_fma_f32 v[2:3], v[124:125], v[184:185], v[210:211]
	s_cbranch_vccnz .LBB0_2051
	global_store_dwordx4 v[136:137], v[2:5], off offset:2048
.LBB0_2051:
	v_mov_b32_e32 v124, v35
	v_cvt_pk_fp8_f32 v124, v2, v3
	v_cvt_pk_f16_f32 v2, v2, v3
	v_cvt_pk_f16_f32 v3, v4, v5
	v_mov_b32_e32 v132, v138
	v_cvt_pk_fp8_f32 v124, v4, v5 op_sel:[0,0,1]
	v_mov_b32_e32 v133, v138
	v_pk_mul_f32 v[130:131], v[130:131], v[138:139]
	global_store_dwordx2 v[38:39], v[2:3], off offset:1024
	global_store_dword v[140:141], v124, off offset:512
	s_nop 0
	v_pk_mul_f32 v[128:129], v[128:129], v[132:133]
	s_and_b64 vcc, exec, s[0:1]
	v_pk_fma_f32 v[4:5], v[128:129], v[190:191], v[216:217]
	v_pk_fma_f32 v[2:3], v[130:131], v[188:189], v[214:215]
	s_cbranch_vccnz .LBB0_2053
	global_store_dwordx4 v[136:137], v[2:5], off offset:3072
.LBB0_2053:
	v_lshlrev_b32_e32 v126, 16, v86
	v_and_b32_e32 v127, 0xffff0000, v88
	v_lshlrev_b32_e32 v124, 16, v88
	v_and_b32_e32 v125, 0xffff0000, v86
	v_pk_mul_f32 v[126:127], v[16:17], v[126:127]
	v_lshlrev_b32_e32 v86, 16, v87
	v_pk_fma_f32 v[124:125], v[16:17], v[124:125], v[126:127] op_sel:[1,0,0] op_sel_hi:[0,1,1]
	v_lshlrev_b32_e32 v126, 16, v84
	v_and_b32_e32 v127, 0xffff0000, v84
	v_pk_add_f32 v[124:125], v[124:125], v[126:127]
	v_and_b32_e32 v127, 0xffff0000, v87
	v_and_b32_e32 v87, 0xffff0000, v89
	v_lshlrev_b32_e32 v126, 16, v89
	v_pk_mul_f32 v[86:87], v[16:17], v[86:87]
	v_lshlrev_b32_e32 v84, 16, v85
	v_pk_fma_f32 v[86:87], v[16:17], v[126:127], v[86:87] op_sel:[1,0,0] op_sel_hi:[0,1,1]
	v_and_b32_e32 v85, 0xffff0000, v85
	v_cvt_f32_f16_sdwa v89, v79 dst_sel:DWORD dst_unused:UNUSED_PAD src0_sel:WORD_1
	v_cvt_f32_f16_e32 v88, v79
	v_pk_add_f32 v[84:85], v[86:87], v[84:85]
	v_cvt_f32_f16_sdwa v87, v78 dst_sel:DWORD dst_unused:UNUSED_PAD src0_sel:WORD_1
	v_cvt_f32_f16_e32 v86, v78
	s_mov_b32 s0, 0x3fd744fd
	v_pk_fma_f32 v[84:85], v[88:89], s[0:1], v[84:85] op_sel_hi:[1,0,1]
	v_lshlrev_b32_e32 v88, 16, v70
	v_and_b32_e32 v89, 0xffff0000, v72
	v_pk_fma_f32 v[78:79], v[86:87], s[0:1], v[124:125] op_sel_hi:[1,0,1]
	v_lshlrev_b32_e32 v86, 16, v72
	v_and_b32_e32 v87, 0xffff0000, v70
	v_pk_mul_f32 v[88:89], v[16:17], v[88:89]
	v_lshlrev_b32_e32 v70, 16, v71
	v_pk_fma_f32 v[86:87], v[16:17], v[86:87], v[88:89] op_sel:[1,0,0] op_sel_hi:[0,1,1]
	v_lshlrev_b32_e32 v88, 16, v68
	v_and_b32_e32 v89, 0xffff0000, v68
	v_pk_add_f32 v[86:87], v[86:87], v[88:89]
	v_and_b32_e32 v89, 0xffff0000, v71
	v_and_b32_e32 v71, 0xffff0000, v73
	v_lshlrev_b32_e32 v88, 16, v73
	v_pk_mul_f32 v[70:71], v[16:17], v[70:71]
	v_lshlrev_b32_e32 v68, 16, v69
	v_pk_fma_f32 v[70:71], v[16:17], v[88:89], v[70:71] op_sel:[1,0,0] op_sel_hi:[0,1,1]
	v_and_b32_e32 v69, 0xffff0000, v69
	v_cvt_f32_f16_sdwa v73, v61 dst_sel:DWORD dst_unused:UNUSED_PAD src0_sel:WORD_1
	v_cvt_f32_f16_e32 v72, v61
	v_pk_add_f32 v[68:69], v[70:71], v[68:69]
	v_cvt_f32_f16_sdwa v71, v60 dst_sel:DWORD dst_unused:UNUSED_PAD src0_sel:WORD_1
	v_cvt_f32_f16_e32 v70, v60
	v_pk_fma_f32 v[68:69], v[72:73], s[0:1], v[68:69] op_sel_hi:[1,0,1]
	v_lshlrev_b32_e32 v72, 16, v54
	v_and_b32_e32 v73, 0xffff0000, v56
	v_pk_fma_f32 v[60:61], v[70:71], s[0:1], v[86:87] op_sel_hi:[1,0,1]
	v_lshlrev_b32_e32 v70, 16, v56
	v_and_b32_e32 v71, 0xffff0000, v54
	v_pk_mul_f32 v[72:73], v[16:17], v[72:73]
	v_lshlrev_b32_e32 v54, 16, v55
	v_pk_fma_f32 v[70:71], v[16:17], v[70:71], v[72:73] op_sel:[1,0,0] op_sel_hi:[0,1,1]
	v_lshlrev_b32_e32 v72, 16, v52
	v_and_b32_e32 v73, 0xffff0000, v52
	v_pk_add_f32 v[70:71], v[70:71], v[72:73]
	v_and_b32_e32 v73, 0xffff0000, v55
	v_and_b32_e32 v55, 0xffff0000, v57
	v_lshlrev_b32_e32 v72, 16, v57
	v_pk_mul_f32 v[54:55], v[16:17], v[54:55]
	v_lshlrev_b32_e32 v52, 16, v53
	v_pk_fma_f32 v[54:55], v[16:17], v[72:73], v[54:55] op_sel:[1,0,0] op_sel_hi:[0,1,1]
	v_and_b32_e32 v53, 0xffff0000, v53
	v_cvt_f32_f16_sdwa v57, v51 dst_sel:DWORD dst_unused:UNUSED_PAD src0_sel:WORD_1
	v_cvt_f32_f16_e32 v56, v51
	v_pk_add_f32 v[52:53], v[54:55], v[52:53]
	v_cvt_f32_f16_sdwa v55, v50 dst_sel:DWORD dst_unused:UNUSED_PAD src0_sel:WORD_1
	v_cvt_f32_f16_e32 v54, v50
	v_pk_fma_f32 v[52:53], v[56:57], s[0:1], v[52:53] op_sel_hi:[1,0,1]
	v_lshlrev_b32_e32 v56, 16, v46
	v_and_b32_e32 v57, 0xffff0000, v48
	v_pk_fma_f32 v[50:51], v[54:55], s[0:1], v[70:71] op_sel_hi:[1,0,1]
	v_lshlrev_b32_e32 v54, 16, v48
; __device__ __forceinline__ float h2f_(unsigned short b) { return (float)__builtin_bit_cast(_Float16, b); }
; __device__ __forceinline__ void ln_row_write(f32x4 (&v)[4], const float* g, const float* bta, float* of, bf16_t* ob, int lane, unsigned char* o8 = nullptr) {
;     float s = 0.f;
; #pragma unroll
;     for (int j = 0; j < 4; ++j) s += (v[j][0] + v[j][1]) + (v[j][2] + v[j][3]);
;     const float mean = wave_sum(s) * (1.0f / 1024.0f); float s2 = 0.f;
; #pragma unroll
;     for (int j = 0; j < 4; ++j) { v[j] = v[j] - mean; s2 += (v[j][0] * v[j][0] + v[j][1] * v[j][1]) + (v[j][2] * v[j][2] + v[j][3] * v[j][3]); }
;     const float rstd = rsqrtf(wave_sum(s2) * (1.0f / 1024.0f) + EPS);
; #pragma unroll
;     for (int j = 0; j < 4; ++j) { const f32x4 gg = *(const f32x4*)(g + 4 * lane + 256 * j), bb = *(const f32x4*)(bta + 4 * lane + 256 * j); v[j] = v[j] * rstd * gg + bb;
;         if (of) *(f32x4*)(of + 4 * lane + 256 * j) = v[j]; u32x2 w; w.x = cvt_pk_f16(v[j][0], v[j][1]); w.y = cvt_pk_f16(v[j][2], v[j][3]); *(u32x2*)(ob + 4 * lane + 256 * j) = w;
; template <bool MOE>
; __device__ __forceinline__ void ln2_phase(const Frame& F, int layer) {
;     ...
;                 for (int j = 0; j < 4; ++j) { const u32x2 x = nxr[s_][j], a = na[s_][j], c = nc[s_][j], pp = np_[s_][j];
;                     f32x4 f;
;                     f[0] = w0 * __uint_as_float(a.x << 16) + w1 * __uint_as_float(c.x << 16) + __uint_as_float(pp.x << 16);
;                     f[1] = w0 * __uint_as_float(a.x & 0xffff0000u) + w1 * __uint_as_float(c.x & 0xffff0000u) + __uint_as_float(pp.x & 0xffff0000u);
;                     f[2] = w0 * __uint_as_float(a.y << 16) + w1 * __uint_as_float(c.y << 16) + __uint_as_float(pp.y << 16);
;                     f[3] = w0 * __uint_as_float(a.y & 0xffff0000u) + w1 * __uint_as_float(c.y & 0xffff0000u) + __uint_as_float(pp.y & 0xffff0000u);
;                     v[s_][j] = (f32x4){h2f_((unsigned short)(x.x & 0xffffu)), h2f_((unsigned short)(x.x >> 16)), h2f_((unsigned short)(x.y & 0xffffu)), h2f_((unsigned short)(x.y >> 16))} * ALPHA + f; } }
	v_and_b32_e32 v55, 0xffff0000, v46
	v_pk_mul_f32 v[56:57], v[16:17], v[56:57]
	v_lshlrev_b32_e32 v46, 16, v47
	v_pk_fma_f32 v[54:55], v[16:17], v[54:55], v[56:57] op_sel:[1,0,0] op_sel_hi:[0,1,1]
	v_lshlrev_b32_e32 v56, 16, v44
	v_and_b32_e32 v57, 0xffff0000, v44
	v_pk_add_f32 v[54:55], v[54:55], v[56:57]
	v_and_b32_e32 v57, 0xffff0000, v47
	v_and_b32_e32 v47, 0xffff0000, v49
	v_lshlrev_b32_e32 v56, 16, v49
	v_pk_mul_f32 v[46:47], v[16:17], v[46:47]
	v_lshlrev_b32_e32 v44, 16, v45
	v_pk_fma_f32 v[16:17], v[16:17], v[56:57], v[46:47] op_sel:[1,0,0] op_sel_hi:[0,1,1]
	v_and_b32_e32 v45, 0xffff0000, v45
	v_pk_add_f32 v[16:17], v[16:17], v[44:45]
	v_cvt_f32_f16_sdwa v45, v32 dst_sel:DWORD dst_unused:UNUSED_PAD src0_sel:WORD_1
	v_cvt_f32_f16_e32 v44, v32
	v_cvt_f32_f16_sdwa v47, v33 dst_sel:DWORD dst_unused:UNUSED_PAD src0_sel:WORD_1
	v_cvt_f32_f16_e32 v46, v33
	v_pk_fma_f32 v[32:33], v[44:45], s[0:1], v[54:55] op_sel_hi:[1,0,1]
	v_cvt_pk_f16_f32 v44, v2, v3
	v_cvt_pk_f16_f32 v45, v4, v5
	global_store_dwordx2 v[38:39], v[44:45], off offset:1536
	v_mov_b32_e32 v38, v35
	v_cvt_pk_fp8_f32 v38, v2, v3
	v_pk_mov_b32 v[2:3], v[78:79], v[84:85] op_sel:[1,0]
	v_mov_b32_e32 v39, v69
	v_pk_fma_f32 v[16:17], v[46:47], s[0:1], v[16:17] op_sel_hi:[1,0,1]
	v_cvt_pk_fp8_f32 v38, v4, v5 op_sel:[0,0,1]
	v_mov_b32_e32 v4, v78
	v_mov_b32_e32 v5, v85
	v_pk_add_f32 v[2:3], v[2:3], v[4:5]
	global_store_dword v[140:141], v38, off offset:768
	v_pk_mov_b32 v[4:5], v[60:61], v[68:69] op_sel:[1,0]
	v_mov_b32_e32 v38, v60
	v_pk_add_f32 v[4:5], v[4:5], v[38:39]
	v_add_f32_e32 v2, v2, v3
	v_pk_add_f32 v[4:5], v[4:5], v[4:5] op_sel:[0,1] op_sel_hi:[1,0]
	v_add_f32_e32 v2, 0, v2
	v_add_f32_e32 v38, v50, v51
	v_add_f32_e32 v44, v52, v53
	v_mov_b32_e32 v3, v32
	v_mov_b32_e32 v5, v33
	v_mov_b32_e32 v39, v16
	v_mov_b32_e32 v45, v17
	v_pk_add_f32 v[2:3], v[2:3], v[4:5]
	v_pk_add_f32 v[4:5], v[38:39], v[44:45]
	s_lshl_b64 s[0:1], s[10:11], 12
	v_pk_add_f32 v[2:3], v[2:3], v[4:5]
	s_add_u32 s4, s34, s0
	v_add_f32_e32 v2, v2, v3
	ds_bpermute_b32 v3, v34, v2
	s_addc_u32 s5, s35, s1
	s_and_b64 s[0:1], s[8:9], exec
	s_cselect_b32 s1, s5, 0
	s_cselect_b32 s0, s4, 0
	s_waitcnt lgkmcnt(0)
	v_add_f32_e32 v2, v2, v3
	ds_bpermute_b32 v3, v164, v2
	s_cmp_lg_u64 s[0:1], 0
	s_cselect_b64 s[4:5], -1, 0
	s_cmp_eq_u64 s[0:1], 0
	s_waitcnt lgkmcnt(0)
	v_add_f32_e32 v2, v2, v3
	ds_bpermute_b32 v3, v165, v2
	s_waitcnt lgkmcnt(0)
	v_add_f32_e32 v2, v2, v3
	ds_bpermute_b32 v3, v166, v2
	s_waitcnt lgkmcnt(0)
	v_add_f32_e32 v2, v2, v3
	ds_bpermute_b32 v3, v167, v2
	s_waitcnt lgkmcnt(0)
	v_add_f32_e32 v2, v2, v3
	ds_bpermute_b32 v3, v168, v2
	s_waitcnt lgkmcnt(0)
	v_add_f32_e32 v46, v2, v3
	v_fmamk_f32 v79, v46, 0xba800000, v79
	v_fmac_f32_e32 v78, 0xba800000, v46
	v_fmamk_f32 v85, v46, 0xba800000, v85
	v_fmac_f32_e32 v84, 0xba800000, v46
	v_pk_mul_f32 v[2:3], v[84:85], v[84:85]
	v_pk_mul_f32 v[4:5], v[78:79], v[78:79]
	v_fmamk_f32 v69, v46, 0xba800000, v69
	v_pk_mov_b32 v[38:39], v[4:5], v[2:3] op_sel:[1,0]
	v_mov_b32_e32 v5, v3
	v_pk_add_f32 v[2:3], v[38:39], v[4:5]
	v_fmac_f32_e32 v68, 0xba800000, v46
	v_fmamk_f32 v61, v46, 0xba800000, v61
	v_fmac_f32_e32 v60, 0xba800000, v46
	v_pk_add_f32 v[2:3], v[2:3], v[2:3] op_sel_hi:[0,1]
	v_pk_mul_f32 v[4:5], v[68:69], v[68:69]
	v_pk_mul_f32 v[38:39], v[60:61], v[60:61]
	v_fmac_f32_e32 v50, 0xba800000, v46
	v_pk_mov_b32 v[44:45], v[38:39], v[4:5] op_sel:[1,0]
	v_mov_b32_e32 v39, v5
	v_fmac_f32_e32 v52, 0xba800000, v46
	v_fmamk_f32 v51, v46, 0xba800000, v51
	v_mul_f32_e32 v2, v50, v50
	v_pk_add_f32 v[4:5], v[44:45], v[38:39]
	v_fmamk_f32 v53, v46, 0xba800000, v53
	v_pk_fma_f32 v[38:39], v[50:51], v[50:51], v[2:3] op_sel_hi:[1,1,0]
	v_mul_f32_e32 v2, v52, v52
	v_pk_add_f32 v[4:5], v[4:5], v[4:5] op_sel_hi:[0,1]
	v_pk_fma_f32 v[44:45], v[52:53], v[52:53], v[2:3] op_sel_hi:[1,1,0]
	v_fmamk_f32 v17, v46, 0xba800000, v17
	v_fmac_f32_e32 v16, 0xba800000, v46
	v_fmamk_f32 v33, v46, 0xba800000, v33
	v_fmac_f32_e32 v32, 0xba800000, v46
	v_mul_f32_e32 v38, v32, v32
	v_mul_f32_e32 v44, v33, v33
	v_mul_f32_e32 v2, v16, v16
	v_mul_f32_e32 v4, v17, v17
	v_pk_add_f32 v[38:39], v[38:39], v[44:45]
	v_pk_add_f32 v[2:3], v[2:3], v[4:5]
	s_nop 0
	v_pk_add_f32 v[2:3], v[38:39], v[2:3]
	v_lshl_add_u64 v[38:39], v[6:7], 2, s[0:1]
	v_add_f32_e32 v2, v2, v3
	ds_bpermute_b32 v3, v34, v2
	s_waitcnt lgkmcnt(0)
	v_add_f32_e32 v2, v2, v3
	ds_bpermute_b32 v3, v164, v2
	s_waitcnt lgkmcnt(0)
	v_add_f32_e32 v2, v2, v3
	ds_bpermute_b32 v3, v165, v2
	s_waitcnt lgkmcnt(0)
	v_add_f32_e32 v2, v2, v3
	ds_bpermute_b32 v3, v166, v2
	s_waitcnt lgkmcnt(0)
	v_add_f32_e32 v2, v2, v3
	ds_bpermute_b32 v3, v167, v2
	s_waitcnt lgkmcnt(0)
	v_add_f32_e32 v2, v2, v3
	ds_bpermute_b32 v3, v168, v2
	s_waitcnt lgkmcnt(0)
	v_add_f32_e32 v2, v2, v3
	v_fmamk_f32 v2, v2, 0x3a800000, v230
	v_cmp_gt_f32_e32 vcc, s97, v2
	v_mul_f32_e32 v3, 0x4b800000, v2
	s_nop 0
	v_cndmask_b32_e32 v2, v2, v3, vcc
	v_rsq_f32_e32 v2, v2
	s_nop 0
	v_mul_f32_e32 v3, 0x45800000, v2
	v_cndmask_b32_e32 v44, v2, v3, vcc
	v_pk_mul_f32 v[54:55], v[78:79], v[44:45] op_sel_hi:[1,0]
	v_pk_mul_f32 v[56:57], v[84:85], v[44:45] op_sel_hi:[1,0]
	v_pk_fma_f32 v[2:3], v[176:177], v[54:55], v[192:193]
	v_pk_fma_f32 v[4:5], v[178:179], v[56:57], v[194:195]
	s_cbranch_scc1 .LBB0_2055
	global_store_dwordx4 v[38:39], v[2:5], off
; __device__ __forceinline__ float h2f_(unsigned short b) { return (float)__builtin_bit_cast(_Float16, b); }
; __device__ __forceinline__ unsigned cvt4_fp8(float a, float b, float c, float d) { int w = 0; w = __builtin_amdgcn_cvt_pk_fp8_f32(a, b, w, false); w = __builtin_amdgcn_cvt_pk_fp8_f32(c, d, w, true); return (unsigned)w; }
; __device__ __forceinline__ void ln_row_write(f32x4 (&v)[4], const float* g, const float* bta, float* of, bf16_t* ob, int lane, unsigned char* o8 = nullptr) {
;     ...
; #pragma unroll
;     for (int j = 0; j < 4; ++j) { const f32x4 gg = *(const f32x4*)(g + 4 * lane + 256 * j), bb = *(const f32x4*)(bta + 4 * lane + 256 * j); v[j] = v[j] * rstd * gg + bb;
;         if (of) *(f32x4*)(of + 4 * lane + 256 * j) = v[j]; u32x2 w; w.x = cvt_pk_f16(v[j][0], v[j][1]); w.y = cvt_pk_f16(v[j][2], v[j][3]); *(u32x2*)(ob + 4 * lane + 256 * j) = w;
;         if (o8) *(unsigned*)(o8 + 4 * lane + 256 * j) = cvt4_fp8(v[j][0], v[j][1], v[j][2], v[j][3]); }
; template <bool MOE>
; __device__ __forceinline__ void ln2_phase(const Frame& F, int layer) {
;     ...
;                 for (int j = 0; j < 4; ++j) { const u32x2 x = nxr[s_][j], a = na[s_][j], c = nc[s_][j], pp = np_[s_][j];
;                     f32x4 f;
;                     f[0] = w0 * __uint_as_float(a.x << 16) + w1 * __uint_as_float(c.x << 16) + __uint_as_float(pp.x << 16);
;                     f[1] = w0 * __uint_as_float(a.x & 0xffff0000u) + w1 * __uint_as_float(c.x & 0xffff0000u) + __uint_as_float(pp.x & 0xffff0000u);
;                     f[2] = w0 * __uint_as_float(a.y << 16) + w1 * __uint_as_float(c.y << 16) + __uint_as_float(pp.y << 16);
;                     f[3] = w0 * __uint_as_float(a.y & 0xffff0000u) + w1 * __uint_as_float(c.y & 0xffff0000u) + __uint_as_float(pp.y & 0xffff0000u);
;                     v[s_][j] = (f32x4){h2f_((unsigned short)(x.x & 0xffffu)), h2f_((unsigned short)(x.x >> 16)), h2f_((unsigned short)(x.y & 0xffffu)), h2f_((unsigned short)(x.y >> 16))} * ALPHA + f; } }
.LBB0_2055:
	v_cvt_pk_f16_f32 v48, v2, v3
	v_cvt_pk_f16_f32 v49, v4, v5
	global_store_dwordx2 v[36:37], v[48:49], off
	v_mov_b32_e32 v48, v35
	v_cvt_pk_fp8_f32 v48, v2, v3
	s_lshl_b64 s[0:1], s[10:11], 10
	s_add_u32 s0, s20, s0
	s_addc_u32 s1, s21, s1
	v_cvt_pk_fp8_f32 v48, v4, v5 op_sel:[0,0,1]
	v_lshl_add_u64 v[46:47], s[0:1], 0, v[6:7]
	v_mov_b32_e32 v45, v44
	v_mov_b32_e32 v49, v44
	global_store_dword v[46:47], v48, off
	v_mov_b32_e32 v48, v44
	v_pk_mul_f32 v[60:61], v[60:61], v[44:45]
	v_pk_mul_f32 v[68:69], v[68:69], v[48:49]
	s_andn2_b64 vcc, exec, s[4:5]
	v_pk_fma_f32 v[2:3], v[60:61], v[180:181], v[206:207]
	v_cndmask_b32_e64 v54, 0, 1, s[4:5]
	v_pk_fma_f32 v[4:5], v[68:69], v[182:183], v[208:209]
	v_cmp_ne_u32_e64 s[0:1], 1, v54
	s_cbranch_vccnz .LBB0_2057
	global_store_dwordx4 v[38:39], v[2:5], off offset:1024
.LBB0_2057:
	v_mov_b32_e32 v54, v35
	v_cvt_pk_fp8_f32 v54, v2, v3
	v_cvt_pk_f16_f32 v2, v2, v3
	v_cvt_pk_f16_f32 v3, v4, v5
	v_pk_mul_f32 v[48:49], v[52:53], v[48:49]
	v_cvt_pk_fp8_f32 v54, v4, v5 op_sel:[0,0,1]
	v_pk_mul_f32 v[50:51], v[50:51], v[44:45]
	s_and_b64 vcc, exec, s[0:1]
	global_store_dwordx2 v[36:37], v[2:3], off offset:512
	global_store_dword v[46:47], v54, off offset:256
	s_nop 0
	v_pk_fma_f32 v[4:5], v[48:49], v[186:187], v[212:213]
	v_pk_fma_f32 v[2:3], v[50:51], v[184:185], v[210:211]
	s_cbranch_vccnz .LBB0_2059
	global_store_dwordx4 v[38:39], v[2:5], off offset:2048
.LBB0_2059:
	v_mov_b32_e32 v48, v35
	v_cvt_pk_fp8_f32 v48, v2, v3
	v_cvt_pk_f16_f32 v2, v2, v3
	v_cvt_pk_f16_f32 v3, v4, v5
	v_mov_b32_e32 v52, v44
	v_cvt_pk_fp8_f32 v48, v4, v5 op_sel:[0,0,1]
	v_mov_b32_e32 v53, v44
	v_pk_mul_f32 v[32:33], v[32:33], v[44:45]
	global_store_dwordx2 v[36:37], v[2:3], off offset:1024
	global_store_dword v[46:47], v48, off offset:512
	s_nop 0
	v_pk_mul_f32 v[16:17], v[16:17], v[52:53]
	s_and_b64 vcc, exec, s[0:1]
	s_waitcnt vmcnt(0)
	v_pk_fma_f32 v[4:5], v[16:17], v[190:191], v[216:217]
	v_pk_fma_f32 v[2:3], v[32:33], v[188:189], v[214:215]
	s_cbranch_vccnz .LBB0_2061
	global_store_dwordx4 v[38:39], v[2:5], off offset:3072
.LBB0_2061:
	v_cvt_pk_f16_f32 v16, v2, v3
	v_cvt_pk_f16_f32 v17, v4, v5
	global_store_dwordx2 v[36:37], v[16:17], off offset:1536
	v_mov_b32_e32 v16, v35
	v_cvt_pk_fp8_f32 v16, v2, v3
	v_lshlrev_b32_e32 v2, 16, v122
	v_and_b32_e32 v3, 0xffff0000, v120
	v_and_b32_e32 v17, 0xffff0000, v123
	v_cvt_pk_fp8_f32 v16, v4, v5 op_sel:[0,0,1]
	v_lshlrev_b32_e32 v4, 16, v120
	v_and_b32_e32 v5, 0xffff0000, v122
	v_pk_mul_f32 v[4:5], v[10:11], v[4:5]
	global_store_dword v[46:47], v16, off offset:768
	v_pk_fma_f32 v[2:3], v[10:11], v[2:3], v[4:5] op_sel:[1,0,0] op_sel_hi:[0,1,1]
	v_lshlrev_b32_e32 v4, 16, v118
	v_and_b32_e32 v5, 0xffff0000, v118
	v_lshlrev_b32_e32 v16, 16, v121
	v_pk_add_f32 v[2:3], v[2:3], v[4:5]
	v_lshlrev_b32_e32 v4, 16, v123
	v_and_b32_e32 v5, 0xffff0000, v121
	v_pk_mul_f32 v[16:17], v[10:11], v[16:17]
	v_cvt_f32_f16_sdwa v33, v117 dst_sel:DWORD dst_unused:UNUSED_PAD src0_sel:WORD_1
	v_pk_fma_f32 v[4:5], v[10:11], v[4:5], v[16:17] op_sel:[1,0,0] op_sel_hi:[0,1,1]
	v_lshlrev_b32_e32 v16, 16, v119
	v_and_b32_e32 v17, 0xffff0000, v119
	v_cvt_f32_f16_e32 v32, v117
	v_pk_add_f32 v[4:5], v[4:5], v[16:17]
	v_cvt_f32_f16_sdwa v17, v116 dst_sel:DWORD dst_unused:UNUSED_PAD src0_sel:WORD_1
	v_cvt_f32_f16_e32 v16, v116
	s_mov_b32 s0, 0x3fd744fd
	v_pk_fma_f32 v[4:5], v[32:33], s[0:1], v[4:5] op_sel_hi:[1,0,1]
	v_lshlrev_b32_e32 v32, 16, v112
	v_and_b32_e32 v33, 0xffff0000, v114
	v_pk_fma_f32 v[2:3], v[16:17], s[0:1], v[2:3] op_sel_hi:[1,0,1]
	v_lshlrev_b32_e32 v16, 16, v114
	v_and_b32_e32 v17, 0xffff0000, v112
	v_pk_mul_f32 v[32:33], v[10:11], v[32:33]
	v_lshlrev_b32_e32 v36, 16, v113
	v_pk_fma_f32 v[16:17], v[10:11], v[16:17], v[32:33] op_sel:[1,0,0] op_sel_hi:[0,1,1]
	v_lshlrev_b32_e32 v32, 16, v110
	v_and_b32_e32 v33, 0xffff0000, v110
	v_and_b32_e32 v37, 0xffff0000, v115
	v_pk_add_f32 v[16:17], v[16:17], v[32:33]
	v_lshlrev_b32_e32 v32, 16, v115
	v_and_b32_e32 v33, 0xffff0000, v113
	v_pk_mul_f32 v[36:37], v[10:11], v[36:37]
	v_cvt_f32_f16_sdwa v45, v109 dst_sel:DWORD dst_unused:UNUSED_PAD src0_sel:WORD_1
	v_pk_fma_f32 v[32:33], v[10:11], v[32:33], v[36:37] op_sel:[1,0,0] op_sel_hi:[0,1,1]
	v_lshlrev_b32_e32 v36, 16, v111
	v_and_b32_e32 v37, 0xffff0000, v111
	v_cvt_f32_f16_e32 v44, v109
	v_pk_add_f32 v[32:33], v[32:33], v[36:37]
	v_cvt_f32_f16_sdwa v37, v108 dst_sel:DWORD dst_unused:UNUSED_PAD src0_sel:WORD_1
	v_cvt_f32_f16_e32 v36, v108
	v_pk_fma_f32 v[44:45], v[44:45], s[0:1], v[32:33] op_sel_hi:[1,0,1]
	v_lshlrev_b32_e32 v32, 16, v104
	v_and_b32_e32 v33, 0xffff0000, v106
	v_pk_fma_f32 v[38:39], v[36:37], s[0:1], v[16:17] op_sel_hi:[1,0,1]
	v_lshlrev_b32_e32 v16, 16, v106
	v_and_b32_e32 v17, 0xffff0000, v104
	v_pk_mul_f32 v[32:33], v[10:11], v[32:33]
	v_lshlrev_b32_e32 v36, 16, v105
	v_pk_fma_f32 v[16:17], v[10:11], v[16:17], v[32:33] op_sel:[1,0,0] op_sel_hi:[0,1,1]
	v_lshlrev_b32_e32 v32, 16, v102
	v_and_b32_e32 v33, 0xffff0000, v102
	v_and_b32_e32 v37, 0xffff0000, v107
	v_pk_add_f32 v[16:17], v[16:17], v[32:33]
	v_lshlrev_b32_e32 v32, 16, v107
	v_and_b32_e32 v33, 0xffff0000, v105
	v_pk_mul_f32 v[36:37], v[10:11], v[36:37]
	v_cvt_f32_f16_sdwa v47, v97 dst_sel:DWORD dst_unused:UNUSED_PAD src0_sel:WORD_1
	v_pk_fma_f32 v[32:33], v[10:11], v[32:33], v[36:37] op_sel:[1,0,0] op_sel_hi:[0,1,1]
	v_lshlrev_b32_e32 v36, 16, v103
	v_and_b32_e32 v37, 0xffff0000, v103
	v_cvt_f32_f16_e32 v46, v97
	v_pk_add_f32 v[32:33], v[32:33], v[36:37]
	v_cvt_f32_f16_sdwa v37, v96 dst_sel:DWORD dst_unused:UNUSED_PAD src0_sel:WORD_1
	v_cvt_f32_f16_e32 v36, v96
	v_pk_fma_f32 v[32:33], v[46:47], s[0:1], v[32:33] op_sel_hi:[1,0,1]
; __device__ __forceinline__ float h2f_(unsigned short b) { return (float)__builtin_bit_cast(_Float16, b); }
; __device__ __forceinline__ void ln_row_write(f32x4 (&v)[4], const float* g, const float* bta, float* of, bf16_t* ob, int lane, unsigned char* o8 = nullptr) {
;     float s = 0.f;
; #pragma unroll
;     for (int j = 0; j < 4; ++j) s += (v[j][0] + v[j][1]) + (v[j][2] + v[j][3]);
;     const float mean = wave_sum(s) * (1.0f / 1024.0f); float s2 = 0.f;
; #pragma unroll
;     for (int j = 0; j < 4; ++j) { v[j] = v[j] - mean; s2 += (v[j][0] * v[j][0] + v[j][1] * v[j][1]) + (v[j][2] * v[j][2] + v[j][3] * v[j][3]); }
;     const float rstd = rsqrtf(wave_sum(s2) * (1.0f / 1024.0f) + EPS);
; #pragma unroll
;     for (int j = 0; j < 4; ++j) { const f32x4 gg = *(const f32x4*)(g + 4 * lane + 256 * j), bb = *(const f32x4*)(bta + 4 * lane + 256 * j); v[j] = v[j] * rstd * gg + bb;
;         if (of) *(f32x4*)(of + 4 * lane + 256 * j) = v[j]; u32x2 w; w.x = cvt_pk_f16(v[j][0], v[j][1]); w.y = cvt_pk_f16(v[j][2], v[j][3]); *(u32x2*)(ob + 4 * lane + 256 * j) = w;
; template <bool MOE>
; __device__ __forceinline__ void ln2_phase(const Frame& F, int layer) {
;     ...
;                 for (int j = 0; j < 4; ++j) { const u32x2 x = nxr[s_][j], a = na[s_][j], c = nc[s_][j], pp = np_[s_][j];
;                     f32x4 f;
;                     f[0] = w0 * __uint_as_float(a.x << 16) + w1 * __uint_as_float(c.x << 16) + __uint_as_float(pp.x << 16);
;                     f[1] = w0 * __uint_as_float(a.x & 0xffff0000u) + w1 * __uint_as_float(c.x & 0xffff0000u) + __uint_as_float(pp.x & 0xffff0000u);
;                     f[2] = w0 * __uint_as_float(a.y << 16) + w1 * __uint_as_float(c.y << 16) + __uint_as_float(pp.y << 16);
;                     f[3] = w0 * __uint_as_float(a.y & 0xffff0000u) + w1 * __uint_as_float(c.y & 0xffff0000u) + __uint_as_float(pp.y & 0xffff0000u);
;                     v[s_][j] = (f32x4){h2f_((unsigned short)(x.x & 0xffffu)), h2f_((unsigned short)(x.x >> 16)), h2f_((unsigned short)(x.y & 0xffffu)), h2f_((unsigned short)(x.y >> 16))} * ALPHA + f; } }
	v_lshlrev_b32_e32 v46, 16, v94
	v_and_b32_e32 v47, 0xffff0000, v98
	v_pk_fma_f32 v[16:17], v[36:37], s[0:1], v[16:17] op_sel_hi:[1,0,1]
	v_lshlrev_b32_e32 v36, 16, v98
	v_and_b32_e32 v37, 0xffff0000, v94
	v_pk_mul_f32 v[46:47], v[10:11], v[46:47]
	v_lshlrev_b32_e32 v48, 16, v95
	v_pk_fma_f32 v[36:37], v[10:11], v[36:37], v[46:47] op_sel:[1,0,0] op_sel_hi:[0,1,1]
	v_lshlrev_b32_e32 v46, 16, v100
	v_and_b32_e32 v47, 0xffff0000, v100
	v_and_b32_e32 v49, 0xffff0000, v99
	v_pk_add_f32 v[36:37], v[36:37], v[46:47]
	v_lshlrev_b32_e32 v46, 16, v99
	v_and_b32_e32 v47, 0xffff0000, v95
	v_pk_mul_f32 v[48:49], v[10:11], v[48:49]
	v_mov_b32_e32 v50, v38
	v_pk_fma_f32 v[10:11], v[10:11], v[46:47], v[48:49] op_sel:[1,0,0] op_sel_hi:[0,1,1]
	v_lshlrev_b32_e32 v46, 16, v101
	v_and_b32_e32 v47, 0xffff0000, v101
	v_pk_add_f32 v[10:11], v[10:11], v[46:47]
	v_cvt_f32_f16_sdwa v47, v92 dst_sel:DWORD dst_unused:UNUSED_PAD src0_sel:WORD_1
	v_cvt_f32_f16_e32 v46, v92
	v_cvt_f32_f16_sdwa v49, v93 dst_sel:DWORD dst_unused:UNUSED_PAD src0_sel:WORD_1
	v_cvt_f32_f16_e32 v48, v93
	v_mov_b32_e32 v51, v45
	v_pk_fma_f32 v[36:37], v[46:47], s[0:1], v[36:37] op_sel_hi:[1,0,1]
	v_pk_mov_b32 v[46:47], v[2:3], v[4:5] op_sel:[1,0]
	v_pk_fma_f32 v[10:11], v[48:49], s[0:1], v[10:11] op_sel_hi:[1,0,1]
	v_mov_b32_e32 v48, v2
	v_mov_b32_e32 v49, v5
	v_pk_add_f32 v[46:47], v[46:47], v[48:49]
	v_pk_mov_b32 v[48:49], v[38:39], v[44:45] op_sel:[1,0]
	v_add_f32_e32 v46, v46, v47
	v_pk_add_f32 v[48:49], v[48:49], v[50:51]
	v_add_f32_e32 v46, 0, v46
	v_pk_add_f32 v[48:49], v[48:49], v[48:49] op_sel:[0,1] op_sel_hi:[1,0]
	v_add_f32_e32 v50, v16, v17
	v_add_f32_e32 v52, v32, v33
	v_mov_b32_e32 v47, v36
	v_mov_b32_e32 v49, v37
	v_mov_b32_e32 v51, v10
	v_mov_b32_e32 v53, v11
	v_pk_add_f32 v[46:47], v[46:47], v[48:49]
	v_pk_add_f32 v[48:49], v[50:51], v[52:53]
	s_lshl_b64 s[0:1], s[6:7], 12
	v_pk_add_f32 v[46:47], v[46:47], v[48:49]
	s_add_u32 s4, s34, s0
	v_add_f32_e32 v46, v46, v47
	ds_bpermute_b32 v47, v34, v46
	s_addc_u32 s5, s35, s1
	s_and_b64 s[0:1], s[8:9], exec
	s_cselect_b32 s1, s5, 0
	s_cselect_b32 s0, s4, 0
	s_waitcnt lgkmcnt(0)
	v_add_f32_e32 v46, v46, v47
	ds_bpermute_b32 v47, v164, v46
	s_cmp_lg_u64 s[0:1], 0
	s_cselect_b64 s[4:5], -1, 0
	s_cmp_eq_u64 s[0:1], 0
	s_waitcnt lgkmcnt(0)
	v_add_f32_e32 v46, v46, v47
	ds_bpermute_b32 v47, v165, v46
	s_waitcnt lgkmcnt(0)
	v_add_f32_e32 v46, v46, v47
	ds_bpermute_b32 v47, v166, v46
	s_waitcnt lgkmcnt(0)
	v_add_f32_e32 v46, v46, v47
	ds_bpermute_b32 v47, v167, v46
	s_waitcnt lgkmcnt(0)
	v_add_f32_e32 v46, v46, v47
	ds_bpermute_b32 v47, v168, v46
	s_waitcnt lgkmcnt(0)
	v_add_f32_e32 v54, v46, v47
	v_fmamk_f32 v3, v54, 0xba800000, v3
	v_fmac_f32_e32 v2, 0xba800000, v54
	v_fmamk_f32 v5, v54, 0xba800000, v5
	v_fmac_f32_e32 v4, 0xba800000, v54
	v_pk_mul_f32 v[46:47], v[4:5], v[4:5]
	v_pk_mul_f32 v[48:49], v[2:3], v[2:3]
	v_fmamk_f32 v45, v54, 0xba800000, v45
	v_pk_mov_b32 v[50:51], v[48:49], v[46:47] op_sel:[1,0]
	v_mov_b32_e32 v49, v47
	v_pk_add_f32 v[46:47], v[50:51], v[48:49]
	v_fmac_f32_e32 v44, 0xba800000, v54
	v_fmamk_f32 v39, v54, 0xba800000, v39
	v_fmac_f32_e32 v38, 0xba800000, v54
	v_pk_add_f32 v[46:47], v[46:47], v[46:47] op_sel_hi:[0,1]
	v_pk_mul_f32 v[48:49], v[44:45], v[44:45]
	v_pk_mul_f32 v[50:51], v[38:39], v[38:39]
	v_fmac_f32_e32 v16, 0xba800000, v54
	v_pk_mov_b32 v[52:53], v[50:51], v[48:49] op_sel:[1,0]
	v_mov_b32_e32 v51, v49
	v_fmac_f32_e32 v32, 0xba800000, v54
	v_fmamk_f32 v17, v54, 0xba800000, v17
	v_mul_f32_e32 v46, v16, v16
	v_pk_add_f32 v[48:49], v[52:53], v[50:51]
	v_fmamk_f32 v33, v54, 0xba800000, v33
	v_pk_fma_f32 v[50:51], v[16:17], v[16:17], v[46:47] op_sel_hi:[1,1,0]
	v_mul_f32_e32 v46, v32, v32
	v_pk_add_f32 v[48:49], v[48:49], v[48:49] op_sel_hi:[0,1]
	v_pk_fma_f32 v[52:53], v[32:33], v[32:33], v[46:47] op_sel_hi:[1,1,0]
	v_fmamk_f32 v11, v54, 0xba800000, v11
	v_fmac_f32_e32 v10, 0xba800000, v54
	v_fmamk_f32 v37, v54, 0xba800000, v37
	v_fmac_f32_e32 v36, 0xba800000, v54
	v_mul_f32_e32 v50, v36, v36
	v_mul_f32_e32 v52, v37, v37
	v_mul_f32_e32 v46, v10, v10
	v_mul_f32_e32 v48, v11, v11
	v_pk_add_f32 v[50:51], v[50:51], v[52:53]
	v_pk_add_f32 v[46:47], v[46:47], v[48:49]
	s_nop 0
	v_pk_add_f32 v[46:47], v[50:51], v[46:47]
	v_add_f32_e32 v46, v46, v47
	ds_bpermute_b32 v47, v34, v46
	s_waitcnt lgkmcnt(0)
	v_add_f32_e32 v46, v46, v47
	ds_bpermute_b32 v47, v164, v46
	s_waitcnt lgkmcnt(0)
	v_add_f32_e32 v46, v46, v47
	ds_bpermute_b32 v47, v165, v46
	s_waitcnt lgkmcnt(0)
	v_add_f32_e32 v46, v46, v47
	ds_bpermute_b32 v47, v166, v46
	s_waitcnt lgkmcnt(0)
	v_add_f32_e32 v46, v46, v47
	ds_bpermute_b32 v47, v167, v46
	s_waitcnt lgkmcnt(0)
	v_add_f32_e32 v46, v46, v47
	ds_bpermute_b32 v47, v168, v46
	s_waitcnt lgkmcnt(0)
	v_add_f32_e32 v46, v46, v47
	v_fmamk_f32 v46, v46, 0x3a800000, v230
	v_cmp_gt_f32_e32 vcc, s97, v46
	v_mul_f32_e32 v47, 0x4b800000, v46
	s_nop 0
	v_cndmask_b32_e32 v46, v46, v47, vcc
	v_rsq_f32_e32 v46, v46
	s_nop 0
	v_mul_f32_e32 v47, 0x45800000, v46
	v_cndmask_b32_e32 v48, v46, v47, vcc
	v_pk_mul_f32 v[2:3], v[2:3], v[48:49] op_sel_hi:[1,0]
	v_pk_mul_f32 v[4:5], v[4:5], v[48:49] op_sel_hi:[1,0]
	v_lshl_add_u64 v[46:47], v[6:7], 2, s[0:1]
	v_pk_fma_f32 v[4:5], v[178:179], v[4:5], v[194:195]
	v_pk_fma_f32 v[2:3], v[176:177], v[2:3], v[192:193]
	s_cbranch_scc1 .LBB0_2063
	global_store_dwordx4 v[46:47], v[2:5], off
; __device__ __forceinline__ float h2f_(unsigned short b) { return (float)__builtin_bit_cast(_Float16, b); }
; __device__ __forceinline__ unsigned cvt4_fp8(float a, float b, float c, float d) { int w = 0; w = __builtin_amdgcn_cvt_pk_fp8_f32(a, b, w, false); w = __builtin_amdgcn_cvt_pk_fp8_f32(c, d, w, true); return (unsigned)w; }
; __device__ __forceinline__ void ln_row_write(f32x4 (&v)[4], const float* g, const float* bta, float* of, bf16_t* ob, int lane, unsigned char* o8 = nullptr) {
;     ...
; #pragma unroll
;     for (int j = 0; j < 4; ++j) { const f32x4 gg = *(const f32x4*)(g + 4 * lane + 256 * j), bb = *(const f32x4*)(bta + 4 * lane + 256 * j); v[j] = v[j] * rstd * gg + bb;
;         if (of) *(f32x4*)(of + 4 * lane + 256 * j) = v[j]; u32x2 w; w.x = cvt_pk_f16(v[j][0], v[j][1]); w.y = cvt_pk_f16(v[j][2], v[j][3]); *(u32x2*)(ob + 4 * lane + 256 * j) = w;
;         if (o8) *(unsigned*)(o8 + 4 * lane + 256 * j) = cvt4_fp8(v[j][0], v[j][1], v[j][2], v[j][3]); }
; template <bool MOE>
; __device__ __forceinline__ void ln2_phase(const Frame& F, int layer) {
;     ...
;                 for (int j = 0; j < 4; ++j) { const u32x2 x = nxr[s_][j], a = na[s_][j], c = nc[s_][j], pp = np_[s_][j];
;                     f32x4 f;
;                     f[0] = w0 * __uint_as_float(a.x << 16) + w1 * __uint_as_float(c.x << 16) + __uint_as_float(pp.x << 16);
;                     f[1] = w0 * __uint_as_float(a.x & 0xffff0000u) + w1 * __uint_as_float(c.x & 0xffff0000u) + __uint_as_float(pp.x & 0xffff0000u);
;                     f[2] = w0 * __uint_as_float(a.y << 16) + w1 * __uint_as_float(c.y << 16) + __uint_as_float(pp.y << 16);
;                     f[3] = w0 * __uint_as_float(a.y & 0xffff0000u) + w1 * __uint_as_float(c.y & 0xffff0000u) + __uint_as_float(pp.y & 0xffff0000u);
;                     v[s_][j] = (f32x4){h2f_((unsigned short)(x.x & 0xffffu)), h2f_((unsigned short)(x.x >> 16)), h2f_((unsigned short)(x.y & 0xffffu)), h2f_((unsigned short)(x.y >> 16))} * ALPHA + f; } }
.LBB0_2063:
	v_cvt_pk_f16_f32 v52, v2, v3
	v_cvt_pk_f16_f32 v53, v4, v5
	global_store_dwordx2 v[22:23], v[52:53], off
	v_mov_b32_e32 v52, v35
	v_cvt_pk_fp8_f32 v52, v2, v3
	s_lshl_b64 s[0:1], s[6:7], 10
	s_add_u32 s0, s20, s0
	s_addc_u32 s1, s21, s1
	v_cvt_pk_fp8_f32 v52, v4, v5 op_sel:[0,0,1]
	v_lshl_add_u64 v[50:51], s[0:1], 0, v[6:7]
	v_mov_b32_e32 v49, v48
	v_mov_b32_e32 v53, v48
	global_store_dword v[50:51], v52, off
	v_mov_b32_e32 v52, v48
	v_pk_mul_f32 v[38:39], v[38:39], v[48:49]
	v_pk_mul_f32 v[44:45], v[44:45], v[52:53]
	s_andn2_b64 vcc, exec, s[4:5]
	v_pk_fma_f32 v[2:3], v[38:39], v[180:181], v[206:207]
	v_cndmask_b32_e64 v38, 0, 1, s[4:5]
	v_pk_fma_f32 v[4:5], v[44:45], v[182:183], v[208:209]
	v_cmp_ne_u32_e64 s[0:1], 1, v38
	s_cbranch_vccnz .LBB0_2065
	global_store_dwordx4 v[46:47], v[2:5], off offset:1024
.LBB0_2065:
	v_mov_b32_e32 v38, v35
	v_cvt_pk_fp8_f32 v38, v2, v3
	v_cvt_pk_f16_f32 v2, v2, v3
	v_cvt_pk_f16_f32 v3, v4, v5
	v_pk_mul_f32 v[32:33], v[32:33], v[52:53]
	v_cvt_pk_fp8_f32 v38, v4, v5 op_sel:[0,0,1]
	v_pk_mul_f32 v[16:17], v[16:17], v[48:49]
	s_and_b64 vcc, exec, s[0:1]
	global_store_dwordx2 v[22:23], v[2:3], off offset:512
	global_store_dword v[50:51], v38, off offset:256
	s_nop 0
	v_pk_fma_f32 v[4:5], v[32:33], v[186:187], v[212:213]
	v_pk_fma_f32 v[2:3], v[16:17], v[184:185], v[210:211]
	s_cbranch_vccnz .LBB0_2067
	global_store_dwordx4 v[46:47], v[2:5], off offset:2048
.LBB0_2067:
	v_mov_b32_e32 v16, v35
	v_cvt_pk_fp8_f32 v16, v2, v3
	v_cvt_pk_f16_f32 v2, v2, v3
	v_cvt_pk_f16_f32 v3, v4, v5
	v_mov_b32_e32 v17, v48
	v_cvt_pk_fp8_f32 v16, v4, v5 op_sel:[0,0,1]
	v_pk_mul_f32 v[32:33], v[36:37], v[48:49]
	s_and_b64 vcc, exec, s[0:1]
	global_store_dwordx2 v[22:23], v[2:3], off offset:1024
	global_store_dword v[50:51], v16, off offset:512
	s_nop 0
	v_mov_b32_e32 v16, v48
	v_pk_mul_f32 v[10:11], v[10:11], v[16:17]
	v_pk_fma_f32 v[2:3], v[32:33], v[188:189], v[214:215]
	v_pk_fma_f32 v[4:5], v[10:11], v[190:191], v[216:217]
	s_cbranch_vccnz .LBB0_2069
	global_store_dwordx4 v[46:47], v[2:5], off offset:3072
.LBB0_2069:
	v_lshlrev_b32_e32 v16, 16, v82
	v_and_b32_e32 v17, 0xffff0000, v90
	v_lshlrev_b32_e32 v10, 16, v90
	v_and_b32_e32 v11, 0xffff0000, v82
	v_pk_mul_f32 v[16:17], v[8:9], v[16:17]
	v_lshlrev_b32_e32 v32, 16, v83
	v_pk_fma_f32 v[10:11], v[8:9], v[10:11], v[16:17] op_sel:[1,0,0] op_sel_hi:[0,1,1]
	v_lshlrev_b32_e32 v16, 16, v80
	v_and_b32_e32 v17, 0xffff0000, v80
	v_and_b32_e32 v33, 0xffff0000, v91
	v_pk_add_f32 v[10:11], v[10:11], v[16:17]
	v_lshlrev_b32_e32 v16, 16, v91
	v_and_b32_e32 v17, 0xffff0000, v83
	v_pk_mul_f32 v[32:33], v[8:9], v[32:33]
	v_cvt_f32_f16_sdwa v37, v77 dst_sel:DWORD dst_unused:UNUSED_PAD src0_sel:WORD_1
	v_pk_fma_f32 v[16:17], v[8:9], v[16:17], v[32:33] op_sel:[1,0,0] op_sel_hi:[0,1,1]
	v_lshlrev_b32_e32 v32, 16, v81
	v_and_b32_e32 v33, 0xffff0000, v81
	v_cvt_f32_f16_e32 v36, v77
	v_pk_add_f32 v[16:17], v[16:17], v[32:33]
	v_cvt_f32_f16_sdwa v33, v76 dst_sel:DWORD dst_unused:UNUSED_PAD src0_sel:WORD_1
	v_cvt_f32_f16_e32 v32, v76
	s_mov_b32 s0, 0x3fd744fd
	v_pk_fma_f32 v[44:45], v[36:37], s[0:1], v[16:17] op_sel_hi:[1,0,1]
	v_lshlrev_b32_e32 v16, 16, v66
	v_and_b32_e32 v17, 0xffff0000, v74
	v_pk_fma_f32 v[38:39], v[32:33], s[0:1], v[10:11] op_sel_hi:[1,0,1]
	v_lshlrev_b32_e32 v10, 16, v74
	v_and_b32_e32 v11, 0xffff0000, v66
	v_pk_mul_f32 v[16:17], v[8:9], v[16:17]
	v_lshlrev_b32_e32 v32, 16, v67
	v_pk_fma_f32 v[10:11], v[8:9], v[10:11], v[16:17] op_sel:[1,0,0] op_sel_hi:[0,1,1]
	v_lshlrev_b32_e32 v16, 16, v64
	v_and_b32_e32 v17, 0xffff0000, v64
	v_and_b32_e32 v33, 0xffff0000, v75
	v_pk_add_f32 v[10:11], v[10:11], v[16:17]
	v_lshlrev_b32_e32 v16, 16, v75
	v_and_b32_e32 v17, 0xffff0000, v67
	v_pk_mul_f32 v[32:33], v[8:9], v[32:33]
	v_cvt_f32_f16_sdwa v37, v63 dst_sel:DWORD dst_unused:UNUSED_PAD src0_sel:WORD_1
	v_pk_fma_f32 v[16:17], v[8:9], v[16:17], v[32:33] op_sel:[1,0,0] op_sel_hi:[0,1,1]
	v_lshlrev_b32_e32 v32, 16, v65
	v_and_b32_e32 v33, 0xffff0000, v65
	v_cvt_f32_f16_e32 v36, v63
	v_pk_add_f32 v[16:17], v[16:17], v[32:33]
	v_cvt_f32_f16_sdwa v33, v62 dst_sel:DWORD dst_unused:UNUSED_PAD src0_sel:WORD_1
	v_cvt_f32_f16_e32 v32, v62
	v_pk_fma_f32 v[36:37], v[36:37], s[0:1], v[16:17] op_sel_hi:[1,0,1]
	v_lshlrev_b32_e32 v16, 16, v42
	v_and_b32_e32 v17, 0xffff0000, v58
	v_pk_fma_f32 v[32:33], v[32:33], s[0:1], v[10:11] op_sel_hi:[1,0,1]
	v_lshlrev_b32_e32 v10, 16, v58
	v_and_b32_e32 v11, 0xffff0000, v42
	v_pk_mul_f32 v[16:17], v[8:9], v[16:17]
	v_lshlrev_b32_e32 v42, 16, v43
	v_pk_fma_f32 v[10:11], v[8:9], v[10:11], v[16:17] op_sel:[1,0,0] op_sel_hi:[0,1,1]
	v_lshlrev_b32_e32 v16, 16, v40
	v_and_b32_e32 v17, 0xffff0000, v40
	v_pk_add_f32 v[10:11], v[10:11], v[16:17]
	v_and_b32_e32 v17, 0xffff0000, v43
	v_and_b32_e32 v43, 0xffff0000, v59
	v_lshlrev_b32_e32 v16, 16, v59
	v_pk_mul_f32 v[42:43], v[8:9], v[42:43]
	v_lshlrev_b32_e32 v40, 16, v41
	v_pk_fma_f32 v[16:17], v[8:9], v[16:17], v[42:43] op_sel:[1,0,0] op_sel_hi:[0,1,1]
	v_and_b32_e32 v41, 0xffff0000, v41
	v_pk_add_f32 v[16:17], v[16:17], v[40:41]
	v_cvt_f32_f16_sdwa v41, v30 dst_sel:DWORD dst_unused:UNUSED_PAD src0_sel:WORD_1
	v_cvt_f32_f16_e32 v40, v30
	v_cvt_f32_f16_sdwa v43, v31 dst_sel:DWORD dst_unused:UNUSED_PAD src0_sel:WORD_1
	v_cvt_f32_f16_e32 v42, v31
	v_lshlrev_b32_e32 v30, 16, v28
	v_pk_fma_f32 v[10:11], v[40:41], s[0:1], v[10:11] op_sel_hi:[1,0,1]
	v_lshlrev_b32_e32 v40, 16, v26
	v_and_b32_e32 v41, 0xffff0000, v28
	v_and_b32_e32 v31, 0xffff0000, v26
	v_pk_mul_f32 v[40:41], v[8:9], v[40:41]
	v_lshlrev_b32_e32 v26, 16, v27
	v_pk_fma_f32 v[30:31], v[8:9], v[30:31], v[40:41] op_sel:[1,0,0] op_sel_hi:[0,1,1]
; __device__ __forceinline__ void ln_row_write(f32x4 (&v)[4], const float* g, const float* bta, float* of, bf16_t* ob, int lane, unsigned char* o8 = nullptr) {
;     float s = 0.f;
; #pragma unroll
;     for (int j = 0; j < 4; ++j) s += (v[j][0] + v[j][1]) + (v[j][2] + v[j][3]);
;     const float mean = wave_sum(s) * (1.0f / 1024.0f); float s2 = 0.f;
; #pragma unroll
;     for (int j = 0; j < 4; ++j) { v[j] = v[j] - mean; s2 += (v[j][0] * v[j][0] + v[j][1] * v[j][1]) + (v[j][2] * v[j][2] + v[j][3] * v[j][3]); }
;     const float rstd = rsqrtf(wave_sum(s2) * (1.0f / 1024.0f) + EPS);
; #pragma unroll
;     for (int j = 0; j < 4; ++j) { const f32x4 gg = *(const f32x4*)(g + 4 * lane + 256 * j), bb = *(const f32x4*)(bta + 4 * lane + 256 * j); v[j] = v[j] * rstd * gg + bb;
;         if (of) *(f32x4*)(of + 4 * lane + 256 * j) = v[j]; u32x2 w; w.x = cvt_pk_f16(v[j][0], v[j][1]); w.y = cvt_pk_f16(v[j][2], v[j][3]); *(u32x2*)(ob + 4 * lane + 256 * j) = w;
	v_lshlrev_b32_e32 v40, 16, v24
	v_and_b32_e32 v41, 0xffff0000, v24
	v_pk_add_f32 v[30:31], v[30:31], v[40:41]
	v_and_b32_e32 v41, 0xffff0000, v27
	v_and_b32_e32 v27, 0xffff0000, v29
	v_lshlrev_b32_e32 v40, 16, v29
	v_pk_mul_f32 v[26:27], v[8:9], v[26:27]
	v_lshlrev_b32_e32 v24, 16, v25
	v_pk_fma_f32 v[8:9], v[8:9], v[40:41], v[26:27] op_sel:[1,0,0] op_sel_hi:[0,1,1]
	v_and_b32_e32 v25, 0xffff0000, v25
	v_pk_add_f32 v[8:9], v[8:9], v[24:25]
	v_cvt_f32_f16_sdwa v25, v18 dst_sel:DWORD dst_unused:UNUSED_PAD src0_sel:WORD_1
	v_cvt_f32_f16_e32 v24, v18
	v_cvt_f32_f16_sdwa v27, v19 dst_sel:DWORD dst_unused:UNUSED_PAD src0_sel:WORD_1
	v_cvt_f32_f16_e32 v26, v19
	v_pk_fma_f32 v[16:17], v[42:43], s[0:1], v[16:17] op_sel_hi:[1,0,1]
	v_pk_fma_f32 v[18:19], v[24:25], s[0:1], v[30:31] op_sel_hi:[1,0,1]
	v_cvt_pk_f16_f32 v24, v2, v3
	v_cvt_pk_f16_f32 v25, v4, v5
	global_store_dwordx2 v[22:23], v[24:25], off offset:1536
	v_mov_b32_e32 v22, v35
	v_cvt_pk_fp8_f32 v22, v2, v3
	v_pk_mov_b32 v[2:3], v[38:39], v[44:45] op_sel:[1,0]
	v_mov_b32_e32 v23, v37
	v_pk_fma_f32 v[8:9], v[26:27], s[0:1], v[8:9] op_sel_hi:[1,0,1]
	v_cvt_pk_fp8_f32 v22, v4, v5 op_sel:[0,0,1]
	v_mov_b32_e32 v4, v38
	v_mov_b32_e32 v5, v45
	v_pk_add_f32 v[2:3], v[2:3], v[4:5]
	global_store_dword v[50:51], v22, off offset:768
	v_pk_mov_b32 v[4:5], v[32:33], v[36:37] op_sel:[1,0]
	v_mov_b32_e32 v22, v32
	v_pk_add_f32 v[4:5], v[4:5], v[22:23]
	v_add_f32_e32 v2, v2, v3
	v_pk_add_f32 v[4:5], v[4:5], v[4:5] op_sel:[0,1] op_sel_hi:[1,0]
	v_add_f32_e32 v2, 0, v2
	v_add_f32_e32 v22, v10, v11
	v_add_f32_e32 v24, v16, v17
	v_mov_b32_e32 v3, v18
	v_mov_b32_e32 v5, v19
	v_mov_b32_e32 v23, v8
	v_mov_b32_e32 v25, v9
	v_pk_add_f32 v[2:3], v[2:3], v[4:5]
	v_pk_add_f32 v[4:5], v[22:23], v[24:25]
	s_lshl_b64 s[0:1], s[2:3], 12
	v_pk_add_f32 v[2:3], v[2:3], v[4:5]
	s_add_u32 s4, s34, s0
	v_add_f32_e32 v2, v2, v3
	ds_bpermute_b32 v3, v34, v2
	s_addc_u32 s5, s35, s1
	s_and_b64 s[0:1], s[8:9], exec
	s_cselect_b32 s1, s5, 0
	s_cselect_b32 s0, s4, 0
	s_waitcnt lgkmcnt(0)
	v_add_f32_e32 v2, v2, v3
	ds_bpermute_b32 v3, v164, v2
	s_cmp_lg_u64 s[0:1], 0
	s_cselect_b64 s[4:5], -1, 0
	s_cmp_eq_u64 s[0:1], 0
	s_waitcnt lgkmcnt(0)
	v_add_f32_e32 v2, v2, v3
	ds_bpermute_b32 v3, v165, v2
	s_waitcnt lgkmcnt(0)
	v_add_f32_e32 v2, v2, v3
	ds_bpermute_b32 v3, v166, v2
	s_waitcnt lgkmcnt(0)
	v_add_f32_e32 v2, v2, v3
	ds_bpermute_b32 v3, v167, v2
	s_waitcnt lgkmcnt(0)
	v_add_f32_e32 v2, v2, v3
	ds_bpermute_b32 v3, v168, v2
	s_waitcnt lgkmcnt(0)
	v_add_f32_e32 v26, v2, v3
	v_fmamk_f32 v39, v26, 0xba800000, v39
	v_fmac_f32_e32 v38, 0xba800000, v26
	v_fmamk_f32 v45, v26, 0xba800000, v45
	v_fmac_f32_e32 v44, 0xba800000, v26
	v_pk_mul_f32 v[2:3], v[44:45], v[44:45]
	v_pk_mul_f32 v[4:5], v[38:39], v[38:39]
	v_fmamk_f32 v37, v26, 0xba800000, v37
	v_pk_mov_b32 v[22:23], v[4:5], v[2:3] op_sel:[1,0]
	v_mov_b32_e32 v5, v3
	v_pk_add_f32 v[2:3], v[22:23], v[4:5]
	v_fmac_f32_e32 v36, 0xba800000, v26
	v_fmamk_f32 v33, v26, 0xba800000, v33
	v_fmac_f32_e32 v32, 0xba800000, v26
	v_pk_add_f32 v[2:3], v[2:3], v[2:3] op_sel_hi:[0,1]
	v_pk_mul_f32 v[4:5], v[36:37], v[36:37]
	v_pk_mul_f32 v[22:23], v[32:33], v[32:33]
	v_fmac_f32_e32 v10, 0xba800000, v26
	v_pk_mov_b32 v[24:25], v[22:23], v[4:5] op_sel:[1,0]
	v_mov_b32_e32 v23, v5
	v_fmac_f32_e32 v16, 0xba800000, v26
	v_fmamk_f32 v11, v26, 0xba800000, v11
	v_mul_f32_e32 v2, v10, v10
	v_pk_add_f32 v[4:5], v[24:25], v[22:23]
	v_fmamk_f32 v17, v26, 0xba800000, v17
	v_pk_fma_f32 v[22:23], v[10:11], v[10:11], v[2:3] op_sel_hi:[1,1,0]
	v_mul_f32_e32 v2, v16, v16
	v_pk_add_f32 v[4:5], v[4:5], v[4:5] op_sel_hi:[0,1]
	v_pk_fma_f32 v[24:25], v[16:17], v[16:17], v[2:3] op_sel_hi:[1,1,0]
	v_fmamk_f32 v9, v26, 0xba800000, v9
	v_fmac_f32_e32 v8, 0xba800000, v26
	v_fmamk_f32 v19, v26, 0xba800000, v19
	v_fmac_f32_e32 v18, 0xba800000, v26
	v_mul_f32_e32 v22, v18, v18
	v_mul_f32_e32 v24, v19, v19
	v_mul_f32_e32 v2, v8, v8
	v_mul_f32_e32 v4, v9, v9
	v_pk_add_f32 v[22:23], v[22:23], v[24:25]
	v_pk_add_f32 v[2:3], v[2:3], v[4:5]
	s_nop 0
	v_pk_add_f32 v[2:3], v[22:23], v[2:3]
	v_lshl_add_u64 v[22:23], v[6:7], 2, s[0:1]
	v_add_f32_e32 v2, v2, v3
	ds_bpermute_b32 v3, v34, v2
	s_waitcnt lgkmcnt(0)
	v_add_f32_e32 v2, v2, v3
	ds_bpermute_b32 v3, v164, v2
	s_waitcnt lgkmcnt(0)
	v_add_f32_e32 v2, v2, v3
	ds_bpermute_b32 v3, v165, v2
	s_waitcnt lgkmcnt(0)
	v_add_f32_e32 v2, v2, v3
	ds_bpermute_b32 v3, v166, v2
	s_waitcnt lgkmcnt(0)
	v_add_f32_e32 v2, v2, v3
	ds_bpermute_b32 v3, v167, v2
	s_waitcnt lgkmcnt(0)
	v_add_f32_e32 v2, v2, v3
	ds_bpermute_b32 v3, v168, v2
	s_waitcnt lgkmcnt(0)
	v_add_f32_e32 v2, v2, v3
	v_fmamk_f32 v2, v2, 0x3a800000, v230
	v_cmp_gt_f32_e32 vcc, s97, v2
	v_mul_f32_e32 v3, 0x4b800000, v2
	s_nop 0
	v_cndmask_b32_e32 v2, v2, v3, vcc
	v_rsq_f32_e32 v2, v2
	s_nop 0
	v_mul_f32_e32 v3, 0x45800000, v2
	v_cndmask_b32_e32 v24, v2, v3, vcc
	v_pk_mul_f32 v[30:31], v[38:39], v[24:25] op_sel_hi:[1,0]
	v_pk_mul_f32 v[38:39], v[44:45], v[24:25] op_sel_hi:[1,0]
	v_pk_fma_f32 v[2:3], v[176:177], v[30:31], v[192:193]
	v_pk_fma_f32 v[4:5], v[178:179], v[38:39], v[194:195]
	s_cbranch_scc1 .LBB0_2071
	global_store_dwordx4 v[22:23], v[2:5], off
; __device__ __forceinline__ unsigned cvt4_fp8(float a, float b, float c, float d) { int w = 0; w = __builtin_amdgcn_cvt_pk_fp8_f32(a, b, w, false); w = __builtin_amdgcn_cvt_pk_fp8_f32(c, d, w, true); return (unsigned)w; }
; __device__ __forceinline__ void ln_row_write(f32x4 (&v)[4], const float* g, const float* bta, float* of, bf16_t* ob, int lane, unsigned char* o8 = nullptr) {
;     ...
; #pragma unroll
;     for (int j = 0; j < 4; ++j) { const f32x4 gg = *(const f32x4*)(g + 4 * lane + 256 * j), bb = *(const f32x4*)(bta + 4 * lane + 256 * j); v[j] = v[j] * rstd * gg + bb;
;         if (of) *(f32x4*)(of + 4 * lane + 256 * j) = v[j]; u32x2 w; w.x = cvt_pk_f16(v[j][0], v[j][1]); w.y = cvt_pk_f16(v[j][2], v[j][3]); *(u32x2*)(ob + 4 * lane + 256 * j) = w;
;         if (o8) *(unsigned*)(o8 + 4 * lane + 256 * j) = cvt4_fp8(v[j][0], v[j][1], v[j][2], v[j][3]); }
.LBB0_2071:
	v_cvt_pk_f16_f32 v26, v2, v3
	v_cvt_pk_f16_f32 v27, v4, v5
	global_store_dwordx2 v[20:21], v[26:27], off
	v_mov_b32_e32 v26, v35
	v_cvt_pk_fp8_f32 v26, v2, v3
	s_lshl_b64 s[0:1], s[2:3], 10
	s_add_u32 s0, s20, s0
	s_addc_u32 s1, s21, s1
	v_cvt_pk_fp8_f32 v26, v4, v5 op_sel:[0,0,1]
	v_lshl_add_u64 v[6:7], s[0:1], 0, v[6:7]
	v_mov_b32_e32 v25, v24
	v_mov_b32_e32 v27, v24
	global_store_dword v[6:7], v26, off
	v_mov_b32_e32 v26, v24
	v_pk_mul_f32 v[32:33], v[32:33], v[24:25]
	v_pk_mul_f32 v[36:37], v[36:37], v[26:27]
	s_andn2_b64 vcc, exec, s[4:5]
	v_pk_fma_f32 v[2:3], v[32:33], v[180:181], v[206:207]
	v_cndmask_b32_e64 v28, 0, 1, s[4:5]
	v_pk_fma_f32 v[4:5], v[36:37], v[182:183], v[208:209]
	v_cmp_ne_u32_e64 s[0:1], 1, v28
	s_cbranch_vccnz .LBB0_2073
	global_store_dwordx4 v[22:23], v[2:5], off offset:1024
.LBB0_2073:
	v_mov_b32_e32 v28, v35
	v_cvt_pk_fp8_f32 v28, v2, v3
	v_cvt_pk_f16_f32 v2, v2, v3
	v_cvt_pk_f16_f32 v3, v4, v5
	v_pk_mul_f32 v[16:17], v[16:17], v[26:27]
	v_cvt_pk_fp8_f32 v28, v4, v5 op_sel:[0,0,1]
	v_pk_mul_f32 v[10:11], v[10:11], v[24:25]
	s_and_b64 vcc, exec, s[0:1]
	global_store_dwordx2 v[20:21], v[2:3], off offset:512
	global_store_dword v[6:7], v28, off offset:256
	s_nop 0
	v_pk_fma_f32 v[4:5], v[16:17], v[186:187], v[212:213]
	v_pk_fma_f32 v[2:3], v[10:11], v[184:185], v[210:211]
	s_cbranch_vccnz .LBB0_2075
	global_store_dwordx4 v[22:23], v[2:5], off offset:2048
.LBB0_2075:
	v_mov_b32_e32 v10, v35
	v_cvt_pk_fp8_f32 v10, v2, v3
	v_cvt_pk_f16_f32 v2, v2, v3
	v_cvt_pk_f16_f32 v3, v4, v5
	v_pk_mul_f32 v[16:17], v[18:19], v[24:25]
	v_cvt_pk_fp8_f32 v10, v4, v5 op_sel:[0,0,1]
	s_and_b64 vcc, exec, s[0:1]
	global_store_dwordx2 v[20:21], v[2:3], off offset:1024
	global_store_dword v[6:7], v10, off offset:512
	s_nop 0
	v_mov_b32_e32 v14, v24
	v_mov_b32_e32 v15, v24
	v_pk_mul_f32 v[8:9], v[8:9], v[14:15]
	s_waitcnt vmcnt(0)
	v_pk_fma_f32 v[2:3], v[16:17], v[188:189], v[214:215]
	v_pk_fma_f32 v[4:5], v[8:9], v[190:191], v[216:217]
	s_cbranch_vccnz .LBB0_2077
	global_store_dwordx4 v[22:23], v[2:5], off offset:3072
